# hand-written dense MLA attention item (software-pipelined, permlane reductions, 3 LDS buffers) and NA block item with 4-deep register ring prefetch
# speedup vs baseline: 1.0479x; 1.0166x over previous
; DI int otid() { int t = threadIdx.x; asm volatile("" : "+v"(t)); return t; }
; template <int DK>
; DI void dense_attn_item(LAS unsigned char* lds, const bf16_t* Qb, int ldq, const bf16_t* Kb, int ldk, const bf16_t* Kpe, const bf16_t* Vt, int nkeys, float sl2, bf16_t* Ob) {
;     const int tid = otid(), lane = tid & 63, wid = tid >> 6, r16 = lane & 15, q4 = lane >> 4;
;     constexpr int KS = DK / 32, KCH = DK / 8, KROW = DK * 2 + 16, KTILE = 64 * KROW, VROW = 144, VTILE = 128 * VROW, NKL = (64 * KCH) / 512;
;     bf16x8 qf[2][KS];
; #pragma unroll
;     for (int qg = 0; qg < 2; ++qg)
; #pragma unroll
;         for (int ks = 0; ks < KS; ++ks) qf[qg][ks] = *(const bf16x8*)(Qb + (size_t)(wid * 32 + qg * 16 + r16) * ldq + ks * 32 + q4 * 8);
;     f32x4 oacc[2][8];
; #pragma unroll
;     for (int qg = 0; qg < 2; ++qg)
; #pragma unroll
;         for (int d = 0; d < 8; ++d) oacc[qg][d] = (f32x4){0.f, 0.f, 0.f, 0.f};
;     float mrun[2] = {-1e30f, -1e30f}, lsum[2] = {0.f, 0.f};
;     u32x4 kst[NKL], vst[2];
;     const int ntiles = nkeys >> 6;
;     ...
;     DA_LOAD(0); DA_STORE(0);
;     __syncthreads();
; DI void dense192_item(unsigned char* ws, LAS unsigned char* lds, int b, int h, int q0, int nk) {
;     const size_t rowb = (size_t)b * RB, row0 = rowb + q0;
;     dense_attn_item<192>(lds, (const bf16_t*)(ws + WS_QM) + row0 * 960 + h * 192, 960, (const bf16_t*)(ws + WS_KM) + rowb * 640 + h * 128, 640, (const bf16_t*)(ws + WS_KPE) + rowb * 64,
;                          (const bf16_t*)(ws + WS_VTM) + ((size_t)b * 640 + h * 128) * RB, nk, 0.07216878364870322f * 1.4426950408889634f, (bf16_t*)(ws + WS_YMIX) + row0 * DM + 768 + h * 128);
.LBB0_1146:
	s_mul_hi_u32 s71, s28, 0x66666667
	s_lshr_b32 s71, s71, 4
	s_lshr_b32 s73, s28, 3
	s_mul_i32 s62, s71, 5
	s_sub_u32 s73, s73, s62
	s_and_b32 s62, s28, 7
	s_lshl_b32 s62, s62, 8
	s_mul_i32 s75, s71, 0x900
	s_add_u32 s74, s75, s62
	s_addk_i32 s74, 0x100
	s_mul_i32 s62, s74, 0x780
	s_mul_i32 s63, s73, 0x180
	s_add_u32 s62, s62, s63
	s_add_u32 s62, s62, 0x1a3a0000
	s_add_u32 s10, s50, s62
	s_addc_u32 s11, s51, 0
	s_mul_i32 s62, s75, 0x500
	s_lshl_b32 s63, s73, 8
	s_add_u32 s62, s62, s63
	s_add_u32 s62, s62, 0x1b480000
	s_add_u32 s4, s50, s62
	s_addc_u32 s5, s51, 0
	s_mul_i32 s62, s75, 0x480
	s_add_u32 s62, s62, s63
	s_sub_u32 s76, 0x167ff00, s62
	s_mul_i32 s62, s71, 0x280
	s_lshl_b32 s63, s73, 7
	s_add_u32 s62, s62, s63
	s_mul_i32 s62, s62, 0x1200
	s_add_u32 s62, s62, 0x1bfc0000
	s_add_u32 s8, s50, s62
	s_addc_u32 s9, s51, 0
	s_lshl_b32 s62, s74, 12
	s_lshl_b32 s63, s73, 8
	s_add_u32 s62, s62, s63
	s_add_u32 s62, s62, 0x1d9a0600
	s_add_u32 s20, s50, s62
	s_addc_u32 s21, s51, 0
	s_mov_b32 s22, 0x3dd53b94
	v_and_b32_e32 v192, 15, v202
	v_bfe_u32 v193, v202, 4, 2
	v_lshrrev_b32_e32 v194, 6, v202
	v_lshl_add_u32 v195, v194, 5, v192
	v_mul_u32_u24_e32 v196, 0x780, v195
	v_lshl_add_u32 v250, v193, 4, v196
	v_add_u32_e32 v251, 0x7800, v250
	global_load_dwordx4 v[0:3], v250, s[10:11] offset:0
	global_load_dwordx4 v[4:7], v250, s[10:11] offset:64
	global_load_dwordx4 v[8:11], v250, s[10:11] offset:128
	global_load_dwordx4 v[12:15], v250, s[10:11] offset:192
	global_load_dwordx4 v[16:19], v250, s[10:11] offset:256
	global_load_dwordx4 v[20:23], v250, s[10:11] offset:320
	global_load_dwordx4 v[24:27], v251, s[10:11] offset:0
	global_load_dwordx4 v[28:31], v251, s[10:11] offset:64
	global_load_dwordx4 v[32:35], v251, s[10:11] offset:128
	global_load_dwordx4 v[36:39], v251, s[10:11] offset:192
	global_load_dwordx4 v[40:43], v251, s[10:11] offset:256
	global_load_dwordx4 v[44:47], v251, s[10:11] offset:320
	s_mov_b32 s62, 0xaaaaaab
	v_mov_b32_e32 v197, v202
	v_mul_hi_u32 v198, v197, s62
	v_mul_u32_u24_e32 v195, 24, v198
	v_sub_u32_e32 v199, v197, v195
	v_mul_u32_u24_e32 v195, 0x190, v198
	v_lshl_add_u32 v230, v199, 4, v195
	v_cmp_gt_u32_e32 vcc, 16, v199
	v_mul_u32_u24_e32 v195, 0x500, v198
	v_lshlrev_b32_e32 v196, 7, v198
	v_add_u32_e32 v196, s76, v196
	s_nop 1
	v_cndmask_b32_e32 v195, v196, v195, vcc
	v_lshl_add_u32 v224, v199, 4, v195
	v_mov_b32_e32 v195, 0x2000
	v_mov_b32_e32 v196, 0x14000
	v_cndmask_b32_e32 v227, v195, v196, vcc
	v_add_u32_e32 v197, 0x200, v202
	v_mul_hi_u32 v198, v197, s62
	v_mul_u32_u24_e32 v195, 24, v198
	v_sub_u32_e32 v199, v197, v195
	v_mul_u32_u24_e32 v195, 0x190, v198
	v_lshl_add_u32 v231, v199, 4, v195
	v_cmp_gt_u32_e32 vcc, 16, v199
	v_mul_u32_u24_e32 v195, 0x500, v198
	v_lshlrev_b32_e32 v196, 7, v198
	v_add_u32_e32 v196, s76, v196
	s_nop 1
	v_cndmask_b32_e32 v195, v196, v195, vcc
	v_lshl_add_u32 v225, v199, 4, v195
	v_mov_b32_e32 v195, 0x2000
	v_mov_b32_e32 v196, 0x14000
	v_cndmask_b32_e32 v228, v195, v196, vcc
	v_add_u32_e32 v197, 0x400, v202
	v_mul_hi_u32 v198, v197, s62
	v_mul_u32_u24_e32 v195, 24, v198
	v_sub_u32_e32 v199, v197, v195
	v_mul_u32_u24_e32 v195, 0x190, v198
	v_lshl_add_u32 v232, v199, 4, v195
	v_cmp_gt_u32_e32 vcc, 16, v199
	v_mul_u32_u24_e32 v195, 0x500, v198
	v_lshlrev_b32_e32 v196, 7, v198
	v_add_u32_e32 v196, s76, v196
	s_nop 1
	v_cndmask_b32_e32 v195, v196, v195, vcc
	v_lshl_add_u32 v226, v199, 4, v195
	v_mov_b32_e32 v195, 0x2000
	v_mov_b32_e32 v196, 0x14000
	v_cndmask_b32_e32 v229, v195, v196, vcc
	v_mov_b32_e32 v197, v202
	v_lshrrev_b32_e32 v198, 3, v197
	v_and_b32_e32 v199, 7, v197
	v_mul_u32_u24_e32 v195, 0x1200, v198
	v_lshl_add_u32 v233, v199, 4, v195
	v_mul_u32_u24_e32 v195, 0x90, v198
	v_lshl_add_u32 v195, v199, 4, v195
	v_add_u32_e32 v235, 0x12c00, v195
	v_add_u32_e32 v197, 0x200, v202
	v_lshrrev_b32_e32 v198, 3, v197
	v_and_b32_e32 v199, 7, v197
	v_mul_u32_u24_e32 v195, 0x1200, v198
	v_lshl_add_u32 v234, v199, 4, v195
	v_mul_u32_u24_e32 v195, 0x90, v198
	v_lshl_add_u32 v195, v199, 4, v195
	v_add_u32_e32 v236, 0x12c00, v195
	v_mul_u32_u24_e32 v195, 0x190, v192
	v_lshl_add_u32 v237, v193, 4, v195
	v_mul_u32_u24_e32 v195, 0x90, v192
	v_lshl_add_u32 v195, v193, 3, v195
	v_add_u32_e32 v238, 0x12c00, v195
	global_load_dwordx4 v[204:207], v224, s[4:5]
	global_load_dwordx4 v[208:211], v225, s[4:5]
	global_load_dwordx4 v[212:215], v226, s[4:5]
	global_load_dwordx4 v[216:219], v233, s[8:9]
	global_load_dwordx4 v[220:223], v234, s[8:9]
	v_add_u32_e32 v224, v224, v227
	v_add_u32_e32 v225, v225, v228
	v_add_u32_e32 v226, v226, v229
	s_add_u32 s8, s8, 0x80
	s_addc_u32 s9, s9, 0
	v_mov_b32_e32 v48, 0
	v_mov_b32_e32 v49, 0
	v_mov_b32_e32 v50, 0
	v_mov_b32_e32 v51, 0
	v_mov_b32_e32 v52, 0
	v_mov_b32_e32 v53, 0
	v_mov_b32_e32 v54, 0
	v_mov_b32_e32 v55, 0
	v_mov_b32_e32 v56, 0
	v_mov_b32_e32 v57, 0
	v_mov_b32_e32 v58, 0
	v_mov_b32_e32 v59, 0
	v_mov_b32_e32 v60, 0
	v_mov_b32_e32 v61, 0
	v_mov_b32_e32 v62, 0
	v_mov_b32_e32 v63, 0
	v_mov_b32_e32 v64, 0
	v_mov_b32_e32 v65, 0
	v_mov_b32_e32 v66, 0
	v_mov_b32_e32 v67, 0
	v_mov_b32_e32 v68, 0
	v_mov_b32_e32 v69, 0
	v_mov_b32_e32 v70, 0
	v_mov_b32_e32 v71, 0
	v_mov_b32_e32 v72, 0
	v_mov_b32_e32 v73, 0
	v_mov_b32_e32 v74, 0
	v_mov_b32_e32 v75, 0
	v_mov_b32_e32 v76, 0
	v_mov_b32_e32 v77, 0
	v_mov_b32_e32 v78, 0
	v_mov_b32_e32 v79, 0
	v_mov_b32_e32 v80, 0
	v_mov_b32_e32 v81, 0
	v_mov_b32_e32 v82, 0
	v_mov_b32_e32 v83, 0
	v_mov_b32_e32 v84, 0
	v_mov_b32_e32 v85, 0
	v_mov_b32_e32 v86, 0
	v_mov_b32_e32 v87, 0
	v_mov_b32_e32 v88, 0
	v_mov_b32_e32 v89, 0
	v_mov_b32_e32 v90, 0
	v_mov_b32_e32 v91, 0
	v_mov_b32_e32 v92, 0
	v_mov_b32_e32 v93, 0
	v_mov_b32_e32 v94, 0
	v_mov_b32_e32 v95, 0
	v_mov_b32_e32 v96, 0
	v_mov_b32_e32 v97, 0
	v_mov_b32_e32 v98, 0
	v_mov_b32_e32 v99, 0
	v_mov_b32_e32 v100, 0
	v_mov_b32_e32 v101, 0
	v_mov_b32_e32 v102, 0
	v_mov_b32_e32 v103, 0
	v_mov_b32_e32 v104, 0
	v_mov_b32_e32 v105, 0
	v_mov_b32_e32 v106, 0
	v_mov_b32_e32 v107, 0
	v_mov_b32_e32 v108, 0
	v_mov_b32_e32 v109, 0
	v_mov_b32_e32 v110, 0
	v_mov_b32_e32 v111, 0
	v_mov_b32_e32 v242, 0xf149f2ca
	v_mov_b32_e32 v244, 0
	v_mov_b32_e32 v243, 0xf149f2ca
	v_mov_b32_e32 v245, 0
	s_waitcnt vmcnt(0)
	v_lshl_add_u32 v195, v194, 5, v192
	v_lshlrev_b32_e32 v195, 12, v195
	v_lshl_add_u32 v250, v193, 3, v195
	v_add_u32_e32 v251, 0x10000, v250
	ds_write_b128 v230, v[204:207]
	ds_write_b128 v231, v[208:211]
	ds_write_b128 v232, v[212:215]
	ds_write_b128 v235, v[216:219]
	ds_write_b128 v236, v[220:223]
	s_waitcnt lgkmcnt(0)
	global_load_dwordx4 v[204:207], v224, s[4:5]
	global_load_dwordx4 v[208:211], v225, s[4:5]
	global_load_dwordx4 v[212:215], v226, s[4:5]
	global_load_dwordx4 v[216:219], v233, s[8:9]
	global_load_dwordx4 v[220:223], v234, s[8:9]
	s_barrier
; template <int DK>
; DI void dense_attn_item(LAS unsigned char* lds, const bf16_t* Qb, int ldq, const bf16_t* Kb, int ldk, const bf16_t* Kpe, const bf16_t* Vt, int nkeys, float sl2, bf16_t* Ob) {
;     ...
;     for (int kt = 0; kt < ntiles; ++kt) {
;         const int cur = kt & 1;
;         if (kt + 1 < ntiles) DA_LOAD((kt + 1) * 64);
;         const LAS unsigned char* kb_ = lds + cur * KTILE; const LAS unsigned char* vb_ = lds + 2 * KTILE + cur * VTILE;
; #pragma unroll
;         for (int kc = 0; kc < 2; ++kc) {
;             f32x4 sacc[2][2];
; #pragma unroll
;             for (int kb = 0; kb < 2; ++kb) {
;                 sacc[0][kb] = (f32x4){0.f, 0.f, 0.f, 0.f}; sacc[1][kb] = (f32x4){0.f, 0.f, 0.f, 0.f};
; #pragma unroll
;                 for (int kh = 0; kh < KS / 2; ++kh) {
;                     const bf16x8 k0 = *(const LAS bf16x8*)(kb_ + ((2 * kc + kb) * 16 + r16) * KROW + (2 * kh) * 64 + q4 * 16);
;                     const bf16x8 k1 = *(const LAS bf16x8*)(kb_ + ((2 * kc + kb) * 16 + r16) * KROW + (2 * kh + 1) * 64 + q4 * 16);
;                     __builtin_amdgcn_s_setprio(1);
;                     sacc[0][kb] = MFMA16(k0, qf[0][2 * kh], sacc[0][kb]); sacc[1][kb] = MFMA16(k0, qf[1][2 * kh], sacc[1][kb]);
;                     sacc[0][kb] = MFMA16(k1, qf[0][2 * kh + 1], sacc[0][kb]); sacc[1][kb] = MFMA16(k1, qf[1][2 * kh + 1], sacc[1][kb]);
;                     __builtin_amdgcn_s_setprio(0);
;                 }
;             }
;             bf16x8 pb[2];
; #pragma unroll
;             for (int qg = 0; qg < 2; ++qg) {
;                 float mx = fmaxf(fmaxf(fmaxf(sacc[qg][0][0], sacc[qg][0][1]), fmaxf(sacc[qg][0][2], sacc[qg][0][3])), fmaxf(fmaxf(sacc[qg][1][0], sacc[qg][1][1]), fmaxf(sacc[qg][1][2], sacc[qg][1][3])));
;                 mx = fmaxf(mx, __shfl_xor(mx, 16)); mx = fmaxf(mx, __shfl_xor(mx, 32));
;                 const float mnew = fmaxf(mrun[qg], mx * sl2), alpha = fast_exp2(mrun[qg] - mnew);
;                 mrun[qg] = mnew;
;                 float ps = 0.f;
; #pragma unroll
;                 for (int kb = 0; kb < 2; ++kb)
; #pragma unroll
;                     for (int j = 0; j < 4; ++j) { const float pv = fast_exp2(sacc[qg][kb][j] * sl2 - mnew); sacc[qg][kb][j] = pv; ps += pv; }
;                 lsum[qg] = lsum[qg] * alpha + ps;
; #pragma unroll
;                 for (int d = 0; d < 8; ++d) oacc[qg][d] *= alpha;
	v_mov_b32_e32 v239, v237
	ds_read_b128 v[144:147], v239 offset:0
	ds_read_b128 v[148:151], v239 offset:64
	ds_read_b128 v[152:155], v239 offset:128
	ds_read_b128 v[156:159], v239 offset:192
	ds_read_b128 v[160:163], v239 offset:256
	ds_read_b128 v[164:167], v239 offset:320
	s_waitcnt lgkmcnt(5)
	v_mfma_f32_16x16x32_bf16 v[112:115], v[144:147], v[0:3], 0
	v_mfma_f32_16x16x32_bf16 v[120:123], v[144:147], v[24:27], 0
	s_waitcnt lgkmcnt(4)
	v_mfma_f32_16x16x32_bf16 v[112:115], v[148:151], v[4:7], v[112:115]
	v_mfma_f32_16x16x32_bf16 v[120:123], v[148:151], v[28:31], v[120:123]
	s_waitcnt lgkmcnt(3)
	v_mfma_f32_16x16x32_bf16 v[112:115], v[152:155], v[8:11], v[112:115]
	v_mfma_f32_16x16x32_bf16 v[120:123], v[152:155], v[32:35], v[120:123]
	s_waitcnt lgkmcnt(2)
	v_mfma_f32_16x16x32_bf16 v[112:115], v[156:159], v[12:15], v[112:115]
	v_mfma_f32_16x16x32_bf16 v[120:123], v[156:159], v[36:39], v[120:123]
	s_waitcnt lgkmcnt(1)
	v_mfma_f32_16x16x32_bf16 v[112:115], v[160:163], v[16:19], v[112:115]
	v_mfma_f32_16x16x32_bf16 v[120:123], v[160:163], v[40:43], v[120:123]
	s_waitcnt lgkmcnt(0)
	v_mfma_f32_16x16x32_bf16 v[112:115], v[164:167], v[20:23], v[112:115]
	v_mfma_f32_16x16x32_bf16 v[120:123], v[164:167], v[44:47], v[120:123]
	ds_read_b128 v[144:147], v239 offset:6400
	ds_read_b128 v[148:151], v239 offset:6464
	ds_read_b128 v[152:155], v239 offset:6528
	ds_read_b128 v[156:159], v239 offset:6592
	ds_read_b128 v[160:163], v239 offset:6656
	ds_read_b128 v[164:167], v239 offset:6720
	s_waitcnt lgkmcnt(5)
	v_mfma_f32_16x16x32_bf16 v[116:119], v[144:147], v[0:3], 0
	v_mfma_f32_16x16x32_bf16 v[124:127], v[144:147], v[24:27], 0
	s_waitcnt lgkmcnt(4)
	v_mfma_f32_16x16x32_bf16 v[116:119], v[148:151], v[4:7], v[116:119]
	v_mfma_f32_16x16x32_bf16 v[124:127], v[148:151], v[28:31], v[124:127]
	s_waitcnt lgkmcnt(3)
	v_mfma_f32_16x16x32_bf16 v[116:119], v[152:155], v[8:11], v[116:119]
	v_mfma_f32_16x16x32_bf16 v[124:127], v[152:155], v[32:35], v[124:127]
	s_waitcnt lgkmcnt(2)
	v_mfma_f32_16x16x32_bf16 v[116:119], v[156:159], v[12:15], v[116:119]
	v_mfma_f32_16x16x32_bf16 v[124:127], v[156:159], v[36:39], v[124:127]
	s_waitcnt lgkmcnt(1)
	v_mfma_f32_16x16x32_bf16 v[116:119], v[160:163], v[16:19], v[116:119]
	v_mfma_f32_16x16x32_bf16 v[124:127], v[160:163], v[40:43], v[124:127]
	s_waitcnt lgkmcnt(0)
	v_mfma_f32_16x16x32_bf16 v[116:119], v[164:167], v[20:23], v[116:119]
	v_mfma_f32_16x16x32_bf16 v[124:127], v[164:167], v[44:47], v[124:127]
	s_mov_b32 s23, 0
	s_mov_b32 s27, 0
dn0_top:
	s_add_u32 s57, s27, 1
	s_cmp_eq_u32 s57, 3
	s_cselect_b32 s57, 0, s57
	s_mul_i32 s36, s27, 0x6400
	s_mul_i32 s54, s27, 0x4800
	s_mul_i32 s37, s57, 0x6400
	s_mul_i32 s56, s57, 0x4800
	v_add_u32_e32 v239, s36, v237
	v_add_u32_e32 v240, s37, v237
	v_add_u32_e32 v241, s54, v238
	v_add_u32_e32 v196, s37, v230
	v_add_u32_e32 v197, s37, v231
	v_add_u32_e32 v198, s37, v232
	v_add_u32_e32 v199, s56, v235
	v_add_u32_e32 v200, s56, v236
	v_add_u32_e32 v224, v224, v227
	v_add_u32_e32 v225, v225, v228
	v_add_u32_e32 v226, v226, v229
	s_add_u32 s8, s8, 0x80
	s_addc_u32 s9, s9, 0
	s_waitcnt vmcnt(0)
	ds_write_b128 v196, v[204:207]
	ds_write_b128 v197, v[208:211]
	ds_write_b128 v198, v[212:215]
	ds_write_b128 v199, v[216:219]
	ds_write_b128 v200, v[220:223]
	ds_read_b128 v[144:147], v239 offset:12800
	ds_read_b128 v[148:151], v239 offset:12864
	ds_read_b128 v[152:155], v239 offset:12928
	ds_read_b128 v[156:159], v239 offset:12992
	ds_read_b128 v[160:163], v239 offset:13056
	ds_read_b128 v[164:167], v239 offset:13120
	v_max3_f32 v192, v112, v113, v114
	v_max3_f32 v194, v120, v121, v122
	v_max3_f32 v193, v115, v116, v117
	v_max3_f32 v195, v123, v124, v125
	v_max3_f32 v192, v192, v118, v119
	v_max3_f32 v194, v194, v126, v127
	v_max_f32_e32 v192, v192, v193
	v_max_f32_e32 v194, v194, v195
	v_mov_b32_e32 v193, v192
	v_mov_b32_e32 v195, v194
	s_nop 1
	v_permlane16_swap_b32_e32 v192, v193
	s_waitcnt lgkmcnt(5)
	global_load_dwordx4 v[204:207], v224, s[4:5]
	global_load_dwordx4 v[208:211], v225, s[4:5]
	global_load_dwordx4 v[212:215], v226, s[4:5]
	global_load_dwordx4 v[216:219], v233, s[8:9]
	global_load_dwordx4 v[220:223], v234, s[8:9]
	v_mfma_f32_16x16x32_bf16 v[128:131], v[144:147], v[0:3], 0
	v_permlane16_swap_b32_e32 v194, v195
	v_max_f32_e32 v192, v192, v193
	v_max_f32_e32 v194, v194, v195
	v_mfma_f32_16x16x32_bf16 v[136:139], v[144:147], v[24:27], 0
	v_mov_b32_e32 v193, v192
	v_mov_b32_e32 v195, v194
	s_nop 1
	ds_read_b128 v[144:147], v239 offset:19200
	s_waitcnt lgkmcnt(5)
	v_mfma_f32_16x16x32_bf16 v[128:131], v[148:151], v[4:7], v[128:131]
	v_permlane32_swap_b32_e32 v192, v193
	v_permlane32_swap_b32_e32 v194, v195
	v_max_f32_e32 v192, v192, v193
	v_mfma_f32_16x16x32_bf16 v[136:139], v[148:151], v[28:31], v[136:139]
	v_max_f32_e32 v194, v194, v195
	v_mul_f32_e32 v192, s22, v192
	v_mul_f32_e32 v194, s22, v194
	ds_read_b128 v[148:151], v239 offset:19264
	s_waitcnt lgkmcnt(5)
	v_mfma_f32_16x16x32_bf16 v[128:131], v[152:155], v[8:11], v[128:131]
	v_max_f32_e32 v193, v242, v192
	v_max_f32_e32 v195, v243, v194
	v_sub_f32_e32 v192, v242, v193
	v_mfma_f32_16x16x32_bf16 v[136:139], v[152:155], v[32:35], v[136:139]
	v_sub_f32_e32 v194, v243, v195
	v_exp_f32_e32 v246, v192
	v_exp_f32_e32 v248, v194
	ds_read_b128 v[152:155], v239 offset:19328
	s_waitcnt lgkmcnt(5)
	v_mfma_f32_16x16x32_bf16 v[128:131], v[156:159], v[12:15], v[128:131]
	v_mov_b32_e32 v242, v193
	v_mov_b32_e32 v243, v195
	v_fma_f32 v112, v112, s22, -v193
	v_mfma_f32_16x16x32_bf16 v[136:139], v[156:159], v[36:39], v[136:139]
	v_fma_f32 v120, v120, s22, -v195
	v_fma_f32 v113, v113, s22, -v193
	v_fma_f32 v121, v121, s22, -v195
	ds_read_b128 v[156:159], v239 offset:19392
	s_waitcnt lgkmcnt(5)
; #define LAS __attribute__((address_space(3)))
; template <int DK>
; DI void dense_attn_item(LAS unsigned char* lds, const bf16_t* Qb, int ldq, const bf16_t* Kb, int ldk, const bf16_t* Kpe, const bf16_t* Vt, int nkeys, float sl2, bf16_t* Ob) {
;     ...
;             for (int qg = 0; qg < 2; ++qg) {
;                 float mx = fmaxf(fmaxf(fmaxf(sacc[qg][0][0], sacc[qg][0][1]), fmaxf(sacc[qg][0][2], sacc[qg][0][3])), fmaxf(fmaxf(sacc[qg][1][0], sacc[qg][1][1]), fmaxf(sacc[qg][1][2], sacc[qg][1][3])));
;                 mx = fmaxf(mx, __shfl_xor(mx, 16)); mx = fmaxf(mx, __shfl_xor(mx, 32));
;                 const float mnew = fmaxf(mrun[qg], mx * sl2), alpha = fast_exp2(mrun[qg] - mnew);
;                 mrun[qg] = mnew;
;                 float ps = 0.f;
; #pragma unroll
;                 for (int kb = 0; kb < 2; ++kb)
; #pragma unroll
;                     for (int j = 0; j < 4; ++j) { const float pv = fast_exp2(sacc[qg][kb][j] * sl2 - mnew); sacc[qg][kb][j] = pv; ps += pv; }
;                 lsum[qg] = lsum[qg] * alpha + ps;
; #pragma unroll
;                 for (int d = 0; d < 8; ++d) oacc[qg][d] *= alpha;
;                 u32x4 w; w.x = cvt_pk_bf16(sacc[qg][0][0], sacc[qg][0][1]); w.y = cvt_pk_bf16(sacc[qg][0][2], sacc[qg][0][3]);
;                 w.z = cvt_pk_bf16(sacc[qg][1][0], sacc[qg][1][1]); w.w = cvt_pk_bf16(sacc[qg][1][2], sacc[qg][1][3]);
;                 pb[qg] = __builtin_bit_cast(bf16x8, w);
;             }
; #pragma unroll
;             for (int dh = 0; dh < 4; ++dh) {
;                 bf16x8 vfr[2];
; #pragma unroll
;                 for (int d4 = 0; d4 < 2; ++d4) {
;                     const int d = dh * 2 + d4;
;                     const u32x2 lo = *(const LAS u32x2*)(vb_ + (d * 16 + r16) * VROW + (kc * 32 + q4 * 4) * 2);
;                     const u32x2 hi = *(const LAS u32x2*)(vb_ + (d * 16 + r16) * VROW + (kc * 32 + 16 + q4 * 4) * 2);
;                     u32x4 w; w.x = lo.x; w.y = lo.y; w.z = hi.x; w.w = hi.y;
;                     vfr[d4] = __builtin_bit_cast(bf16x8, w);
;                 }
;                 __builtin_amdgcn_s_setprio(1);
; #pragma unroll
;                 for (int d4 = 0; d4 < 2; ++d4) { const int d = dh * 2 + d4; oacc[0][d] = MFMA16(vfr[d4], pb[0], oacc[0][d]); oacc[1][d] = MFMA16(vfr[d4], pb[1], oacc[1][d]); }
;                 __builtin_amdgcn_s_setprio(0);
;             }
	v_mfma_f32_16x16x32_bf16 v[128:131], v[160:163], v[16:19], v[128:131]
	v_fma_f32 v114, v114, s22, -v193
	v_fma_f32 v122, v122, s22, -v195
	v_fma_f32 v115, v115, s22, -v193
	v_mfma_f32_16x16x32_bf16 v[136:139], v[160:163], v[40:43], v[136:139]
	v_fma_f32 v123, v123, s22, -v195
	v_fma_f32 v116, v116, s22, -v193
	v_fma_f32 v124, v124, s22, -v195
	ds_read_b128 v[160:163], v239 offset:19456
	s_waitcnt lgkmcnt(5)
	v_mfma_f32_16x16x32_bf16 v[128:131], v[164:167], v[20:23], v[128:131]
	v_fma_f32 v117, v117, s22, -v193
	v_fma_f32 v125, v125, s22, -v195
	v_fma_f32 v118, v118, s22, -v193
	v_mfma_f32_16x16x32_bf16 v[136:139], v[164:167], v[44:47], v[136:139]
	v_fma_f32 v126, v126, s22, -v195
	v_fma_f32 v119, v119, s22, -v193
	v_fma_f32 v127, v127, s22, -v195
	ds_read_b128 v[164:167], v239 offset:19520
	s_waitcnt lgkmcnt(5)
	v_mfma_f32_16x16x32_bf16 v[132:135], v[144:147], v[0:3], 0
	v_exp_f32_e32 v112, v112
	v_exp_f32_e32 v120, v120
	v_exp_f32_e32 v113, v113
	v_mfma_f32_16x16x32_bf16 v[140:143], v[144:147], v[24:27], 0
	v_exp_f32_e32 v121, v121
	v_exp_f32_e32 v114, v114
	v_exp_f32_e32 v122, v122
	ds_read_b64 v[168:169], v241 offset:0
	ds_read_b64 v[170:171], v241 offset:32
	s_waitcnt lgkmcnt(6)
	v_mfma_f32_16x16x32_bf16 v[132:135], v[148:151], v[4:7], v[132:135]
	v_exp_f32_e32 v115, v115
	v_exp_f32_e32 v123, v123
	v_exp_f32_e32 v116, v116
	v_mfma_f32_16x16x32_bf16 v[140:143], v[148:151], v[28:31], v[140:143]
	v_exp_f32_e32 v124, v124
	v_exp_f32_e32 v117, v117
	v_exp_f32_e32 v125, v125
	ds_read_b64 v[172:173], v241 offset:2304
	ds_read_b64 v[174:175], v241 offset:2336
	s_waitcnt lgkmcnt(7)
	v_mfma_f32_16x16x32_bf16 v[132:135], v[152:155], v[8:11], v[132:135]
	v_exp_f32_e32 v118, v118
	v_exp_f32_e32 v126, v126
	v_exp_f32_e32 v119, v119
	v_mfma_f32_16x16x32_bf16 v[140:143], v[152:155], v[32:35], v[140:143]
	v_exp_f32_e32 v127, v127
	v_add_f32_e32 v192, v112, v113
	v_add_f32_e32 v194, v120, v121
	ds_read_b64 v[176:177], v241 offset:4608
	ds_read_b64 v[178:179], v241 offset:4640
	s_waitcnt lgkmcnt(8)
	v_mfma_f32_16x16x32_bf16 v[132:135], v[156:159], v[12:15], v[132:135]
	v_add_f32_e32 v192, v192, v114
	v_add_f32_e32 v194, v194, v122
	v_add_f32_e32 v192, v192, v115
	v_mfma_f32_16x16x32_bf16 v[140:143], v[156:159], v[36:39], v[140:143]
	v_add_f32_e32 v194, v194, v123
	v_add_f32_e32 v192, v192, v116
	v_add_f32_e32 v194, v194, v124
	ds_read_b64 v[180:181], v241 offset:6912
	ds_read_b64 v[182:183], v241 offset:6944
	s_waitcnt lgkmcnt(9)
	v_mfma_f32_16x16x32_bf16 v[132:135], v[160:163], v[16:19], v[132:135]
	v_add_f32_e32 v192, v192, v117
	v_add_f32_e32 v194, v194, v125
	v_add_f32_e32 v192, v192, v118
	v_mfma_f32_16x16x32_bf16 v[140:143], v[160:163], v[40:43], v[140:143]
	v_add_f32_e32 v194, v194, v126
	v_add_f32_e32 v192, v192, v119
	v_add_f32_e32 v194, v194, v127
	s_waitcnt lgkmcnt(8)
	v_mfma_f32_16x16x32_bf16 v[132:135], v[164:167], v[20:23], v[132:135]
	v_fma_f32 v244, v244, v246, v192
	v_fma_f32 v245, v245, v248, v194
	v_cvt_pk_bf16_f32 v184, v112, v113
	v_mfma_f32_16x16x32_bf16 v[140:143], v[164:167], v[44:47], v[140:143]
	v_cvt_pk_bf16_f32 v188, v120, v121
	v_cvt_pk_bf16_f32 v185, v114, v115
	v_cvt_pk_bf16_f32 v189, v122, v123
	v_cvt_pk_bf16_f32 v186, v116, v117
	v_cvt_pk_bf16_f32 v190, v124, v125
	v_cvt_pk_bf16_f32 v187, v118, v119
	v_cvt_pk_bf16_f32 v191, v126, v127
	v_pk_mul_f32 v[48:49], v[48:49], v[246:247] op_sel_hi:[1,0]
	v_pk_mul_f32 v[50:51], v[50:51], v[246:247] op_sel_hi:[1,0]
	v_pk_mul_f32 v[80:81], v[80:81], v[248:249] op_sel_hi:[1,0]
	v_pk_mul_f32 v[82:83], v[82:83], v[248:249] op_sel_hi:[1,0]
	s_waitcnt lgkmcnt(6)
	v_mfma_f32_16x16x32_bf16 v[48:51], v[168:171], v[184:187], v[48:51]
	v_pk_mul_f32 v[52:53], v[52:53], v[246:247] op_sel_hi:[1,0]
	v_pk_mul_f32 v[54:55], v[54:55], v[246:247] op_sel_hi:[1,0]
	v_mfma_f32_16x16x32_bf16 v[80:83], v[168:171], v[188:191], v[80:83]
	v_pk_mul_f32 v[84:85], v[84:85], v[248:249] op_sel_hi:[1,0]
	v_pk_mul_f32 v[86:87], v[86:87], v[248:249] op_sel_hi:[1,0]
	ds_read_b64 v[168:169], v241 offset:9216
	ds_read_b64 v[170:171], v241 offset:9248
	s_waitcnt lgkmcnt(6)
	v_mfma_f32_16x16x32_bf16 v[52:55], v[172:175], v[184:187], v[52:55]
	v_pk_mul_f32 v[56:57], v[56:57], v[246:247] op_sel_hi:[1,0]
	v_pk_mul_f32 v[58:59], v[58:59], v[246:247] op_sel_hi:[1,0]
	v_mfma_f32_16x16x32_bf16 v[84:87], v[172:175], v[188:191], v[84:87]
	v_pk_mul_f32 v[88:89], v[88:89], v[248:249] op_sel_hi:[1,0]
	v_pk_mul_f32 v[90:91], v[90:91], v[248:249] op_sel_hi:[1,0]
	ds_read_b64 v[172:173], v241 offset:11520
	ds_read_b64 v[174:175], v241 offset:11552
	s_waitcnt lgkmcnt(6)
	v_mfma_f32_16x16x32_bf16 v[56:59], v[176:179], v[184:187], v[56:59]
	v_pk_mul_f32 v[60:61], v[60:61], v[246:247] op_sel_hi:[1,0]
	v_pk_mul_f32 v[62:63], v[62:63], v[246:247] op_sel_hi:[1,0]
	v_mfma_f32_16x16x32_bf16 v[88:91], v[176:179], v[188:191], v[88:91]
	v_pk_mul_f32 v[92:93], v[92:93], v[248:249] op_sel_hi:[1,0]
	v_pk_mul_f32 v[94:95], v[94:95], v[248:249] op_sel_hi:[1,0]
	ds_read_b64 v[176:177], v241 offset:13824
	ds_read_b64 v[178:179], v241 offset:13856
	s_waitcnt lgkmcnt(6)
	v_mfma_f32_16x16x32_bf16 v[60:63], v[180:183], v[184:187], v[60:63]
	v_pk_mul_f32 v[64:65], v[64:65], v[246:247] op_sel_hi:[1,0]
	v_pk_mul_f32 v[66:67], v[66:67], v[246:247] op_sel_hi:[1,0]
	v_mfma_f32_16x16x32_bf16 v[92:95], v[180:183], v[188:191], v[92:95]
	v_pk_mul_f32 v[96:97], v[96:97], v[248:249] op_sel_hi:[1,0]
	v_pk_mul_f32 v[98:99], v[98:99], v[248:249] op_sel_hi:[1,0]
	ds_read_b64 v[180:181], v241 offset:16128
	ds_read_b64 v[182:183], v241 offset:16160
	s_waitcnt lgkmcnt(6)
	v_mfma_f32_16x16x32_bf16 v[64:67], v[168:171], v[184:187], v[64:67]
	v_pk_mul_f32 v[68:69], v[68:69], v[246:247] op_sel_hi:[1,0]
	v_pk_mul_f32 v[70:71], v[70:71], v[246:247] op_sel_hi:[1,0]
	v_mfma_f32_16x16x32_bf16 v[96:99], v[168:171], v[188:191], v[96:99]
	v_pk_mul_f32 v[100:101], v[100:101], v[248:249] op_sel_hi:[1,0]
	v_pk_mul_f32 v[102:103], v[102:103], v[248:249] op_sel_hi:[1,0]
	s_waitcnt lgkmcnt(4)
	v_mfma_f32_16x16x32_bf16 v[68:71], v[172:175], v[184:187], v[68:71]
	v_pk_mul_f32 v[72:73], v[72:73], v[246:247] op_sel_hi:[1,0]
	v_pk_mul_f32 v[74:75], v[74:75], v[246:247] op_sel_hi:[1,0]
	v_mfma_f32_16x16x32_bf16 v[100:103], v[172:175], v[188:191], v[100:103]
	v_pk_mul_f32 v[104:105], v[104:105], v[248:249] op_sel_hi:[1,0]
	v_pk_mul_f32 v[106:107], v[106:107], v[248:249] op_sel_hi:[1,0]
	s_waitcnt lgkmcnt(2)
	v_mfma_f32_16x16x32_bf16 v[72:75], v[176:179], v[184:187], v[72:75]
	v_pk_mul_f32 v[76:77], v[76:77], v[246:247] op_sel_hi:[1,0]
	v_pk_mul_f32 v[78:79], v[78:79], v[246:247] op_sel_hi:[1,0]
	v_mfma_f32_16x16x32_bf16 v[104:107], v[176:179], v[188:191], v[104:107]
	v_pk_mul_f32 v[108:109], v[108:109], v[248:249] op_sel_hi:[1,0]
	v_pk_mul_f32 v[110:111], v[110:111], v[248:249] op_sel_hi:[1,0]
	s_waitcnt lgkmcnt(0)
	v_mfma_f32_16x16x32_bf16 v[76:79], v[180:183], v[184:187], v[76:79]
	v_mfma_f32_16x16x32_bf16 v[108:111], v[180:183], v[188:191], v[108:111]
	s_waitcnt lgkmcnt(0)
	s_barrier
; template <int DK>
; DI void dense_attn_item(LAS unsigned char* lds, const bf16_t* Qb, int ldq, const bf16_t* Kb, int ldk, const bf16_t* Kpe, const bf16_t* Vt, int nkeys, float sl2, bf16_t* Ob) {
;     ...
;     for (int kt = 0; kt < ntiles; ++kt) {
;         const int cur = kt & 1;
;         if (kt + 1 < ntiles) DA_LOAD((kt + 1) * 64);
;         const LAS unsigned char* kb_ = lds + cur * KTILE; const LAS unsigned char* vb_ = lds + 2 * KTILE + cur * VTILE;
; #pragma unroll
;         for (int kc = 0; kc < 2; ++kc) {
;             f32x4 sacc[2][2];
; #pragma unroll
;             for (int kb = 0; kb < 2; ++kb) {
;                 sacc[0][kb] = (f32x4){0.f, 0.f, 0.f, 0.f}; sacc[1][kb] = (f32x4){0.f, 0.f, 0.f, 0.f};
; #pragma unroll
;                 for (int kh = 0; kh < KS / 2; ++kh) {
;                     const bf16x8 k0 = *(const LAS bf16x8*)(kb_ + ((2 * kc + kb) * 16 + r16) * KROW + (2 * kh) * 64 + q4 * 16);
;                     const bf16x8 k1 = *(const LAS bf16x8*)(kb_ + ((2 * kc + kb) * 16 + r16) * KROW + (2 * kh + 1) * 64 + q4 * 16);
;                     __builtin_amdgcn_s_setprio(1);
;                     sacc[0][kb] = MFMA16(k0, qf[0][2 * kh], sacc[0][kb]); sacc[1][kb] = MFMA16(k0, qf[1][2 * kh], sacc[1][kb]);
;                     sacc[0][kb] = MFMA16(k1, qf[0][2 * kh + 1], sacc[0][kb]); sacc[1][kb] = MFMA16(k1, qf[1][2 * kh + 1], sacc[1][kb]);
;                     __builtin_amdgcn_s_setprio(0);
;                 }
;             }
;             bf16x8 pb[2];
; #pragma unroll
;             for (int qg = 0; qg < 2; ++qg) {
;                 float mx = fmaxf(fmaxf(fmaxf(sacc[qg][0][0], sacc[qg][0][1]), fmaxf(sacc[qg][0][2], sacc[qg][0][3])), fmaxf(fmaxf(sacc[qg][1][0], sacc[qg][1][1]), fmaxf(sacc[qg][1][2], sacc[qg][1][3])));
;                 mx = fmaxf(mx, __shfl_xor(mx, 16)); mx = fmaxf(mx, __shfl_xor(mx, 32));
;                 const float mnew = fmaxf(mrun[qg], mx * sl2), alpha = fast_exp2(mrun[qg] - mnew);
;                 mrun[qg] = mnew;
;                 float ps = 0.f;
; #pragma unroll
;                 for (int kb = 0; kb < 2; ++kb)
; #pragma unroll
;                     for (int j = 0; j < 4; ++j) { const float pv = fast_exp2(sacc[qg][kb][j] * sl2 - mnew); sacc[qg][kb][j] = pv; ps += pv; }
;                 lsum[qg] = lsum[qg] * alpha + ps;
; #pragma unroll
;                 for (int d = 0; d < 8; ++d) oacc[qg][d] *= alpha;
	ds_read_b128 v[144:147], v240 offset:0
	ds_read_b128 v[148:151], v240 offset:64
	ds_read_b128 v[152:155], v240 offset:128
	ds_read_b128 v[156:159], v240 offset:192
	ds_read_b128 v[160:163], v240 offset:256
	ds_read_b128 v[164:167], v240 offset:320
	v_max3_f32 v192, v128, v129, v130
	v_max3_f32 v194, v136, v137, v138
	v_max3_f32 v193, v131, v132, v133
	v_max3_f32 v195, v139, v140, v141
	v_max3_f32 v192, v192, v134, v135
	v_max3_f32 v194, v194, v142, v143
	v_max_f32_e32 v192, v192, v193
	v_max_f32_e32 v194, v194, v195
	v_mov_b32_e32 v193, v192
	v_mov_b32_e32 v195, v194
	s_nop 1
	v_permlane16_swap_b32_e32 v192, v193
	s_waitcnt lgkmcnt(5)
	v_mfma_f32_16x16x32_bf16 v[112:115], v[144:147], v[0:3], 0
	v_permlane16_swap_b32_e32 v194, v195
	v_max_f32_e32 v192, v192, v193
	v_max_f32_e32 v194, v194, v195
	v_mfma_f32_16x16x32_bf16 v[120:123], v[144:147], v[24:27], 0
	v_mov_b32_e32 v193, v192
	v_mov_b32_e32 v195, v194
	s_nop 1
	ds_read_b128 v[144:147], v240 offset:6400
	s_waitcnt lgkmcnt(5)
	v_mfma_f32_16x16x32_bf16 v[112:115], v[148:151], v[4:7], v[112:115]
	v_permlane32_swap_b32_e32 v192, v193
	v_permlane32_swap_b32_e32 v194, v195
	v_max_f32_e32 v192, v192, v193
	v_mfma_f32_16x16x32_bf16 v[120:123], v[148:151], v[28:31], v[120:123]
	v_max_f32_e32 v194, v194, v195
	v_mul_f32_e32 v192, s22, v192
	v_mul_f32_e32 v194, s22, v194
	ds_read_b128 v[148:151], v240 offset:6464
	s_waitcnt lgkmcnt(5)
	v_mfma_f32_16x16x32_bf16 v[112:115], v[152:155], v[8:11], v[112:115]
	v_max_f32_e32 v193, v242, v192
	v_max_f32_e32 v195, v243, v194
	v_sub_f32_e32 v192, v242, v193
	v_mfma_f32_16x16x32_bf16 v[120:123], v[152:155], v[32:35], v[120:123]
	v_sub_f32_e32 v194, v243, v195
	v_exp_f32_e32 v246, v192
	v_exp_f32_e32 v248, v194
	ds_read_b128 v[152:155], v240 offset:6528
	s_waitcnt lgkmcnt(5)
	v_mfma_f32_16x16x32_bf16 v[112:115], v[156:159], v[12:15], v[112:115]
	v_mov_b32_e32 v242, v193
	v_mov_b32_e32 v243, v195
	v_fma_f32 v128, v128, s22, -v193
	v_mfma_f32_16x16x32_bf16 v[120:123], v[156:159], v[36:39], v[120:123]
	v_fma_f32 v136, v136, s22, -v195
	v_fma_f32 v129, v129, s22, -v193
	v_fma_f32 v137, v137, s22, -v195
	ds_read_b128 v[156:159], v240 offset:6592
	s_waitcnt lgkmcnt(5)
	v_mfma_f32_16x16x32_bf16 v[112:115], v[160:163], v[16:19], v[112:115]
	v_fma_f32 v130, v130, s22, -v193
	v_fma_f32 v138, v138, s22, -v195
	v_fma_f32 v131, v131, s22, -v193
	v_mfma_f32_16x16x32_bf16 v[120:123], v[160:163], v[40:43], v[120:123]
	v_fma_f32 v139, v139, s22, -v195
	v_fma_f32 v132, v132, s22, -v193
	v_fma_f32 v140, v140, s22, -v195
	ds_read_b128 v[160:163], v240 offset:6656
	s_waitcnt lgkmcnt(5)
	v_mfma_f32_16x16x32_bf16 v[112:115], v[164:167], v[20:23], v[112:115]
	v_fma_f32 v133, v133, s22, -v193
	v_fma_f32 v141, v141, s22, -v195
	v_fma_f32 v134, v134, s22, -v193
	v_mfma_f32_16x16x32_bf16 v[120:123], v[164:167], v[44:47], v[120:123]
	v_fma_f32 v142, v142, s22, -v195
	v_fma_f32 v135, v135, s22, -v193
	v_fma_f32 v143, v143, s22, -v195
	ds_read_b128 v[164:167], v240 offset:6720
	s_waitcnt lgkmcnt(5)
	v_mfma_f32_16x16x32_bf16 v[116:119], v[144:147], v[0:3], 0
	v_exp_f32_e32 v128, v128
	v_exp_f32_e32 v136, v136
	v_exp_f32_e32 v129, v129
	v_mfma_f32_16x16x32_bf16 v[124:127], v[144:147], v[24:27], 0
	v_exp_f32_e32 v137, v137
	v_exp_f32_e32 v130, v130
	v_exp_f32_e32 v138, v138
	ds_read_b64 v[168:169], v241 offset:64
	ds_read_b64 v[170:171], v241 offset:96
	s_waitcnt lgkmcnt(6)
	v_mfma_f32_16x16x32_bf16 v[116:119], v[148:151], v[4:7], v[116:119]
	v_exp_f32_e32 v131, v131
	v_exp_f32_e32 v139, v139
	v_exp_f32_e32 v132, v132
	v_mfma_f32_16x16x32_bf16 v[124:127], v[148:151], v[28:31], v[124:127]
	v_exp_f32_e32 v140, v140
	v_exp_f32_e32 v133, v133
	v_exp_f32_e32 v141, v141
	ds_read_b64 v[172:173], v241 offset:2368
	ds_read_b64 v[174:175], v241 offset:2400
	s_waitcnt lgkmcnt(7)
	v_mfma_f32_16x16x32_bf16 v[116:119], v[152:155], v[8:11], v[116:119]
	v_exp_f32_e32 v134, v134
	v_exp_f32_e32 v142, v142
	v_exp_f32_e32 v135, v135
	v_mfma_f32_16x16x32_bf16 v[124:127], v[152:155], v[32:35], v[124:127]
	v_exp_f32_e32 v143, v143
	v_add_f32_e32 v192, v128, v129
	v_add_f32_e32 v194, v136, v137
	ds_read_b64 v[176:177], v241 offset:4672
	ds_read_b64 v[178:179], v241 offset:4704
	s_waitcnt lgkmcnt(8)
	v_mfma_f32_16x16x32_bf16 v[116:119], v[156:159], v[12:15], v[116:119]
	v_add_f32_e32 v192, v192, v130
	v_add_f32_e32 v194, v194, v138
	v_add_f32_e32 v192, v192, v131
	v_mfma_f32_16x16x32_bf16 v[124:127], v[156:159], v[36:39], v[124:127]
	v_add_f32_e32 v194, v194, v139
	v_add_f32_e32 v192, v192, v132
	v_add_f32_e32 v194, v194, v140
	ds_read_b64 v[180:181], v241 offset:6976
	ds_read_b64 v[182:183], v241 offset:7008
	s_waitcnt lgkmcnt(9)
	v_mfma_f32_16x16x32_bf16 v[116:119], v[160:163], v[16:19], v[116:119]
	v_add_f32_e32 v192, v192, v133
	v_add_f32_e32 v194, v194, v141
	v_add_f32_e32 v192, v192, v134
	v_mfma_f32_16x16x32_bf16 v[124:127], v[160:163], v[40:43], v[124:127]
	v_add_f32_e32 v194, v194, v142
	v_add_f32_e32 v192, v192, v135
	v_add_f32_e32 v194, v194, v143
	s_waitcnt lgkmcnt(8)
	v_mfma_f32_16x16x32_bf16 v[116:119], v[164:167], v[20:23], v[116:119]
	v_fma_f32 v244, v244, v246, v192
	v_fma_f32 v245, v245, v248, v194
	v_cvt_pk_bf16_f32 v184, v128, v129
	v_mfma_f32_16x16x32_bf16 v[124:127], v[164:167], v[44:47], v[124:127]
	v_cvt_pk_bf16_f32 v188, v136, v137
	v_cvt_pk_bf16_f32 v185, v130, v131
	v_cvt_pk_bf16_f32 v189, v138, v139
	v_cvt_pk_bf16_f32 v186, v132, v133
	v_cvt_pk_bf16_f32 v190, v140, v141
	v_cvt_pk_bf16_f32 v187, v134, v135
	v_cvt_pk_bf16_f32 v191, v142, v143
	v_pk_mul_f32 v[48:49], v[48:49], v[246:247] op_sel_hi:[1,0]
	v_pk_mul_f32 v[50:51], v[50:51], v[246:247] op_sel_hi:[1,0]
	v_pk_mul_f32 v[80:81], v[80:81], v[248:249] op_sel_hi:[1,0]
	v_pk_mul_f32 v[82:83], v[82:83], v[248:249] op_sel_hi:[1,0]
	s_waitcnt lgkmcnt(6)
; #define LAS __attribute__((address_space(3)))
; #define MFMA16(a, b, c) __builtin_amdgcn_mfma_f32_16x16x32_bf16((a), (b), (c), 0, 0, 0)
; template <int DK>
; DI void dense_attn_item(LAS unsigned char* lds, const bf16_t* Qb, int ldq, const bf16_t* Kb, int ldk, const bf16_t* Kpe, const bf16_t* Vt, int nkeys, float sl2, bf16_t* Ob) {
;     ...
; #pragma unroll
;             for (int dh = 0; dh < 4; ++dh) {
;                 bf16x8 vfr[2];
; #pragma unroll
;                 for (int d4 = 0; d4 < 2; ++d4) {
;                     const int d = dh * 2 + d4;
;                     const u32x2 lo = *(const LAS u32x2*)(vb_ + (d * 16 + r16) * VROW + (kc * 32 + q4 * 4) * 2);
;                     const u32x2 hi = *(const LAS u32x2*)(vb_ + (d * 16 + r16) * VROW + (kc * 32 + 16 + q4 * 4) * 2);
;                     u32x4 w; w.x = lo.x; w.y = lo.y; w.z = hi.x; w.w = hi.y;
;                     vfr[d4] = __builtin_bit_cast(bf16x8, w);
;                 }
;                 __builtin_amdgcn_s_setprio(1);
; #pragma unroll
;                 for (int d4 = 0; d4 < 2; ++d4) { const int d = dh * 2 + d4; oacc[0][d] = MFMA16(vfr[d4], pb[0], oacc[0][d]); oacc[1][d] = MFMA16(vfr[d4], pb[1], oacc[1][d]); }
;                 __builtin_amdgcn_s_setprio(0);
;             }
;         }
;         if (kt + 1 < ntiles) DA_STORE(cur ^ 1);
;         __syncthreads();
;     }
	v_mfma_f32_16x16x32_bf16 v[48:51], v[168:171], v[184:187], v[48:51]
	v_pk_mul_f32 v[52:53], v[52:53], v[246:247] op_sel_hi:[1,0]
	v_pk_mul_f32 v[54:55], v[54:55], v[246:247] op_sel_hi:[1,0]
	v_mfma_f32_16x16x32_bf16 v[80:83], v[168:171], v[188:191], v[80:83]
	v_pk_mul_f32 v[84:85], v[84:85], v[248:249] op_sel_hi:[1,0]
	v_pk_mul_f32 v[86:87], v[86:87], v[248:249] op_sel_hi:[1,0]
	ds_read_b64 v[168:169], v241 offset:9280
	ds_read_b64 v[170:171], v241 offset:9312
	s_waitcnt lgkmcnt(6)
	v_mfma_f32_16x16x32_bf16 v[52:55], v[172:175], v[184:187], v[52:55]
	v_pk_mul_f32 v[56:57], v[56:57], v[246:247] op_sel_hi:[1,0]
	v_pk_mul_f32 v[58:59], v[58:59], v[246:247] op_sel_hi:[1,0]
	v_mfma_f32_16x16x32_bf16 v[84:87], v[172:175], v[188:191], v[84:87]
	v_pk_mul_f32 v[88:89], v[88:89], v[248:249] op_sel_hi:[1,0]
	v_pk_mul_f32 v[90:91], v[90:91], v[248:249] op_sel_hi:[1,0]
	ds_read_b64 v[172:173], v241 offset:11584
	ds_read_b64 v[174:175], v241 offset:11616
	s_waitcnt lgkmcnt(6)
	v_mfma_f32_16x16x32_bf16 v[56:59], v[176:179], v[184:187], v[56:59]
	v_pk_mul_f32 v[60:61], v[60:61], v[246:247] op_sel_hi:[1,0]
	v_pk_mul_f32 v[62:63], v[62:63], v[246:247] op_sel_hi:[1,0]
	v_mfma_f32_16x16x32_bf16 v[88:91], v[176:179], v[188:191], v[88:91]
	v_pk_mul_f32 v[92:93], v[92:93], v[248:249] op_sel_hi:[1,0]
	v_pk_mul_f32 v[94:95], v[94:95], v[248:249] op_sel_hi:[1,0]
	ds_read_b64 v[176:177], v241 offset:13888
	ds_read_b64 v[178:179], v241 offset:13920
	s_waitcnt lgkmcnt(6)
	v_mfma_f32_16x16x32_bf16 v[60:63], v[180:183], v[184:187], v[60:63]
	v_pk_mul_f32 v[64:65], v[64:65], v[246:247] op_sel_hi:[1,0]
	v_pk_mul_f32 v[66:67], v[66:67], v[246:247] op_sel_hi:[1,0]
	v_mfma_f32_16x16x32_bf16 v[92:95], v[180:183], v[188:191], v[92:95]
	v_pk_mul_f32 v[96:97], v[96:97], v[248:249] op_sel_hi:[1,0]
	v_pk_mul_f32 v[98:99], v[98:99], v[248:249] op_sel_hi:[1,0]
	ds_read_b64 v[180:181], v241 offset:16192
	ds_read_b64 v[182:183], v241 offset:16224
	s_waitcnt lgkmcnt(6)
	v_mfma_f32_16x16x32_bf16 v[64:67], v[168:171], v[184:187], v[64:67]
	v_pk_mul_f32 v[68:69], v[68:69], v[246:247] op_sel_hi:[1,0]
	v_pk_mul_f32 v[70:71], v[70:71], v[246:247] op_sel_hi:[1,0]
	v_mfma_f32_16x16x32_bf16 v[96:99], v[168:171], v[188:191], v[96:99]
	v_pk_mul_f32 v[100:101], v[100:101], v[248:249] op_sel_hi:[1,0]
	v_pk_mul_f32 v[102:103], v[102:103], v[248:249] op_sel_hi:[1,0]
	s_waitcnt lgkmcnt(4)
	v_mfma_f32_16x16x32_bf16 v[68:71], v[172:175], v[184:187], v[68:71]
	v_pk_mul_f32 v[72:73], v[72:73], v[246:247] op_sel_hi:[1,0]
	v_pk_mul_f32 v[74:75], v[74:75], v[246:247] op_sel_hi:[1,0]
	v_mfma_f32_16x16x32_bf16 v[100:103], v[172:175], v[188:191], v[100:103]
	v_pk_mul_f32 v[104:105], v[104:105], v[248:249] op_sel_hi:[1,0]
	v_pk_mul_f32 v[106:107], v[106:107], v[248:249] op_sel_hi:[1,0]
	s_waitcnt lgkmcnt(2)
	v_mfma_f32_16x16x32_bf16 v[72:75], v[176:179], v[184:187], v[72:75]
	v_pk_mul_f32 v[76:77], v[76:77], v[246:247] op_sel_hi:[1,0]
	v_pk_mul_f32 v[78:79], v[78:79], v[246:247] op_sel_hi:[1,0]
	v_mfma_f32_16x16x32_bf16 v[104:107], v[176:179], v[188:191], v[104:107]
	v_pk_mul_f32 v[108:109], v[108:109], v[248:249] op_sel_hi:[1,0]
	v_pk_mul_f32 v[110:111], v[110:111], v[248:249] op_sel_hi:[1,0]
	s_waitcnt lgkmcnt(0)
	v_mfma_f32_16x16x32_bf16 v[76:79], v[180:183], v[184:187], v[76:79]
	v_mfma_f32_16x16x32_bf16 v[108:111], v[180:183], v[188:191], v[108:111]
	s_mov_b32 s27, s57
	s_add_u32 s23, s23, 1
	s_cmp_lt_u32 s23, 36
	s_cbranch_scc1 dn0_top
; #define LAS __attribute__((address_space(3)))
; DI unsigned xb_add(unsigned* p, unsigned v) { return __hip_atomic_fetch_add(p, v, __ATOMIC_RELAXED, __HIP_MEMORY_SCOPE_AGENT); }
; DI void st_bf16x4(bf16_t* p, f32x4 v) { u32x2 w; w.x = cvt_pk_bf16(v[0], v[1]); w.y = cvt_pk_bf16(v[2], v[3]); *(u32x2*)p = w; }
; DI int next_item(unsigned* ctr, volatile LAS int* slot) {
;     __syncthreads();
;     if (threadIdx.x == 0) *slot = (int)xb_add(ctr, 1u);
;     __syncthreads();
;     return *slot;
; template <int DK>
; DI void dense_attn_item(LAS unsigned char* lds, const bf16_t* Qb, int ldq, const bf16_t* Kb, int ldk, const bf16_t* Kpe, const bf16_t* Vt, int nkeys, float sl2, bf16_t* Ob) {
;     ...
; #pragma unroll
;     for (int qg = 0; qg < 2; ++qg) {
;         float l = lsum[qg]; l += __shfl_xor(l, 16); l += __shfl_xor(l, 32);
;         const float inv = 1.f / l;
;         bf16_t* op = Ob + (size_t)(wid * 32 + qg * 16 + r16) * DM + q4 * 4;
; #pragma unroll
;         for (int d = 0; d < 8; ++d) st_bf16x4(op + d * 16, oacc[qg][d] * inv);
;     }
	s_waitcnt vmcnt(0) lgkmcnt(0)
	v_mov_b32_e32 v192, v244
	v_mov_b32_e32 v193, v244
	v_mov_b32_e32 v194, v245
	v_mov_b32_e32 v195, v245
	s_nop 1
	v_permlane16_swap_b32_e32 v192, v193
	v_permlane16_swap_b32_e32 v194, v195
	v_add_f32_e32 v192, v192, v193
	v_add_f32_e32 v194, v194, v195
	v_mov_b32_e32 v193, v192
	v_mov_b32_e32 v195, v194
	s_nop 1
	v_permlane32_swap_b32_e32 v192, v193
	v_permlane32_swap_b32_e32 v194, v195
	v_add_f32_e32 v192, v192, v193
	v_add_f32_e32 v194, v194, v195
	v_rcp_f32_e32 v193, v192
	v_rcp_f32_e32 v195, v194
	s_nop 0
	v_fma_f32 v192, -v192, v193, 1.0
	v_fma_f32 v194, -v194, v195, 1.0
	v_fma_f32 v246, v192, v193, v193
	v_fma_f32 v248, v194, v195, v195
	v_pk_mul_f32 v[48:49], v[48:49], v[246:247] op_sel_hi:[1,0]
	v_pk_mul_f32 v[50:51], v[50:51], v[246:247] op_sel_hi:[1,0]
	v_cvt_pk_bf16_f32 v48, v48, v49
	v_cvt_pk_bf16_f32 v49, v50, v51
	global_store_dwordx2 v250, v[48:49], s[20:21] offset:0
	v_pk_mul_f32 v[52:53], v[52:53], v[246:247] op_sel_hi:[1,0]
	v_pk_mul_f32 v[54:55], v[54:55], v[246:247] op_sel_hi:[1,0]
	v_cvt_pk_bf16_f32 v52, v52, v53
	v_cvt_pk_bf16_f32 v53, v54, v55
	global_store_dwordx2 v250, v[52:53], s[20:21] offset:32
	v_pk_mul_f32 v[56:57], v[56:57], v[246:247] op_sel_hi:[1,0]
	v_pk_mul_f32 v[58:59], v[58:59], v[246:247] op_sel_hi:[1,0]
	v_cvt_pk_bf16_f32 v56, v56, v57
	v_cvt_pk_bf16_f32 v57, v58, v59
	global_store_dwordx2 v250, v[56:57], s[20:21] offset:64
	v_pk_mul_f32 v[60:61], v[60:61], v[246:247] op_sel_hi:[1,0]
	v_pk_mul_f32 v[62:63], v[62:63], v[246:247] op_sel_hi:[1,0]
	v_cvt_pk_bf16_f32 v60, v60, v61
	v_cvt_pk_bf16_f32 v61, v62, v63
	global_store_dwordx2 v250, v[60:61], s[20:21] offset:96
	v_pk_mul_f32 v[64:65], v[64:65], v[246:247] op_sel_hi:[1,0]
	v_pk_mul_f32 v[66:67], v[66:67], v[246:247] op_sel_hi:[1,0]
	v_cvt_pk_bf16_f32 v64, v64, v65
	v_cvt_pk_bf16_f32 v65, v66, v67
	global_store_dwordx2 v250, v[64:65], s[20:21] offset:128
	v_pk_mul_f32 v[68:69], v[68:69], v[246:247] op_sel_hi:[1,0]
	v_pk_mul_f32 v[70:71], v[70:71], v[246:247] op_sel_hi:[1,0]
	v_cvt_pk_bf16_f32 v68, v68, v69
	v_cvt_pk_bf16_f32 v69, v70, v71
	global_store_dwordx2 v250, v[68:69], s[20:21] offset:160
	v_pk_mul_f32 v[72:73], v[72:73], v[246:247] op_sel_hi:[1,0]
	v_pk_mul_f32 v[74:75], v[74:75], v[246:247] op_sel_hi:[1,0]
	v_cvt_pk_bf16_f32 v72, v72, v73
	v_cvt_pk_bf16_f32 v73, v74, v75
	global_store_dwordx2 v250, v[72:73], s[20:21] offset:192
	v_pk_mul_f32 v[76:77], v[76:77], v[246:247] op_sel_hi:[1,0]
	v_pk_mul_f32 v[78:79], v[78:79], v[246:247] op_sel_hi:[1,0]
	v_cvt_pk_bf16_f32 v76, v76, v77
	v_cvt_pk_bf16_f32 v77, v78, v79
	global_store_dwordx2 v250, v[76:77], s[20:21] offset:224
	v_pk_mul_f32 v[80:81], v[80:81], v[248:249] op_sel_hi:[1,0]
	v_pk_mul_f32 v[82:83], v[82:83], v[248:249] op_sel_hi:[1,0]
	v_cvt_pk_bf16_f32 v80, v80, v81
	v_cvt_pk_bf16_f32 v81, v82, v83
	global_store_dwordx2 v251, v[80:81], s[20:21] offset:0
	v_pk_mul_f32 v[84:85], v[84:85], v[248:249] op_sel_hi:[1,0]
	v_pk_mul_f32 v[86:87], v[86:87], v[248:249] op_sel_hi:[1,0]
	v_cvt_pk_bf16_f32 v84, v84, v85
	v_cvt_pk_bf16_f32 v85, v86, v87
	global_store_dwordx2 v251, v[84:85], s[20:21] offset:32
	v_pk_mul_f32 v[88:89], v[88:89], v[248:249] op_sel_hi:[1,0]
	v_pk_mul_f32 v[90:91], v[90:91], v[248:249] op_sel_hi:[1,0]
	v_cvt_pk_bf16_f32 v88, v88, v89
	v_cvt_pk_bf16_f32 v89, v90, v91
	global_store_dwordx2 v251, v[88:89], s[20:21] offset:64
	v_pk_mul_f32 v[92:93], v[92:93], v[248:249] op_sel_hi:[1,0]
	v_pk_mul_f32 v[94:95], v[94:95], v[248:249] op_sel_hi:[1,0]
	v_cvt_pk_bf16_f32 v92, v92, v93
	v_cvt_pk_bf16_f32 v93, v94, v95
	global_store_dwordx2 v251, v[92:93], s[20:21] offset:96
	v_pk_mul_f32 v[96:97], v[96:97], v[248:249] op_sel_hi:[1,0]
	v_pk_mul_f32 v[98:99], v[98:99], v[248:249] op_sel_hi:[1,0]
	v_cvt_pk_bf16_f32 v96, v96, v97
	v_cvt_pk_bf16_f32 v97, v98, v99
	global_store_dwordx2 v251, v[96:97], s[20:21] offset:128
	v_pk_mul_f32 v[100:101], v[100:101], v[248:249] op_sel_hi:[1,0]
	v_pk_mul_f32 v[102:103], v[102:103], v[248:249] op_sel_hi:[1,0]
	v_cvt_pk_bf16_f32 v100, v100, v101
	v_cvt_pk_bf16_f32 v101, v102, v103
	global_store_dwordx2 v251, v[100:101], s[20:21] offset:160
	v_pk_mul_f32 v[104:105], v[104:105], v[248:249] op_sel_hi:[1,0]
	v_pk_mul_f32 v[106:107], v[106:107], v[248:249] op_sel_hi:[1,0]
	v_cvt_pk_bf16_f32 v104, v104, v105
	v_cvt_pk_bf16_f32 v105, v106, v107
	global_store_dwordx2 v251, v[104:105], s[20:21] offset:192
	v_pk_mul_f32 v[108:109], v[108:109], v[248:249] op_sel_hi:[1,0]
	v_pk_mul_f32 v[110:111], v[110:111], v[248:249] op_sel_hi:[1,0]
	v_cvt_pk_bf16_f32 v108, v108, v109
	v_cvt_pk_bf16_f32 v109, v110, v111
	global_store_dwordx2 v251, v[108:109], s[20:21] offset:224
	v_mov_b32_e32 v133, 0
	s_waitcnt vmcnt(0)
	s_barrier
	s_and_saveexec_b64 s[0:1], s[24:25]
	s_cbranch_execz .LBB0_1145
	s_mov_b64 s[8:9], exec
	v_mbcnt_lo_u32_b32 v0, s8, 0
	v_mbcnt_hi_u32_b32 v0, s9, v0
	v_cmp_eq_u32_e32 vcc, 0, v0
	s_and_saveexec_b64 s[6:7], vcc
	s_cbranch_execz .LBB0_1144
	s_bcnt1_i32_b64 s8, s[8:9]
	v_mov_b32_e32 v1, s8
	global_atomic_add v1, v133, v1, s[42:43] sc0
	s_branch .LBB0_1144

; #define LAS __attribute__((address_space(3)))
; DI void na_block_item(const Params& p, int l, int b, int h, int rp, LAS unsigned char* lds) {
;     const int tid = otid(), lane = tid & 63, wid = tid >> 6, r16 = lane & 15, q4 = lane >> 4;
;     unsigned char* ws = p.ws;
;     const bf16_t* P = (const bf16_t*)(ws + WS_P);
;     constexpr int KROW = 272, KTILE = 64 * KROW, VROW = 144, VTILE = 128 * VROW;
;     const int gr = 2 * rp + (wid >> 2), jq = wid & 3;
;     const int gc = jq * 16 + r16, r0w = min(max(gr - 4, 0), 24), band = min(max(jq * 16 - 8, 0), 32), cs = min(max(gc - 8, 0), 48);
;     const int r0a = min(max(2 * rp - 4, 0), 24), r0b = min(max(2 * rp - 3, 0), 24), nloc = r0b + 8 - r0a, ntl = nloc + 4;
;     const size_t rowb = (size_t)b * RB, rowq = rowb + CL + gr * 64 + gc;
;     const float sl2 = 0.08838834764831845f * 1.4426950408889634f;
;     const float* rpb = p.in[11] + (size_t)(l * 6 + h) * 15 * 31;
;     bf16x8 qf[4];
; #pragma unroll
;     for (int ks = 0; ks < 4; ++ks) qf[ks] = *(const bf16x8*)(P + rowq * INP + C_NAQ + h * 128 + ks * 32 + q4 * 8);
;     f32x4 oacc[8];
; #pragma unroll
;     for (int d = 0; d < 8; ++d) oacc[d] = (f32x4){0.f, 0.f, 0.f, 0.f};
;     float mrun = -1e30f, lsum = 0.f;
;     const bf16_t* kg = P + rowb * INP + C_NAK + h * 128;
;     const bf16_t* vg = (const bf16_t*)(ws + WS_VTNA) + ((size_t)b * 768 + h * 128) * RB;
;     u32x4 kstA[2], vstA[2], kstB[2], vstB[2];
;     ...
;     LAS float* s_rpb = (LAS float*)(lds + 3 * KTILE + 3 * VTILE);
;     if (tid < 465) s_rpb[tid] = rpb[tid];
;     ...
;                 const LAS float* rp_ = s_rpb + (kr - gr + 7) * 31;
; #pragma unroll
;                 for (int e = 0; e < 8; ++e) { const int kcol = band + (e >> 2) * 16 + q4 * 4 + (e & 3); bias8[e] = rp_[min(max(kcol - gc + 15, 0), 30)]; }
;             }
;             f32x4 s[2];
; #pragma unroll
;             for (int hf = 0; hf < 2; ++hf) {
;                 s[hf] = (f32x4){0.f, 0.f, 0.f, 0.f};
; #pragma unroll
;                 for (int ks = 0; ks < 4; ++ks) s[hf] = MFMA16(*(const LAS bf16x8*)(kb_ + hf * 16 * KROW + ks * 64), qf[ks], s[hf]);
;             }
;             if (local) {
; #pragma unroll
;                 for (int hf = 0; hf < 2; ++hf)
; #pragma unroll
;                     for (int j = 0; j < 4; ++j) {
;                         const int kcol = band + hf * 16 + q4 * 4 + j; const bool inw = kcol >= cs && kcol < cs + 16;
.LBB0_1183:
	s_cmpk_gt_u32 s28, 0x387
	s_cbranch_scc1 .LBB0_1234
	s_mov_b32 s29, s28
	s_mov_b32 s22, 0x3e0293ee
	s_mov_b32 s23, 0x3fb8aa3b
	v_and_b32_e32 v196, 15, v202
	v_bfe_u32 v197, v202, 4, 2
	v_lshrrev_b32_e32 v198, 6, v202
	s_nop 0
	v_readfirstlane_b32 s74, v198
	v_mov_b32_e32 v199, v202
	v_lshrrev_b32_e32 v200, 4, v199
	v_and_b32_e32 v201, 15, v199
	v_lshlrev_b32_e32 v201, 4, v201
	v_mul_u32_u24_e32 v230, 0x3000, v200
	v_add_u32_e32 v230, v230, v201
	v_mul_u32_u24_e32 v234, 0x110, v200
	v_add_u32_e32 v234, v234, v201
	v_lshrrev_b32_e32 v200, 3, v199
	v_and_b32_e32 v201, 7, v199
	v_lshlrev_b32_e32 v201, 4, v201
	v_mul_u32_u24_e32 v232, 0x1200, v200
	v_add_u32_e32 v232, v232, v201
	v_mul_u32_u24_e32 v236, 0x90, v200
	v_add_u32_e32 v236, v236, v201
	v_add_u32_e32 v236, 0xcc00, v236
	v_add_u32_e32 v199, 0x200, v202
	v_lshrrev_b32_e32 v200, 4, v199
	v_and_b32_e32 v201, 15, v199
	v_lshlrev_b32_e32 v201, 4, v201
	v_mul_u32_u24_e32 v231, 0x3000, v200
	v_add_u32_e32 v231, v231, v201
	v_mul_u32_u24_e32 v235, 0x110, v200
	v_add_u32_e32 v235, v235, v201
	v_lshrrev_b32_e32 v200, 3, v199
	v_and_b32_e32 v201, 7, v199
	v_lshlrev_b32_e32 v201, 4, v201
	v_mul_u32_u24_e32 v233, 0x1200, v200
	v_add_u32_e32 v233, v233, v201
	v_mul_u32_u24_e32 v237, 0x90, v200
	v_add_u32_e32 v237, v237, v201
	v_add_u32_e32 v237, 0xcc00, v237
	v_mul_u32_u24_e32 v199, 0x110, v196
	v_lshl_add_u32 v238, v197, 4, v199
	v_mul_u32_u24_e32 v199, 0x90, v196
	v_lshl_add_u32 v199, v197, 3, v199
	v_add_u32_e32 v239, 0xcc00, v199
	v_mul_u32_u24_e32 v199, 0x3000, v196
	v_lshl_add_u32 v251, v197, 4, v199
	v_lshlrev_b32_e32 v199, 12, v196
	v_lshl_add_u32 v246, v197, 3, v199
	s_and_b32 s73, s74, 3
	s_lshl_b32 s73, s73, 4
	s_sub_i32 s56, s73, 8
	s_max_i32 s56, s56, 0
	s_min_i32 s56, s56, 32
	v_add_u32_e32 v220, s73, v196
	v_subrev_u32_e32 v221, 8, v220
	v_max_i32_e32 v221, 0, v221
	v_min_i32_e32 v221, 48, v221
	v_add_u32_e32 v222, 16, v221
	v_lshlrev_b32_e32 v223, 2, v197
	v_mov_b32_e32 v224, 0xf149f2ca
	v_mov_b32_e32 v225, 0x7f7fffff
	s_add_u32 s57, s56, 0
	v_add_u32_e32 v199, s57, v223
	v_sub_u32_e32 v200, v199, v220
	v_add_u32_e32 v200, 15, v200
	v_max_i32_e32 v200, 0, v200
	v_min_i32_e32 v200, 30, v200
	v_lshlrev_b32_e32 v200, 2, v200
	v_add_u32_e32 v132, 0x1a400, v200
	v_cmp_ge_i32_e32 vcc, v199, v221
	v_cmp_lt_i32_e64 s[0:1], v199, v222
	s_and_b64 vcc, vcc, s[0:1]
	v_cndmask_b32_e32 v140, v224, v225, vcc
	s_add_u32 s57, s56, 1
	v_add_u32_e32 v199, s57, v223
	v_sub_u32_e32 v200, v199, v220
	v_add_u32_e32 v200, 15, v200
	v_max_i32_e32 v200, 0, v200
	v_min_i32_e32 v200, 30, v200
	v_lshlrev_b32_e32 v200, 2, v200
	v_add_u32_e32 v133, 0x1a400, v200
	v_cmp_ge_i32_e32 vcc, v199, v221
	v_cmp_lt_i32_e64 s[0:1], v199, v222
	s_and_b64 vcc, vcc, s[0:1]
	v_cndmask_b32_e32 v141, v224, v225, vcc
	s_add_u32 s57, s56, 2
	v_add_u32_e32 v199, s57, v223
	v_sub_u32_e32 v200, v199, v220
	v_add_u32_e32 v200, 15, v200
	v_max_i32_e32 v200, 0, v200
	v_min_i32_e32 v200, 30, v200
	v_lshlrev_b32_e32 v200, 2, v200
	v_add_u32_e32 v134, 0x1a400, v200
	v_cmp_ge_i32_e32 vcc, v199, v221
	v_cmp_lt_i32_e64 s[0:1], v199, v222
	s_and_b64 vcc, vcc, s[0:1]
	v_cndmask_b32_e32 v142, v224, v225, vcc
	s_add_u32 s57, s56, 3
	v_add_u32_e32 v199, s57, v223
	v_sub_u32_e32 v200, v199, v220
	v_add_u32_e32 v200, 15, v200
	v_max_i32_e32 v200, 0, v200
	v_min_i32_e32 v200, 30, v200
	v_lshlrev_b32_e32 v200, 2, v200
	v_add_u32_e32 v135, 0x1a400, v200
	v_cmp_ge_i32_e32 vcc, v199, v221
	v_cmp_lt_i32_e64 s[0:1], v199, v222
	s_and_b64 vcc, vcc, s[0:1]
	v_cndmask_b32_e32 v143, v224, v225, vcc
	s_add_u32 s57, s56, 16
	v_add_u32_e32 v199, s57, v223
	v_sub_u32_e32 v200, v199, v220
	v_add_u32_e32 v200, 15, v200
	v_max_i32_e32 v200, 0, v200
	v_min_i32_e32 v200, 30, v200
	v_lshlrev_b32_e32 v200, 2, v200
	v_add_u32_e32 v136, 0x1a400, v200
	v_cmp_ge_i32_e32 vcc, v199, v221
	v_cmp_lt_i32_e64 s[0:1], v199, v222
	s_and_b64 vcc, vcc, s[0:1]
	v_cndmask_b32_e32 v144, v224, v225, vcc
	s_add_u32 s57, s56, 17
	v_add_u32_e32 v199, s57, v223
	v_sub_u32_e32 v200, v199, v220
	v_add_u32_e32 v200, 15, v200
	v_max_i32_e32 v200, 0, v200
	v_min_i32_e32 v200, 30, v200
	v_lshlrev_b32_e32 v200, 2, v200
	v_add_u32_e32 v137, 0x1a400, v200
	v_cmp_ge_i32_e32 vcc, v199, v221
	v_cmp_lt_i32_e64 s[0:1], v199, v222
	s_and_b64 vcc, vcc, s[0:1]
	v_cndmask_b32_e32 v145, v224, v225, vcc
	s_add_u32 s57, s56, 18
	v_add_u32_e32 v199, s57, v223
	v_sub_u32_e32 v200, v199, v220
	v_add_u32_e32 v200, 15, v200
	v_max_i32_e32 v200, 0, v200
	v_min_i32_e32 v200, 30, v200
	v_lshlrev_b32_e32 v200, 2, v200
	v_add_u32_e32 v138, 0x1a400, v200
	v_cmp_ge_i32_e32 vcc, v199, v221
	v_cmp_lt_i32_e64 s[0:1], v199, v222
	s_and_b64 vcc, vcc, s[0:1]
	v_cndmask_b32_e32 v146, v224, v225, vcc
	s_add_u32 s57, s56, 19
	v_add_u32_e32 v199, s57, v223
	v_sub_u32_e32 v200, v199, v220
	v_add_u32_e32 v200, 15, v200
	v_max_i32_e32 v200, 0, v200
	v_min_i32_e32 v200, 30, v200
	v_lshlrev_b32_e32 v200, 2, v200
	v_add_u32_e32 v139, 0x1a400, v200
	v_cmp_ge_i32_e32 vcc, v199, v221
	v_cmp_lt_i32_e64 s[0:1], v199, v222
	s_and_b64 vcc, vcc, s[0:1]
	v_cndmask_b32_e32 v147, v224, v225, vcc
	v_readlane_b32 s10, v255, 62
	v_readlane_b32 s11, v255, 63
	s_nop 4
	s_load_dwordx2 s[100:101], s[10:11], 0x58
	s_waitcnt lgkmcnt(0)
	v_writelane_b32 v254, s100, 0
	v_writelane_b32 v254, s101, 1
	v_writelane_b32 v254, s74, 2
; #define LAS __attribute__((address_space(3)))
; #define NA_LOAD(t, ks_, vs_) do { const int tb_ = NA_TB(t); \
;         _Pragma("unroll") for (int i = 0; i < 2; ++i) { const int cid = tid + i * 512; \
;             ks_[i] = *(const u32x4*)(kg + (size_t)(tb_ + (cid >> 4)) * INP + (cid & 15) * 8); \
;             vs_[i] = *(const u32x4*)(vg + (size_t)(cid >> 3) * RB + tb_ + (cid & 7) * 8); } } while (0)
; #define NA_STORE(buf, ks_, vs_) do { \
;         _Pragma("unroll") for (int i = 0; i < 2; ++i) { const int cid = tid + i * 512; \
;             *(LAS u32x4*)(lds + (buf) * KTILE + (cid >> 4) * KROW + (cid & 15) * 16) = ks_[i]; \
;             *(LAS u32x4*)(lds + 3 * KTILE + (buf) * VTILE + (cid >> 3) * VROW + (cid & 7) * 16) = vs_[i]; } } while (0)
; DI void na_block_item(const Params& p, int l, int b, int h, int rp, LAS unsigned char* lds) {
;     ...
;     const int gr = 2 * rp + (wid >> 2), jq = wid & 3;
;     const int gc = jq * 16 + r16, r0w = min(max(gr - 4, 0), 24), band = min(max(jq * 16 - 8, 0), 32), cs = min(max(gc - 8, 0), 48);
;     const int r0a = min(max(2 * rp - 4, 0), 24), r0b = min(max(2 * rp - 3, 0), 24), nloc = r0b + 8 - r0a, ntl = nloc + 4;
;     const size_t rowb = (size_t)b * RB, rowq = rowb + CL + gr * 64 + gc;
;     const float sl2 = 0.08838834764831845f * 1.4426950408889634f;
;     const float* rpb = p.in[11] + (size_t)(l * 6 + h) * 15 * 31;
;     bf16x8 qf[4];
; #pragma unroll
;     for (int ks = 0; ks < 4; ++ks) qf[ks] = *(const bf16x8*)(P + rowq * INP + C_NAQ + h * 128 + ks * 32 + q4 * 8);
;     f32x4 oacc[8];
; #pragma unroll
;     for (int d = 0; d < 8; ++d) oacc[d] = (f32x4){0.f, 0.f, 0.f, 0.f};
;     float mrun = -1e30f, lsum = 0.f;
;     const bf16_t* kg = P + rowb * INP + C_NAK + h * 128;
;     const bf16_t* vg = (const bf16_t*)(ws + WS_VTNA) + ((size_t)b * 768 + h * 128) * RB;
;     u32x4 kstA[2], vstA[2], kstB[2], vstB[2];
;     ...
;     LAS float* s_rpb = (LAS float*)(lds + 3 * KTILE + 3 * VTILE);
;     if (tid < 465) s_rpb[tid] = rpb[tid];
;     NA_LOAD(0, kstA, vstA); NA_LOAD(1, kstB, vstB);
;     NA_STORE(0, kstA, vstA);
;     NA_LOAD(2, kstA, vstA);
;     __syncthreads();
na0_item:
	s_sub_u32 s57, s29, 0x208
	s_and_b32 s101, s57, 15
	s_lshr_b32 s57, s57, 4
	s_mul_i32 s99, s57, 43
	s_lshr_b32 s99, s99, 8
	s_mul_i32 s63, s99, 6
	s_sub_u32 s98, s57, s63
	s_lshl_b32 s57, s101, 1
	s_sub_i32 s36, s57, 4
	s_max_i32 s36, s36, 0
	s_min_i32 s36, s36, 24
	s_sub_i32 s63, s57, 3
	s_max_i32 s63, s63, 0
	s_min_i32 s63, s63, 24
	s_sub_u32 s30, s63, s36
	s_add_u32 s30, s30, 8
	s_add_u32 s31, s30, 4
	v_readlane_b32 s74, v254, 2
	s_lshr_b32 s63, s74, 2
	s_add_u32 s37, s57, s63
	s_sub_i32 s54, s37, 4
	s_max_i32 s54, s54, 0
	s_min_i32 s54, s54, 24
	s_mul_i32 s68, s99, 0x900
	s_mul_i32 s57, s68, 0x3000
	s_lshl_b32 s63, s98, 8
	s_add_u32 s57, s57, s63
	s_add_u32 s57, s57, 0x113a0600
	s_add_u32 s2, s50, s57
	s_addc_u32 s3, s51, 0
	s_mul_i32 s57, s99, 0x300
	s_lshl_b32 s69, s98, 7
	s_add_u32 s57, s57, s69
	s_mul_i32 s57, s57, 0x1200
	s_add_u32 s57, s57, 0x17fa0000
	s_add_u32 s4, s50, s57
	s_addc_u32 s5, s51, 0
	s_and_b32 s69, s74, 3
	s_lshl_b32 s69, s69, 4
	s_lshl_b32 s70, s37, 6
	s_add_u32 s69, s69, s70
	s_add_u32 s69, s69, s68
	s_addk_i32 s69, 0x100
	s_mul_i32 s57, s69, 0x3000
	s_add_u32 s57, s57, s63
	s_add_u32 s57, s57, 0x113a0000
	s_add_u32 s6, s50, s57
	s_addc_u32 s7, s51, 0
	global_load_dwordx4 v[0:3], v251, s[6:7] offset:0
	global_load_dwordx4 v[4:7], v251, s[6:7] offset:64
	global_load_dwordx4 v[8:11], v251, s[6:7] offset:128
	global_load_dwordx4 v[12:15], v251, s[6:7] offset:192
	s_lshl_b32 s57, s69, 12
	s_add_u32 s57, s57, s63
	s_add_u32 s57, s57, 0x1d9a0000
	s_add_u32 s10, s50, s57
	s_addc_u32 s11, s51, 0
	v_readlane_b32 s6, v254, 0
	v_readlane_b32 s7, v254, 1
	s_mul_i32 s57, s98, 0x744
	s_add_u32 s57, s57, 0x0
	s_nop 2
	s_add_u32 s6, s6, s57
	s_addc_u32 s7, s7, 0
	v_lshlrev_b32_e32 v196, 2, v202
	v_cmp_gt_u32_e32 vcc, 0x1d1, v202
	s_and_saveexec_b64 s[0:1], vcc
	global_load_dword v197, v196, s[6:7]
	s_or_b64 exec, exec, s[0:1]
	s_mov_b32 s70, 0
	s_add_u32 s57, s36, s70
	s_lshl_b32 s57, s57, 6
	s_addk_i32 s57, 0x100
	s_sub_u32 s63, s70, s30
	s_lshl_b32 s63, s63, 6
	s_cmp_lt_u32 s70, s30
	s_cselect_b32 s57, s57, s63
	s_mul_i32 s63, s57, 0x3000
	s_add_u32 s6, s2, s63
	s_addc_u32 s7, s3, 0
	s_lshl_b32 s63, s57, 1
	s_add_u32 s8, s4, s63
	s_addc_u32 s9, s5, 0
	global_load_dwordx4 v[148:151], v230, s[6:7]
	global_load_dwordx4 v[152:155], v231, s[6:7]
	global_load_dwordx4 v[156:159], v232, s[8:9]
	global_load_dwordx4 v[160:163], v233, s[8:9]
	s_mov_b32 s70, 1
	s_add_u32 s57, s36, s70
	s_lshl_b32 s57, s57, 6
	s_addk_i32 s57, 0x100
	s_sub_u32 s63, s70, s30
	s_lshl_b32 s63, s63, 6
	s_cmp_lt_u32 s70, s30
	s_cselect_b32 s57, s57, s63
	s_mul_i32 s63, s57, 0x3000
	s_add_u32 s6, s2, s63
	s_addc_u32 s7, s3, 0
	s_lshl_b32 s63, s57, 1
	s_add_u32 s8, s4, s63
	s_addc_u32 s9, s5, 0
	global_load_dwordx4 v[164:167], v230, s[6:7]
	global_load_dwordx4 v[168:171], v231, s[6:7]
	global_load_dwordx4 v[172:175], v232, s[8:9]
	global_load_dwordx4 v[176:179], v233, s[8:9]
	s_mov_b32 s70, 2
	s_add_u32 s57, s36, s70
	s_lshl_b32 s57, s57, 6
	s_addk_i32 s57, 0x100
	s_sub_u32 s63, s70, s30
	s_lshl_b32 s63, s63, 6
	s_cmp_lt_u32 s70, s30
	s_cselect_b32 s57, s57, s63
	s_mul_i32 s63, s57, 0x3000
	s_add_u32 s6, s2, s63
	s_addc_u32 s7, s3, 0
	s_lshl_b32 s63, s57, 1
	s_add_u32 s8, s4, s63
	s_addc_u32 s9, s5, 0
	global_load_dwordx4 v[180:183], v230, s[6:7]
	global_load_dwordx4 v[184:187], v231, s[6:7]
	global_load_dwordx4 v[188:191], v232, s[8:9]
	global_load_dwordx4 v[192:195], v233, s[8:9]
	s_mov_b32 s70, 3
	s_add_u32 s57, s36, s70
	s_lshl_b32 s57, s57, 6
	s_addk_i32 s57, 0x100
	s_sub_u32 s63, s70, s30
	s_lshl_b32 s63, s63, 6
	s_cmp_lt_u32 s70, s30
	s_cselect_b32 s57, s57, s63
	s_mul_i32 s63, s57, 0x3000
	s_add_u32 s6, s2, s63
	s_addc_u32 s7, s3, 0
	s_lshl_b32 s63, s57, 1
	s_add_u32 s8, s4, s63
	s_addc_u32 s9, s5, 0
	global_load_dwordx4 v[204:207], v230, s[6:7]
	global_load_dwordx4 v[208:211], v231, s[6:7]
	global_load_dwordx4 v[212:215], v232, s[8:9]
	global_load_dwordx4 v[216:219], v233, s[8:9]
	v_mov_b32_e32 v16, 0
	v_mov_b32_e32 v17, 0
	v_mov_b32_e32 v18, 0
	v_mov_b32_e32 v19, 0
	v_mov_b32_e32 v20, 0
	v_mov_b32_e32 v21, 0
	v_mov_b32_e32 v22, 0
	v_mov_b32_e32 v23, 0
	v_mov_b32_e32 v24, 0
	v_mov_b32_e32 v25, 0
	v_mov_b32_e32 v26, 0
	v_mov_b32_e32 v27, 0
	v_mov_b32_e32 v28, 0
	v_mov_b32_e32 v29, 0
	v_mov_b32_e32 v30, 0
	v_mov_b32_e32 v31, 0
	v_mov_b32_e32 v32, 0
	v_mov_b32_e32 v33, 0
	v_mov_b32_e32 v34, 0
	v_mov_b32_e32 v35, 0
	v_mov_b32_e32 v36, 0
	v_mov_b32_e32 v37, 0
	v_mov_b32_e32 v38, 0
	v_mov_b32_e32 v39, 0
	v_mov_b32_e32 v40, 0
	v_mov_b32_e32 v41, 0
	v_mov_b32_e32 v42, 0
	v_mov_b32_e32 v43, 0
	v_mov_b32_e32 v44, 0
	v_mov_b32_e32 v45, 0
	v_mov_b32_e32 v46, 0
	v_mov_b32_e32 v47, 0
	v_mov_b32_e32 v242, 0xf149f2ca
	v_mov_b32_e32 v243, 0
	s_waitcnt vmcnt(12)
	v_cmp_gt_u32_e32 vcc, 0x1d1, v202
	s_and_saveexec_b64 s[0:1], vcc
	v_add_u32_e32 v196, 0x1a400, v196
	ds_write_b32 v196, v197
	s_or_b64 exec, exec, s[0:1]
	ds_write_b128 v234, v[148:151]
	ds_write_b128 v235, v[152:155]
	ds_write_b128 v236, v[156:159]
	ds_write_b128 v237, v[160:163]
	s_waitcnt lgkmcnt(0)
	s_mov_b32 s70, 4
	s_add_u32 s57, s36, s70
	s_lshl_b32 s57, s57, 6
	s_addk_i32 s57, 0x100
	s_sub_u32 s63, s70, s30
	s_lshl_b32 s63, s63, 6
	s_cmp_lt_u32 s70, s30
	s_cselect_b32 s57, s57, s63
	s_mul_i32 s63, s57, 0x3000
	s_add_u32 s6, s2, s63
	s_addc_u32 s7, s3, 0
	s_lshl_b32 s63, s57, 1
	s_add_u32 s8, s4, s63
	s_addc_u32 s9, s5, 0
	global_load_dwordx4 v[148:151], v230, s[6:7]
	global_load_dwordx4 v[152:155], v231, s[6:7]
	global_load_dwordx4 v[156:159], v232, s[8:9]
	global_load_dwordx4 v[160:163], v233, s[8:9]
	s_barrier
	s_mov_b32 s27, 0
; #define LAS __attribute__((address_space(3)))
; #define MFMA16(a, b, c) __builtin_amdgcn_mfma_f32_16x16x32_bf16((a), (b), (c), 0, 0, 0)
; #define NA_LOAD(t, ks_, vs_) do { const int tb_ = NA_TB(t); \
;         _Pragma("unroll") for (int i = 0; i < 2; ++i) { const int cid = tid + i * 512; \
;             ks_[i] = *(const u32x4*)(kg + (size_t)(tb_ + (cid >> 4)) * INP + (cid & 15) * 8); \
;             vs_[i] = *(const u32x4*)(vg + (size_t)(cid >> 3) * RB + tb_ + (cid & 7) * 8); } } while (0)
; #define NA_STORE(buf, ks_, vs_) do { \
;         _Pragma("unroll") for (int i = 0; i < 2; ++i) { const int cid = tid + i * 512; \
;             *(LAS u32x4*)(lds + (buf) * KTILE + (cid >> 4) * KROW + (cid & 15) * 16) = ks_[i]; \
;             *(LAS u32x4*)(lds + 3 * KTILE + (buf) * VTILE + (cid >> 3) * VROW + (cid & 7) * 16) = vs_[i]; } } while (0)
; DI void na_block_item(const Params& p, int l, int b, int h, int rp, LAS unsigned char* lds) {
;     ...
;     for (int t = 0; t < ntl; ++t) {
;         const int cur = t % 3;
;         const bool local = t < nloc; const int kr = r0a + t;
;         const int nch = local ? ((kr >= r0w && kr < r0w + 8) ? 1 : 0) : 2;
;         for (int ci = 0; ci < nch; ++ci) {
;             const int toff = local ? band : ci * 32;
;             const LAS unsigned char* kb_ = lds + cur * KTILE + (toff + r16) * KROW + q4 * 16;
;             const LAS unsigned char* vb_ = lds + 3 * KTILE + cur * VTILE + r16 * VROW + (toff + q4 * 4) * 2;
;             float bias8[8];
;             if (local) {
;                 const LAS float* rp_ = s_rpb + (kr - gr + 7) * 31;
; #pragma unroll
;                 for (int e = 0; e < 8; ++e) { const int kcol = band + (e >> 2) * 16 + q4 * 4 + (e & 3); bias8[e] = rp_[min(max(kcol - gc + 15, 0), 30)]; }
;             }
;             f32x4 s[2];
; #pragma unroll
;             for (int hf = 0; hf < 2; ++hf) {
;                 s[hf] = (f32x4){0.f, 0.f, 0.f, 0.f};
; #pragma unroll
;                 for (int ks = 0; ks < 4; ++ks) s[hf] = MFMA16(*(const LAS bf16x8*)(kb_ + hf * 16 * KROW + ks * 64), qf[ks], s[hf]);
;             }
;     ...
;         const int nb_ = (t + 1) % 3;
;         if (t & 1) { if (t + 1 < ntl) NA_STORE(nb_, kstA, vstA); if (t + 3 < ntl) NA_LOAD(t + 3, kstA, vstA); }
;         else       { if (t + 1 < ntl) NA_STORE(nb_, kstB, vstB); if (t + 3 < ntl) NA_LOAD(t + 3, kstB, vstB); }
na0_top:
	s_add_u32 s70, s27, 1
	s_cmp_ge_u32 s70, s31
	s_cbranch_scc1 na0_nostage
	s_mul_hi_u32 s57, s70, 0x55555556
	s_mul_i32 s57, s57, 3
	s_sub_u32 s57, s70, s57
	s_mul_i32 s63, s57, 0x4400
	s_mul_i32 s57, s57, 0x4800
	v_add_u32_e32 v247, s63, v234
	v_add_u32_e32 v248, s63, v235
	v_add_u32_e32 v249, s57, v236
	v_add_u32_e32 v250, s57, v237
	s_sub_u32 s57, s31, s27
	s_sub_u32 s57, s57, 2
	s_cmp_ge_u32 s57, 3
	s_cbranch_scc1 na0_w12
	s_cmp_eq_u32 s57, 2
	s_cbranch_scc1 na0_w8
	s_cmp_eq_u32 s57, 1
	s_cbranch_scc1 na0_w4
	s_waitcnt vmcnt(0)
	s_branch na0_wd
na0_w4:
	s_waitcnt vmcnt(4)
	s_branch na0_wd
na0_w8:
	s_waitcnt vmcnt(8)
	s_branch na0_wd
na0_w12:
	s_waitcnt vmcnt(12)
na0_wd:
	s_add_u32 s71, s27, 5
	s_add_u32 s57, s36, s71
	s_lshl_b32 s57, s57, 6
	s_addk_i32 s57, 0x100
	s_sub_u32 s63, s71, s30
	s_lshl_b32 s63, s63, 6
	s_cmp_lt_u32 s71, s30
	s_cselect_b32 s57, s57, s63
	s_mul_i32 s63, s57, 0x3000
	s_add_u32 s6, s2, s63
	s_addc_u32 s7, s3, 0
	s_lshl_b32 s63, s57, 1
	s_add_u32 s8, s4, s63
	s_addc_u32 s9, s5, 0
	s_and_b32 s57, s70, 3
	s_cmp_eq_u32 s57, 1
	s_cbranch_scc1 na0_rs1
	s_cmp_eq_u32 s57, 2
	s_cbranch_scc1 na0_rs2
	s_cmp_eq_u32 s57, 3
	s_cbranch_scc1 na0_rs3
	ds_write_b128 v247, v[148:151]
	ds_write_b128 v248, v[152:155]
	ds_write_b128 v249, v[156:159]
	ds_write_b128 v250, v[160:163]
	s_waitcnt lgkmcnt(0)
	s_cmp_ge_u32 s71, s31
	s_cbranch_scc1 na0_nostage
	global_load_dwordx4 v[148:151], v230, s[6:7]
	global_load_dwordx4 v[152:155], v231, s[6:7]
	global_load_dwordx4 v[156:159], v232, s[8:9]
	global_load_dwordx4 v[160:163], v233, s[8:9]
	s_branch na0_nostage
na0_rs1:
	ds_write_b128 v247, v[164:167]
	ds_write_b128 v248, v[168:171]
	ds_write_b128 v249, v[172:175]
	ds_write_b128 v250, v[176:179]
	s_waitcnt lgkmcnt(0)
	s_cmp_ge_u32 s71, s31
	s_cbranch_scc1 na0_nostage
	global_load_dwordx4 v[164:167], v230, s[6:7]
	global_load_dwordx4 v[168:171], v231, s[6:7]
	global_load_dwordx4 v[172:175], v232, s[8:9]
	global_load_dwordx4 v[176:179], v233, s[8:9]
	s_branch na0_nostage
na0_rs2:
	ds_write_b128 v247, v[180:183]
	ds_write_b128 v248, v[184:187]
	ds_write_b128 v249, v[188:191]
	ds_write_b128 v250, v[192:195]
	s_waitcnt lgkmcnt(0)
	s_cmp_ge_u32 s71, s31
	s_cbranch_scc1 na0_nostage
	global_load_dwordx4 v[180:183], v230, s[6:7]
	global_load_dwordx4 v[184:187], v231, s[6:7]
	global_load_dwordx4 v[188:191], v232, s[8:9]
	global_load_dwordx4 v[192:195], v233, s[8:9]
	s_branch na0_nostage
na0_rs3:
	ds_write_b128 v247, v[204:207]
	ds_write_b128 v248, v[208:211]
	ds_write_b128 v249, v[212:215]
	ds_write_b128 v250, v[216:219]
	s_waitcnt lgkmcnt(0)
	s_cmp_ge_u32 s71, s31
	s_cbranch_scc1 na0_nostage
	global_load_dwordx4 v[204:207], v230, s[6:7]
	global_load_dwordx4 v[208:211], v231, s[6:7]
	global_load_dwordx4 v[212:215], v232, s[8:9]
	global_load_dwordx4 v[216:219], v233, s[8:9]
na0_nostage:
	s_mul_hi_u32 s57, s27, 0x55555556
	s_mul_i32 s57, s57, 3
	s_sub_u32 s57, s27, s57
	s_mul_i32 s75, s57, 0x4400
	s_mul_i32 s76, s57, 0x4800
	s_cmp_lt_u32 s27, s30
	s_cbranch_scc0 na0_ctx
	s_add_u32 s68, s36, s27
	s_cmp_lt_i32 s68, s54
	s_cbranch_scc1 na0_bar
	s_add_u32 s69, s54, 8
	s_cmp_ge_i32 s68, s69
	s_cbranch_scc1 na0_bar
	s_sub_i32 s69, s68, s37
	s_add_u32 s69, s69, 7
	s_mul_i32 s100, s69, 0x7c
	s_mul_i32 s57, s56, 0x110
	s_add_u32 s57, s57, s75
	s_lshl_b32 s63, s56, 1
	s_add_u32 s63, s63, s76
	v_add_u32_e32 v240, s57, v238
	v_add_u32_e32 v241, s63, v239
	v_add_u32_e32 v222, s100, v132
	v_add_u32_e32 v223, s100, v133
	v_add_u32_e32 v224, s100, v134
	v_add_u32_e32 v225, s100, v135
	v_add_u32_e32 v226, s100, v136
	v_add_u32_e32 v227, s100, v137
	v_add_u32_e32 v228, s100, v138
	v_add_u32_e32 v229, s100, v139
	ds_read_b32 v124, v222
	ds_read_b32 v125, v223
	ds_read_b32 v126, v224
	ds_read_b32 v127, v225
	ds_read_b32 v128, v226
	ds_read_b32 v129, v227
	ds_read_b32 v130, v228
	ds_read_b32 v131, v229
	ds_read_b128 v[56:59], v240 offset:0
	ds_read_b128 v[72:75], v240 offset:4352
	ds_read_b128 v[60:63], v240 offset:64
	ds_read_b128 v[76:79], v240 offset:4416
	ds_read_b128 v[64:67], v240 offset:128
	ds_read_b128 v[80:83], v240 offset:4480
	ds_read_b128 v[68:71], v240 offset:192
	ds_read_b128 v[84:87], v240 offset:4544
	s_waitcnt lgkmcnt(7)
	v_mfma_f32_16x16x32_bf16 v[48:51], v[56:59], v[0:3], 0
	ds_read_b64 v[88:89], v241 offset:0
	ds_read_b64 v[90:91], v241 offset:32
	s_waitcnt lgkmcnt(8)
	v_mfma_f32_16x16x32_bf16 v[52:55], v[72:75], v[0:3], 0
	ds_read_b64 v[92:93], v241 offset:2304
	ds_read_b64 v[94:95], v241 offset:2336
	s_waitcnt lgkmcnt(9)
	v_mfma_f32_16x16x32_bf16 v[48:51], v[60:63], v[4:7], v[48:51]
	ds_read_b64 v[96:97], v241 offset:4608
	ds_read_b64 v[98:99], v241 offset:4640
	s_waitcnt lgkmcnt(10)
	v_mfma_f32_16x16x32_bf16 v[52:55], v[76:79], v[4:7], v[52:55]
	ds_read_b64 v[100:101], v241 offset:6912
	ds_read_b64 v[102:103], v241 offset:6944
	s_waitcnt lgkmcnt(11)
	v_mfma_f32_16x16x32_bf16 v[48:51], v[64:67], v[8:11], v[48:51]
	ds_read_b64 v[104:105], v241 offset:9216
	ds_read_b64 v[106:107], v241 offset:9248
	s_waitcnt lgkmcnt(12)
	v_mfma_f32_16x16x32_bf16 v[52:55], v[80:83], v[8:11], v[52:55]
	ds_read_b64 v[108:109], v241 offset:11520
	ds_read_b64 v[110:111], v241 offset:11552
	s_waitcnt lgkmcnt(13)
	v_mfma_f32_16x16x32_bf16 v[48:51], v[68:71], v[12:15], v[48:51]
	ds_read_b64 v[112:113], v241 offset:13824
	ds_read_b64 v[114:115], v241 offset:13856
	s_waitcnt lgkmcnt(14)
; #define LAS __attribute__((address_space(3)))
; DI unsigned cvt_pk_bf16(float lo, float hi) { unsigned r; asm volatile("v_cvt_pk_bf16_f32 %0, %1, %2" : "=v"(r) : "v"(lo), "v"(hi)); return r; }
; #define MFMA16(a, b, c) __builtin_amdgcn_mfma_f32_16x16x32_bf16((a), (b), (c), 0, 0, 0)
; DI float fast_exp2(float x) { return __builtin_amdgcn_exp2f(x); }
; DI void na_block_item(const Params& p, int l, int b, int h, int rp, LAS unsigned char* lds) {
;     ...
;             if (local) {
; #pragma unroll
;                 for (int hf = 0; hf < 2; ++hf)
; #pragma unroll
;                     for (int j = 0; j < 4; ++j) {
;                         const int kcol = band + hf * 16 + q4 * 4 + j; const bool inw = kcol >= cs && kcol < cs + 16;
;                         s[hf][j] = inw ? s[hf][j] * sl2 + bias8[hf * 4 + j] * 1.4426950408889634f : -1e30f;
;                     }
;             } else { s[0] *= sl2; s[1] *= sl2; }
;             float mx = fmaxf(fmaxf(fmaxf(s[0][0], s[0][1]), fmaxf(s[0][2], s[0][3])), fmaxf(fmaxf(s[1][0], s[1][1]), fmaxf(s[1][2], s[1][3])));
;             mx = fmaxf(mx, __shfl_xor(mx, 16)); mx = fmaxf(mx, __shfl_xor(mx, 32));
;             const float mnew = fmaxf(mrun, mx), alpha = fast_exp2(mrun - mnew);
;             mrun = mnew;
;             float ps = 0.f;
; #pragma unroll
;             for (int hf = 0; hf < 2; ++hf)
; #pragma unroll
;                 for (int j = 0; j < 4; ++j) { const float pv = fast_exp2(s[hf][j] - mnew); s[hf][j] = pv; ps += pv; }
;             lsum = lsum * alpha + ps;
; #pragma unroll
;             for (int d = 0; d < 8; ++d) oacc[d] *= alpha;
;             u32x4 w4; w4.x = cvt_pk_bf16(s[0][0], s[0][1]); w4.y = cvt_pk_bf16(s[0][2], s[0][3]); w4.z = cvt_pk_bf16(s[1][0], s[1][1]); w4.w = cvt_pk_bf16(s[1][2], s[1][3]);
;             const bf16x8 pb = __builtin_bit_cast(bf16x8, w4);
;             __builtin_amdgcn_s_setprio(1);
; #pragma unroll
;             for (int d = 0; d < 8; ++d) {
;                 const u32x2 lo = *(const LAS u32x2*)(vb_ + d * 16 * VROW), hi = *(const LAS u32x2*)(vb_ + d * 16 * VROW + 32);
;                 u32x4 a4; a4.x = lo.x; a4.y = lo.y; a4.z = hi.x; a4.w = hi.y;
;                 oacc[d] = MFMA16(__builtin_bit_cast(bf16x8, a4), pb, oacc[d]);
;             }
;             __builtin_amdgcn_s_setprio(0);
;         }
	v_mfma_f32_16x16x32_bf16 v[52:55], v[84:87], v[12:15], v[52:55]
	ds_read_b64 v[116:117], v241 offset:16128
	ds_read_b64 v[118:119], v241 offset:16160
	v_mul_f32_e32 v124, s23, v124
	v_mul_f32_e32 v125, s23, v125
	v_mul_f32_e32 v126, s23, v126
	v_mul_f32_e32 v127, s23, v127
	v_mul_f32_e32 v128, s23, v128
	v_mul_f32_e32 v129, s23, v129
	v_mul_f32_e32 v130, s23, v130
	v_mul_f32_e32 v131, s23, v131
	s_nop 1
	v_fma_f32 v48, v48, s22, v124
	v_fma_f32 v49, v49, s22, v125
	v_fma_f32 v50, v50, s22, v126
	v_fma_f32 v51, v51, s22, v127
	v_fma_f32 v52, v52, s22, v128
	v_fma_f32 v53, v53, s22, v129
	v_fma_f32 v54, v54, s22, v130
	v_fma_f32 v55, v55, s22, v131
	v_min_f32_e32 v48, v48, v140
	v_min_f32_e32 v49, v49, v141
	v_min_f32_e32 v50, v50, v142
	v_min_f32_e32 v51, v51, v143
	v_min_f32_e32 v52, v52, v144
	v_min_f32_e32 v53, v53, v145
	v_min_f32_e32 v54, v54, v146
	v_min_f32_e32 v55, v55, v147
	v_max3_f32 v196, v48, v49, v50
	v_max3_f32 v197, v51, v52, v53
	v_max3_f32 v196, v196, v54, v55
	v_max_f32_e32 v196, v196, v197
	v_mov_b32_e32 v197, v196
	s_nop 1
	v_permlane16_swap_b32_e32 v196, v197
	v_max_f32_e32 v196, v196, v197
	v_mov_b32_e32 v197, v196
	s_nop 1
	v_permlane32_swap_b32_e32 v196, v197
	v_max_f32_e32 v196, v196, v197
	v_max_f32_e32 v197, v242, v196
	v_sub_f32_e32 v196, v242, v197
	v_exp_f32_e32 v244, v196
	v_mov_b32_e32 v242, v197
	v_sub_f32_e32 v48, v48, v197
	v_sub_f32_e32 v49, v49, v197
	v_sub_f32_e32 v50, v50, v197
	v_sub_f32_e32 v51, v51, v197
	v_sub_f32_e32 v52, v52, v197
	v_sub_f32_e32 v53, v53, v197
	v_sub_f32_e32 v54, v54, v197
	v_sub_f32_e32 v55, v55, v197
	v_exp_f32_e32 v48, v48
	v_exp_f32_e32 v49, v49
	v_exp_f32_e32 v50, v50
	v_exp_f32_e32 v51, v51
	v_exp_f32_e32 v52, v52
	v_exp_f32_e32 v53, v53
	v_exp_f32_e32 v54, v54
	v_exp_f32_e32 v55, v55
	v_add_f32_e32 v196, v48, v49
	v_add_f32_e32 v196, v196, v50
	v_add_f32_e32 v196, v196, v51
	v_add_f32_e32 v196, v196, v52
	v_add_f32_e32 v196, v196, v53
	v_add_f32_e32 v196, v196, v54
	v_add_f32_e32 v196, v196, v55
	v_fma_f32 v243, v243, v244, v196
	v_cvt_pk_bf16_f32 v120, v48, v49
	v_cvt_pk_bf16_f32 v121, v50, v51
	v_cvt_pk_bf16_f32 v122, v52, v53
	v_cvt_pk_bf16_f32 v123, v54, v55
	v_pk_mul_f32 v[16:17], v[16:17], v[244:245] op_sel_hi:[1,0]
	v_pk_mul_f32 v[18:19], v[18:19], v[244:245] op_sel_hi:[1,0]
	v_pk_mul_f32 v[20:21], v[20:21], v[244:245] op_sel_hi:[1,0]
	v_pk_mul_f32 v[22:23], v[22:23], v[244:245] op_sel_hi:[1,0]
	v_pk_mul_f32 v[24:25], v[24:25], v[244:245] op_sel_hi:[1,0]
	v_pk_mul_f32 v[26:27], v[26:27], v[244:245] op_sel_hi:[1,0]
	v_pk_mul_f32 v[28:29], v[28:29], v[244:245] op_sel_hi:[1,0]
	v_pk_mul_f32 v[30:31], v[30:31], v[244:245] op_sel_hi:[1,0]
	v_pk_mul_f32 v[32:33], v[32:33], v[244:245] op_sel_hi:[1,0]
	v_pk_mul_f32 v[34:35], v[34:35], v[244:245] op_sel_hi:[1,0]
	v_pk_mul_f32 v[36:37], v[36:37], v[244:245] op_sel_hi:[1,0]
	v_pk_mul_f32 v[38:39], v[38:39], v[244:245] op_sel_hi:[1,0]
	v_pk_mul_f32 v[40:41], v[40:41], v[244:245] op_sel_hi:[1,0]
	v_pk_mul_f32 v[42:43], v[42:43], v[244:245] op_sel_hi:[1,0]
	v_pk_mul_f32 v[44:45], v[44:45], v[244:245] op_sel_hi:[1,0]
	v_pk_mul_f32 v[46:47], v[46:47], v[244:245] op_sel_hi:[1,0]
	s_waitcnt lgkmcnt(14)
	v_mfma_f32_16x16x32_bf16 v[16:19], v[88:91], v[120:123], v[16:19]
	s_waitcnt lgkmcnt(12)
	v_mfma_f32_16x16x32_bf16 v[20:23], v[92:95], v[120:123], v[20:23]
	s_waitcnt lgkmcnt(10)
	v_mfma_f32_16x16x32_bf16 v[24:27], v[96:99], v[120:123], v[24:27]
	s_waitcnt lgkmcnt(8)
	v_mfma_f32_16x16x32_bf16 v[28:31], v[100:103], v[120:123], v[28:31]
	s_waitcnt lgkmcnt(6)
	v_mfma_f32_16x16x32_bf16 v[32:35], v[104:107], v[120:123], v[32:35]
	s_waitcnt lgkmcnt(4)
	v_mfma_f32_16x16x32_bf16 v[36:39], v[108:111], v[120:123], v[36:39]
	s_waitcnt lgkmcnt(2)
	v_mfma_f32_16x16x32_bf16 v[40:43], v[112:115], v[120:123], v[40:43]
	s_waitcnt lgkmcnt(0)
	v_mfma_f32_16x16x32_bf16 v[44:47], v[116:119], v[120:123], v[44:47]
	s_branch na0_bar
na0_ctx:
	s_add_u32 s57, s75, 0x0
	s_add_u32 s63, s76, 0x0
	v_add_u32_e32 v240, s57, v238
	v_add_u32_e32 v241, s63, v239
	ds_read_b128 v[56:59], v240 offset:0
	ds_read_b128 v[72:75], v240 offset:4352
	ds_read_b128 v[60:63], v240 offset:64
	ds_read_b128 v[76:79], v240 offset:4416
	ds_read_b128 v[64:67], v240 offset:128
	ds_read_b128 v[80:83], v240 offset:4480
	ds_read_b128 v[68:71], v240 offset:192
	ds_read_b128 v[84:87], v240 offset:4544
	s_waitcnt lgkmcnt(7)
	v_mfma_f32_16x16x32_bf16 v[48:51], v[56:59], v[0:3], 0
	ds_read_b64 v[88:89], v241 offset:0
	ds_read_b64 v[90:91], v241 offset:32
	s_waitcnt lgkmcnt(8)
	v_mfma_f32_16x16x32_bf16 v[52:55], v[72:75], v[0:3], 0
	ds_read_b64 v[92:93], v241 offset:2304
	ds_read_b64 v[94:95], v241 offset:2336
	s_waitcnt lgkmcnt(9)
	v_mfma_f32_16x16x32_bf16 v[48:51], v[60:63], v[4:7], v[48:51]
	ds_read_b64 v[96:97], v241 offset:4608
	ds_read_b64 v[98:99], v241 offset:4640
	s_waitcnt lgkmcnt(10)
	v_mfma_f32_16x16x32_bf16 v[52:55], v[76:79], v[4:7], v[52:55]
	ds_read_b64 v[100:101], v241 offset:6912
	ds_read_b64 v[102:103], v241 offset:6944
	s_waitcnt lgkmcnt(11)
	v_mfma_f32_16x16x32_bf16 v[48:51], v[64:67], v[8:11], v[48:51]
	ds_read_b64 v[104:105], v241 offset:9216
	ds_read_b64 v[106:107], v241 offset:9248
	s_waitcnt lgkmcnt(12)
	v_mfma_f32_16x16x32_bf16 v[52:55], v[80:83], v[8:11], v[52:55]
	ds_read_b64 v[108:109], v241 offset:11520
	ds_read_b64 v[110:111], v241 offset:11552
	s_waitcnt lgkmcnt(13)
	v_mfma_f32_16x16x32_bf16 v[48:51], v[68:71], v[12:15], v[48:51]
	ds_read_b64 v[112:113], v241 offset:13824
	ds_read_b64 v[114:115], v241 offset:13856
	s_waitcnt lgkmcnt(14)
; #define LAS __attribute__((address_space(3)))
; DI float fast_exp2(float x) { return __builtin_amdgcn_exp2f(x); }
; DI void na_block_item(const Params& p, int l, int b, int h, int rp, LAS unsigned char* lds) {
;     ...
;             f32x4 s[2];
; #pragma unroll
;             for (int hf = 0; hf < 2; ++hf) {
;                 s[hf] = (f32x4){0.f, 0.f, 0.f, 0.f};
; #pragma unroll
;                 for (int ks = 0; ks < 4; ++ks) s[hf] = MFMA16(*(const LAS bf16x8*)(kb_ + hf * 16 * KROW + ks * 64), qf[ks], s[hf]);
;             }
;             if (local) {
; #pragma unroll
;                 for (int hf = 0; hf < 2; ++hf)
; #pragma unroll
;                     for (int j = 0; j < 4; ++j) {
;                         const int kcol = band + hf * 16 + q4 * 4 + j; const bool inw = kcol >= cs && kcol < cs + 16;
;                         s[hf][j] = inw ? s[hf][j] * sl2 + bias8[hf * 4 + j] * 1.4426950408889634f : -1e30f;
;                     }
;             } else { s[0] *= sl2; s[1] *= sl2; }
;             float mx = fmaxf(fmaxf(fmaxf(s[0][0], s[0][1]), fmaxf(s[0][2], s[0][3])), fmaxf(fmaxf(s[1][0], s[1][1]), fmaxf(s[1][2], s[1][3])));
;             mx = fmaxf(mx, __shfl_xor(mx, 16)); mx = fmaxf(mx, __shfl_xor(mx, 32));
;             const float mnew = fmaxf(mrun, mx), alpha = fast_exp2(mrun - mnew);
;             mrun = mnew;
;             float ps = 0.f;
; #pragma unroll
;             for (int hf = 0; hf < 2; ++hf)
; #pragma unroll
;                 for (int j = 0; j < 4; ++j) { const float pv = fast_exp2(s[hf][j] - mnew); s[hf][j] = pv; ps += pv; }
;             lsum = lsum * alpha + ps;
; #pragma unroll
;             for (int d = 0; d < 8; ++d) oacc[d] *= alpha;
;             u32x4 w4; w4.x = cvt_pk_bf16(s[0][0], s[0][1]); w4.y = cvt_pk_bf16(s[0][2], s[0][3]); w4.z = cvt_pk_bf16(s[1][0], s[1][1]); w4.w = cvt_pk_bf16(s[1][2], s[1][3]);
;             const bf16x8 pb = __builtin_bit_cast(bf16x8, w4);
;             __builtin_amdgcn_s_setprio(1);
; #pragma unroll
;             for (int d = 0; d < 8; ++d) {
;                 const u32x2 lo = *(const LAS u32x2*)(vb_ + d * 16 * VROW), hi = *(const LAS u32x2*)(vb_ + d * 16 * VROW + 32);
;                 u32x4 a4; a4.x = lo.x; a4.y = lo.y; a4.z = hi.x; a4.w = hi.y;
;                 oacc[d] = MFMA16(__builtin_bit_cast(bf16x8, a4), pb, oacc[d]);
;             }
;             __builtin_amdgcn_s_setprio(0);
;         }
	v_mfma_f32_16x16x32_bf16 v[52:55], v[84:87], v[12:15], v[52:55]
	ds_read_b64 v[116:117], v241 offset:16128
	ds_read_b64 v[118:119], v241 offset:16160
	s_nop 7
	s_nop 1
	v_mul_f32_e32 v48, s22, v48
	v_mul_f32_e32 v49, s22, v49
	v_mul_f32_e32 v50, s22, v50
	v_mul_f32_e32 v51, s22, v51
	v_mul_f32_e32 v52, s22, v52
	v_mul_f32_e32 v53, s22, v53
	v_mul_f32_e32 v54, s22, v54
	v_mul_f32_e32 v55, s22, v55
	v_max3_f32 v196, v48, v49, v50
	v_max3_f32 v197, v51, v52, v53
	v_max3_f32 v196, v196, v54, v55
	v_max_f32_e32 v196, v196, v197
	v_mov_b32_e32 v197, v196
	s_nop 1
	v_permlane16_swap_b32_e32 v196, v197
	v_max_f32_e32 v196, v196, v197
	v_mov_b32_e32 v197, v196
	s_nop 1
	v_permlane32_swap_b32_e32 v196, v197
	v_max_f32_e32 v196, v196, v197
	v_max_f32_e32 v197, v242, v196
	v_sub_f32_e32 v196, v242, v197
	v_exp_f32_e32 v244, v196
	v_mov_b32_e32 v242, v197
	v_sub_f32_e32 v48, v48, v197
	v_sub_f32_e32 v49, v49, v197
	v_sub_f32_e32 v50, v50, v197
	v_sub_f32_e32 v51, v51, v197
	v_sub_f32_e32 v52, v52, v197
	v_sub_f32_e32 v53, v53, v197
	v_sub_f32_e32 v54, v54, v197
	v_sub_f32_e32 v55, v55, v197
	v_exp_f32_e32 v48, v48
	v_exp_f32_e32 v49, v49
	v_exp_f32_e32 v50, v50
	v_exp_f32_e32 v51, v51
	v_exp_f32_e32 v52, v52
	v_exp_f32_e32 v53, v53
	v_exp_f32_e32 v54, v54
	v_exp_f32_e32 v55, v55
	v_add_f32_e32 v196, v48, v49
	v_add_f32_e32 v196, v196, v50
	v_add_f32_e32 v196, v196, v51
	v_add_f32_e32 v196, v196, v52
	v_add_f32_e32 v196, v196, v53
	v_add_f32_e32 v196, v196, v54
	v_add_f32_e32 v196, v196, v55
	v_fma_f32 v243, v243, v244, v196
	v_cvt_pk_bf16_f32 v120, v48, v49
	v_cvt_pk_bf16_f32 v121, v50, v51
	v_cvt_pk_bf16_f32 v122, v52, v53
	v_cvt_pk_bf16_f32 v123, v54, v55
	v_pk_mul_f32 v[16:17], v[16:17], v[244:245] op_sel_hi:[1,0]
	v_pk_mul_f32 v[18:19], v[18:19], v[244:245] op_sel_hi:[1,0]
	v_pk_mul_f32 v[20:21], v[20:21], v[244:245] op_sel_hi:[1,0]
	v_pk_mul_f32 v[22:23], v[22:23], v[244:245] op_sel_hi:[1,0]
	v_pk_mul_f32 v[24:25], v[24:25], v[244:245] op_sel_hi:[1,0]
	v_pk_mul_f32 v[26:27], v[26:27], v[244:245] op_sel_hi:[1,0]
	v_pk_mul_f32 v[28:29], v[28:29], v[244:245] op_sel_hi:[1,0]
	v_pk_mul_f32 v[30:31], v[30:31], v[244:245] op_sel_hi:[1,0]
	v_pk_mul_f32 v[32:33], v[32:33], v[244:245] op_sel_hi:[1,0]
	v_pk_mul_f32 v[34:35], v[34:35], v[244:245] op_sel_hi:[1,0]
	v_pk_mul_f32 v[36:37], v[36:37], v[244:245] op_sel_hi:[1,0]
	v_pk_mul_f32 v[38:39], v[38:39], v[244:245] op_sel_hi:[1,0]
	v_pk_mul_f32 v[40:41], v[40:41], v[244:245] op_sel_hi:[1,0]
	v_pk_mul_f32 v[42:43], v[42:43], v[244:245] op_sel_hi:[1,0]
	v_pk_mul_f32 v[44:45], v[44:45], v[244:245] op_sel_hi:[1,0]
	v_pk_mul_f32 v[46:47], v[46:47], v[244:245] op_sel_hi:[1,0]
	s_waitcnt lgkmcnt(14)
	v_mfma_f32_16x16x32_bf16 v[16:19], v[88:91], v[120:123], v[16:19]
	s_waitcnt lgkmcnt(12)
	v_mfma_f32_16x16x32_bf16 v[20:23], v[92:95], v[120:123], v[20:23]
	s_waitcnt lgkmcnt(10)
	v_mfma_f32_16x16x32_bf16 v[24:27], v[96:99], v[120:123], v[24:27]
	s_waitcnt lgkmcnt(8)
	v_mfma_f32_16x16x32_bf16 v[28:31], v[100:103], v[120:123], v[28:31]
	s_waitcnt lgkmcnt(6)
	v_mfma_f32_16x16x32_bf16 v[32:35], v[104:107], v[120:123], v[32:35]
	s_waitcnt lgkmcnt(4)
	v_mfma_f32_16x16x32_bf16 v[36:39], v[108:111], v[120:123], v[36:39]
	s_waitcnt lgkmcnt(2)
	v_mfma_f32_16x16x32_bf16 v[40:43], v[112:115], v[120:123], v[40:43]
	s_waitcnt lgkmcnt(0)
	v_mfma_f32_16x16x32_bf16 v[44:47], v[116:119], v[120:123], v[44:47]
	s_add_u32 s57, s75, 0x2200
	s_add_u32 s63, s76, 0x40
	v_add_u32_e32 v240, s57, v238
	v_add_u32_e32 v241, s63, v239
	ds_read_b128 v[56:59], v240 offset:0
	ds_read_b128 v[72:75], v240 offset:4352
	ds_read_b128 v[60:63], v240 offset:64
	ds_read_b128 v[76:79], v240 offset:4416
	ds_read_b128 v[64:67], v240 offset:128
	ds_read_b128 v[80:83], v240 offset:4480
	ds_read_b128 v[68:71], v240 offset:192
	ds_read_b128 v[84:87], v240 offset:4544
	s_waitcnt lgkmcnt(7)
	v_mfma_f32_16x16x32_bf16 v[48:51], v[56:59], v[0:3], 0
	ds_read_b64 v[88:89], v241 offset:0
	ds_read_b64 v[90:91], v241 offset:32
	s_waitcnt lgkmcnt(8)
	v_mfma_f32_16x16x32_bf16 v[52:55], v[72:75], v[0:3], 0
	ds_read_b64 v[92:93], v241 offset:2304
	ds_read_b64 v[94:95], v241 offset:2336
	s_waitcnt lgkmcnt(9)
	v_mfma_f32_16x16x32_bf16 v[48:51], v[60:63], v[4:7], v[48:51]
	ds_read_b64 v[96:97], v241 offset:4608
	ds_read_b64 v[98:99], v241 offset:4640
	s_waitcnt lgkmcnt(10)
	v_mfma_f32_16x16x32_bf16 v[52:55], v[76:79], v[4:7], v[52:55]
	ds_read_b64 v[100:101], v241 offset:6912
	ds_read_b64 v[102:103], v241 offset:6944
	s_waitcnt lgkmcnt(11)
	v_mfma_f32_16x16x32_bf16 v[48:51], v[64:67], v[8:11], v[48:51]
	ds_read_b64 v[104:105], v241 offset:9216
	ds_read_b64 v[106:107], v241 offset:9248
	s_waitcnt lgkmcnt(12)
	v_mfma_f32_16x16x32_bf16 v[52:55], v[80:83], v[8:11], v[52:55]
	ds_read_b64 v[108:109], v241 offset:11520
	ds_read_b64 v[110:111], v241 offset:11552
	s_waitcnt lgkmcnt(13)
	v_mfma_f32_16x16x32_bf16 v[48:51], v[68:71], v[12:15], v[48:51]
	ds_read_b64 v[112:113], v241 offset:13824
	ds_read_b64 v[114:115], v241 offset:13856
	s_waitcnt lgkmcnt(14)
; #define LAS __attribute__((address_space(3)))
; #define MFMA16(a, b, c) __builtin_amdgcn_mfma_f32_16x16x32_bf16((a), (b), (c), 0, 0, 0)
; DI int next_item(unsigned* ctr, volatile LAS int* slot) {
;     __syncthreads();
;     if (threadIdx.x == 0) *slot = (int)xb_add(ctr, 1u);
;     __syncthreads();
;     return *slot;
; DI void na_block_item(const Params& p, int l, int b, int h, int rp, LAS unsigned char* lds) {
;     ...
;             float mx = fmaxf(fmaxf(fmaxf(s[0][0], s[0][1]), fmaxf(s[0][2], s[0][3])), fmaxf(fmaxf(s[1][0], s[1][1]), fmaxf(s[1][2], s[1][3])));
;             mx = fmaxf(mx, __shfl_xor(mx, 16)); mx = fmaxf(mx, __shfl_xor(mx, 32));
;             const float mnew = fmaxf(mrun, mx), alpha = fast_exp2(mrun - mnew);
;             mrun = mnew;
;             float ps = 0.f;
; #pragma unroll
;             for (int hf = 0; hf < 2; ++hf)
; #pragma unroll
;                 for (int j = 0; j < 4; ++j) { const float pv = fast_exp2(s[hf][j] - mnew); s[hf][j] = pv; ps += pv; }
;             lsum = lsum * alpha + ps;
; #pragma unroll
;             for (int d = 0; d < 8; ++d) oacc[d] *= alpha;
;             u32x4 w4; w4.x = cvt_pk_bf16(s[0][0], s[0][1]); w4.y = cvt_pk_bf16(s[0][2], s[0][3]); w4.z = cvt_pk_bf16(s[1][0], s[1][1]); w4.w = cvt_pk_bf16(s[1][2], s[1][3]);
;             const bf16x8 pb = __builtin_bit_cast(bf16x8, w4);
;             __builtin_amdgcn_s_setprio(1);
; #pragma unroll
;             for (int d = 0; d < 8; ++d) {
;                 const u32x2 lo = *(const LAS u32x2*)(vb_ + d * 16 * VROW), hi = *(const LAS u32x2*)(vb_ + d * 16 * VROW + 32);
;                 u32x4 a4; a4.x = lo.x; a4.y = lo.y; a4.z = hi.x; a4.w = hi.y;
;                 oacc[d] = MFMA16(__builtin_bit_cast(bf16x8, a4), pb, oacc[d]);
;             }
;             __builtin_amdgcn_s_setprio(0);
;         }
;         const int nb_ = (t + 1) % 3;
;         if (t & 1) { if (t + 1 < ntl) NA_STORE(nb_, kstA, vstA); if (t + 3 < ntl) NA_LOAD(t + 3, kstA, vstA); }
;         else       { if (t + 1 < ntl) NA_STORE(nb_, kstB, vstB); if (t + 3 < ntl) NA_LOAD(t + 3, kstB, vstB); }
;         __syncthreads();
;     }
;     ...
;     float lt = lsum; lt += __shfl_xor(lt, 16); lt += __shfl_xor(lt, 32);
;     const float inv = 1.f / lt;
;     bf16_t* op = (bf16_t*)(ws + WS_YMIX) + rowq * DM + h * 128 + q4 * 4;
; #pragma unroll
;     for (int d = 0; d < 8; ++d) st_bf16x4(op + d * 16, oacc[d] * inv);
	v_mfma_f32_16x16x32_bf16 v[52:55], v[84:87], v[12:15], v[52:55]
	ds_read_b64 v[116:117], v241 offset:16128
	ds_read_b64 v[118:119], v241 offset:16160
	s_nop 7
	s_nop 1
	v_mul_f32_e32 v48, s22, v48
	v_mul_f32_e32 v49, s22, v49
	v_mul_f32_e32 v50, s22, v50
	v_mul_f32_e32 v51, s22, v51
	v_mul_f32_e32 v52, s22, v52
	v_mul_f32_e32 v53, s22, v53
	v_mul_f32_e32 v54, s22, v54
	v_mul_f32_e32 v55, s22, v55
	v_max3_f32 v196, v48, v49, v50
	v_max3_f32 v197, v51, v52, v53
	v_max3_f32 v196, v196, v54, v55
	v_max_f32_e32 v196, v196, v197
	v_mov_b32_e32 v197, v196
	s_nop 1
	v_permlane16_swap_b32_e32 v196, v197
	v_max_f32_e32 v196, v196, v197
	v_mov_b32_e32 v197, v196
	s_nop 1
	v_permlane32_swap_b32_e32 v196, v197
	v_max_f32_e32 v196, v196, v197
	v_max_f32_e32 v197, v242, v196
	v_sub_f32_e32 v196, v242, v197
	v_exp_f32_e32 v244, v196
	v_mov_b32_e32 v242, v197
	v_sub_f32_e32 v48, v48, v197
	v_sub_f32_e32 v49, v49, v197
	v_sub_f32_e32 v50, v50, v197
	v_sub_f32_e32 v51, v51, v197
	v_sub_f32_e32 v52, v52, v197
	v_sub_f32_e32 v53, v53, v197
	v_sub_f32_e32 v54, v54, v197
	v_sub_f32_e32 v55, v55, v197
	v_exp_f32_e32 v48, v48
	v_exp_f32_e32 v49, v49
	v_exp_f32_e32 v50, v50
	v_exp_f32_e32 v51, v51
	v_exp_f32_e32 v52, v52
	v_exp_f32_e32 v53, v53
	v_exp_f32_e32 v54, v54
	v_exp_f32_e32 v55, v55
	v_add_f32_e32 v196, v48, v49
	v_add_f32_e32 v196, v196, v50
	v_add_f32_e32 v196, v196, v51
	v_add_f32_e32 v196, v196, v52
	v_add_f32_e32 v196, v196, v53
	v_add_f32_e32 v196, v196, v54
	v_add_f32_e32 v196, v196, v55
	v_fma_f32 v243, v243, v244, v196
	v_cvt_pk_bf16_f32 v120, v48, v49
	v_cvt_pk_bf16_f32 v121, v50, v51
	v_cvt_pk_bf16_f32 v122, v52, v53
	v_cvt_pk_bf16_f32 v123, v54, v55
	v_pk_mul_f32 v[16:17], v[16:17], v[244:245] op_sel_hi:[1,0]
	v_pk_mul_f32 v[18:19], v[18:19], v[244:245] op_sel_hi:[1,0]
	v_pk_mul_f32 v[20:21], v[20:21], v[244:245] op_sel_hi:[1,0]
	v_pk_mul_f32 v[22:23], v[22:23], v[244:245] op_sel_hi:[1,0]
	v_pk_mul_f32 v[24:25], v[24:25], v[244:245] op_sel_hi:[1,0]
	v_pk_mul_f32 v[26:27], v[26:27], v[244:245] op_sel_hi:[1,0]
	v_pk_mul_f32 v[28:29], v[28:29], v[244:245] op_sel_hi:[1,0]
	v_pk_mul_f32 v[30:31], v[30:31], v[244:245] op_sel_hi:[1,0]
	v_pk_mul_f32 v[32:33], v[32:33], v[244:245] op_sel_hi:[1,0]
	v_pk_mul_f32 v[34:35], v[34:35], v[244:245] op_sel_hi:[1,0]
	v_pk_mul_f32 v[36:37], v[36:37], v[244:245] op_sel_hi:[1,0]
	v_pk_mul_f32 v[38:39], v[38:39], v[244:245] op_sel_hi:[1,0]
	v_pk_mul_f32 v[40:41], v[40:41], v[244:245] op_sel_hi:[1,0]
	v_pk_mul_f32 v[42:43], v[42:43], v[244:245] op_sel_hi:[1,0]
	v_pk_mul_f32 v[44:45], v[44:45], v[244:245] op_sel_hi:[1,0]
	v_pk_mul_f32 v[46:47], v[46:47], v[244:245] op_sel_hi:[1,0]
	s_waitcnt lgkmcnt(14)
	v_mfma_f32_16x16x32_bf16 v[16:19], v[88:91], v[120:123], v[16:19]
	s_waitcnt lgkmcnt(12)
	v_mfma_f32_16x16x32_bf16 v[20:23], v[92:95], v[120:123], v[20:23]
	s_waitcnt lgkmcnt(10)
	v_mfma_f32_16x16x32_bf16 v[24:27], v[96:99], v[120:123], v[24:27]
	s_waitcnt lgkmcnt(8)
	v_mfma_f32_16x16x32_bf16 v[28:31], v[100:103], v[120:123], v[28:31]
	s_waitcnt lgkmcnt(6)
	v_mfma_f32_16x16x32_bf16 v[32:35], v[104:107], v[120:123], v[32:35]
	s_waitcnt lgkmcnt(4)
	v_mfma_f32_16x16x32_bf16 v[36:39], v[108:111], v[120:123], v[36:39]
	s_waitcnt lgkmcnt(2)
	v_mfma_f32_16x16x32_bf16 v[40:43], v[112:115], v[120:123], v[40:43]
	s_waitcnt lgkmcnt(0)
	v_mfma_f32_16x16x32_bf16 v[44:47], v[116:119], v[120:123], v[44:47]
na0_bar:
	s_waitcnt lgkmcnt(0)
	s_barrier
	s_add_u32 s27, s27, 1
	s_cmp_lt_u32 s27, s31
	s_cbranch_scc1 na0_top
	v_mov_b32_e32 v196, v243
	v_mov_b32_e32 v197, v243
	s_nop 1
	v_permlane16_swap_b32_e32 v196, v197
	v_add_f32_e32 v196, v196, v197
	v_mov_b32_e32 v197, v196
	s_nop 1
	v_permlane32_swap_b32_e32 v196, v197
	v_add_f32_e32 v196, v196, v197
	v_rcp_f32_e32 v197, v196
	s_nop 0
	v_fma_f32 v196, -v196, v197, 1.0
	v_fma_f32 v244, v196, v197, v197
	v_pk_mul_f32 v[16:17], v[16:17], v[244:245] op_sel_hi:[1,0]
	v_pk_mul_f32 v[18:19], v[18:19], v[244:245] op_sel_hi:[1,0]
	v_cvt_pk_bf16_f32 v16, v16, v17
	v_cvt_pk_bf16_f32 v17, v18, v19
	global_store_dwordx2 v246, v[16:17], s[10:11] offset:0
	v_pk_mul_f32 v[20:21], v[20:21], v[244:245] op_sel_hi:[1,0]
	v_pk_mul_f32 v[22:23], v[22:23], v[244:245] op_sel_hi:[1,0]
	v_cvt_pk_bf16_f32 v20, v20, v21
	v_cvt_pk_bf16_f32 v21, v22, v23
	global_store_dwordx2 v246, v[20:21], s[10:11] offset:32
	v_pk_mul_f32 v[24:25], v[24:25], v[244:245] op_sel_hi:[1,0]
	v_pk_mul_f32 v[26:27], v[26:27], v[244:245] op_sel_hi:[1,0]
	v_cvt_pk_bf16_f32 v24, v24, v25
	v_cvt_pk_bf16_f32 v25, v26, v27
	global_store_dwordx2 v246, v[24:25], s[10:11] offset:64
	v_pk_mul_f32 v[28:29], v[28:29], v[244:245] op_sel_hi:[1,0]
	v_pk_mul_f32 v[30:31], v[30:31], v[244:245] op_sel_hi:[1,0]
	v_cvt_pk_bf16_f32 v28, v28, v29
	v_cvt_pk_bf16_f32 v29, v30, v31
	global_store_dwordx2 v246, v[28:29], s[10:11] offset:96
	v_pk_mul_f32 v[32:33], v[32:33], v[244:245] op_sel_hi:[1,0]
	v_pk_mul_f32 v[34:35], v[34:35], v[244:245] op_sel_hi:[1,0]
	v_cvt_pk_bf16_f32 v32, v32, v33
	v_cvt_pk_bf16_f32 v33, v34, v35
	global_store_dwordx2 v246, v[32:33], s[10:11] offset:128
	v_pk_mul_f32 v[36:37], v[36:37], v[244:245] op_sel_hi:[1,0]
	v_pk_mul_f32 v[38:39], v[38:39], v[244:245] op_sel_hi:[1,0]
	v_cvt_pk_bf16_f32 v36, v36, v37
	v_cvt_pk_bf16_f32 v37, v38, v39
	global_store_dwordx2 v246, v[36:37], s[10:11] offset:160
	v_pk_mul_f32 v[40:41], v[40:41], v[244:245] op_sel_hi:[1,0]
	v_pk_mul_f32 v[42:43], v[42:43], v[244:245] op_sel_hi:[1,0]
	v_cvt_pk_bf16_f32 v40, v40, v41
	v_cvt_pk_bf16_f32 v41, v42, v43
	global_store_dwordx2 v246, v[40:41], s[10:11] offset:192
	v_pk_mul_f32 v[44:45], v[44:45], v[244:245] op_sel_hi:[1,0]
	v_pk_mul_f32 v[46:47], v[46:47], v[244:245] op_sel_hi:[1,0]
	v_cvt_pk_bf16_f32 v44, v44, v45
	v_cvt_pk_bf16_f32 v45, v46, v47
	global_store_dwordx2 v246, v[44:45], s[10:11] offset:224
	s_barrier
	s_and_saveexec_b64 s[0:1], s[24:25]
	s_cbranch_execz na0_nq
	v_mov_b32_e32 v196, 1
	v_mov_b32_e32 v197, 0
	s_add_u32 s6, s50, 0x4100
	s_addc_u32 s7, s51, 0
	global_atomic_add v196, v197, v196, s[6:7] sc0
	v_mov_b32_e32 v197, 0x22040
	s_waitcnt vmcnt(0)
	ds_write_b32 v197, v196
na0_nq:
	s_or_b64 exec, exec, s[0:1]
	v_mov_b32_e32 v197, 0x22040
	s_waitcnt vmcnt(0) lgkmcnt(0)
	s_barrier
	ds_read_b32 v196, v197
	s_waitcnt lgkmcnt(0)
	v_readfirstlane_b32 s29, v196
	s_cmp_lt_u32 s29, 0x388
	s_cbranch_scc1 na0_item
	s_mov_b32 s28, s29
	v_mov_b32_e32 v133, 0

; DI int otid() { int t = threadIdx.x; asm volatile("" : "+v"(t)); return t; }
; template <int DK>
; DI void dense_attn_item(LAS unsigned char* lds, const bf16_t* Qb, int ldq, const bf16_t* Kb, int ldk, const bf16_t* Kpe, const bf16_t* Vt, int nkeys, float sl2, bf16_t* Ob) {
;     const int tid = otid(), lane = tid & 63, wid = tid >> 6, r16 = lane & 15, q4 = lane >> 4;
;     constexpr int KS = DK / 32, KCH = DK / 8, KROW = DK * 2 + 16, KTILE = 64 * KROW, VROW = 144, VTILE = 128 * VROW, NKL = (64 * KCH) / 512;
;     bf16x8 qf[2][KS];
; #pragma unroll
;     for (int qg = 0; qg < 2; ++qg)
; #pragma unroll
;         for (int ks = 0; ks < KS; ++ks) qf[qg][ks] = *(const bf16x8*)(Qb + (size_t)(wid * 32 + qg * 16 + r16) * ldq + ks * 32 + q4 * 8);
;     f32x4 oacc[2][8];
; #pragma unroll
;     for (int qg = 0; qg < 2; ++qg)
; #pragma unroll
;         for (int d = 0; d < 8; ++d) oacc[qg][d] = (f32x4){0.f, 0.f, 0.f, 0.f};
;     float mrun[2] = {-1e30f, -1e30f}, lsum[2] = {0.f, 0.f};
;     u32x4 kst[NKL], vst[2];
;     const int ntiles = nkeys >> 6;
;     ...
;     DA_LOAD(0); DA_STORE(0);
;     __syncthreads();
; DI void dense192_item(unsigned char* ws, LAS unsigned char* lds, int b, int h, int q0, int nk) {
;     const size_t rowb = (size_t)b * RB, row0 = rowb + q0;
;     dense_attn_item<192>(lds, (const bf16_t*)(ws + WS_QM) + row0 * 960 + h * 192, 960, (const bf16_t*)(ws + WS_KM) + rowb * 640 + h * 128, 640, (const bf16_t*)(ws + WS_KPE) + rowb * 64,
;                          (const bf16_t*)(ws + WS_VTM) + ((size_t)b * 640 + h * 128) * RB, nk, 0.07216878364870322f * 1.4426950408889634f, (bf16_t*)(ws + WS_YMIX) + row0 * DM + 768 + h * 128);
.LBB0_2593:
	s_mul_hi_u32 s71, s0, 0x66666667
	s_lshr_b32 s71, s71, 4
	s_lshr_b32 s73, s0, 3
	s_mul_i32 s62, s71, 5
	s_sub_u32 s73, s73, s62
	s_and_b32 s62, s0, 7
	s_lshl_b32 s62, s62, 8
	s_mul_i32 s75, s71, 0x900
	s_add_u32 s74, s75, s62
	s_addk_i32 s74, 0x100
	s_mul_i32 s62, s74, 0x780
	s_mul_i32 s63, s73, 0x180
	s_add_u32 s62, s62, s63
	s_add_u32 s62, s62, 0x1a3a0000
	s_add_u32 s10, s50, s62
	s_addc_u32 s11, s51, 0
	s_mul_i32 s62, s75, 0x500
	s_lshl_b32 s63, s73, 8
	s_add_u32 s62, s62, s63
	s_add_u32 s62, s62, 0x1b480000
	s_add_u32 s4, s50, s62
	s_addc_u32 s5, s51, 0
	s_mul_i32 s62, s75, 0x480
	s_add_u32 s62, s62, s63
	s_sub_u32 s76, 0x167ff00, s62
	s_mul_i32 s62, s71, 0x280
	s_lshl_b32 s63, s73, 7
	s_add_u32 s62, s62, s63
	s_mul_i32 s62, s62, 0x1200
	s_add_u32 s62, s62, 0x1bfc0000
	s_add_u32 s8, s50, s62
	s_addc_u32 s9, s51, 0
	s_lshl_b32 s62, s74, 12
	s_lshl_b32 s63, s73, 8
	s_add_u32 s62, s62, s63
	s_add_u32 s62, s62, 0x1d9a0600
	s_add_u32 s20, s50, s62
	s_addc_u32 s21, s51, 0
	s_mov_b32 s22, 0x3dd53b94
	v_and_b32_e32 v192, 15, v202
	v_bfe_u32 v193, v202, 4, 2
	v_lshrrev_b32_e32 v194, 6, v202
	v_lshl_add_u32 v195, v194, 5, v192
	v_mul_u32_u24_e32 v196, 0x780, v195
	v_lshl_add_u32 v250, v193, 4, v196
	v_add_u32_e32 v251, 0x7800, v250
	global_load_dwordx4 v[0:3], v250, s[10:11] offset:0
	global_load_dwordx4 v[4:7], v250, s[10:11] offset:64
	global_load_dwordx4 v[8:11], v250, s[10:11] offset:128
	global_load_dwordx4 v[12:15], v250, s[10:11] offset:192
	global_load_dwordx4 v[16:19], v250, s[10:11] offset:256
	global_load_dwordx4 v[20:23], v250, s[10:11] offset:320
	global_load_dwordx4 v[24:27], v251, s[10:11] offset:0
	global_load_dwordx4 v[28:31], v251, s[10:11] offset:64
	global_load_dwordx4 v[32:35], v251, s[10:11] offset:128
	global_load_dwordx4 v[36:39], v251, s[10:11] offset:192
	global_load_dwordx4 v[40:43], v251, s[10:11] offset:256
	global_load_dwordx4 v[44:47], v251, s[10:11] offset:320
	s_mov_b32 s62, 0xaaaaaab
	v_mov_b32_e32 v197, v202
	v_mul_hi_u32 v198, v197, s62
	v_mul_u32_u24_e32 v195, 24, v198
	v_sub_u32_e32 v199, v197, v195
	v_mul_u32_u24_e32 v195, 0x190, v198
	v_lshl_add_u32 v230, v199, 4, v195
	v_cmp_gt_u32_e32 vcc, 16, v199
	v_mul_u32_u24_e32 v195, 0x500, v198
	v_lshlrev_b32_e32 v196, 7, v198
	v_add_u32_e32 v196, s76, v196
	s_nop 1
	v_cndmask_b32_e32 v195, v196, v195, vcc
	v_lshl_add_u32 v224, v199, 4, v195
	v_mov_b32_e32 v195, 0x2000
	v_mov_b32_e32 v196, 0x14000
	v_cndmask_b32_e32 v227, v195, v196, vcc
	v_add_u32_e32 v197, 0x200, v202
	v_mul_hi_u32 v198, v197, s62
	v_mul_u32_u24_e32 v195, 24, v198
	v_sub_u32_e32 v199, v197, v195
	v_mul_u32_u24_e32 v195, 0x190, v198
	v_lshl_add_u32 v231, v199, 4, v195
	v_cmp_gt_u32_e32 vcc, 16, v199
	v_mul_u32_u24_e32 v195, 0x500, v198
	v_lshlrev_b32_e32 v196, 7, v198
	v_add_u32_e32 v196, s76, v196
	s_nop 1
	v_cndmask_b32_e32 v195, v196, v195, vcc
	v_lshl_add_u32 v225, v199, 4, v195
	v_mov_b32_e32 v195, 0x2000
	v_mov_b32_e32 v196, 0x14000
	v_cndmask_b32_e32 v228, v195, v196, vcc
	v_add_u32_e32 v197, 0x400, v202
	v_mul_hi_u32 v198, v197, s62
	v_mul_u32_u24_e32 v195, 24, v198
	v_sub_u32_e32 v199, v197, v195
	v_mul_u32_u24_e32 v195, 0x190, v198
	v_lshl_add_u32 v232, v199, 4, v195
	v_cmp_gt_u32_e32 vcc, 16, v199
	v_mul_u32_u24_e32 v195, 0x500, v198
	v_lshlrev_b32_e32 v196, 7, v198
	v_add_u32_e32 v196, s76, v196
	s_nop 1
	v_cndmask_b32_e32 v195, v196, v195, vcc
	v_lshl_add_u32 v226, v199, 4, v195
	v_mov_b32_e32 v195, 0x2000
	v_mov_b32_e32 v196, 0x14000
	v_cndmask_b32_e32 v229, v195, v196, vcc
	v_mov_b32_e32 v197, v202
	v_lshrrev_b32_e32 v198, 3, v197
	v_and_b32_e32 v199, 7, v197
	v_mul_u32_u24_e32 v195, 0x1200, v198
	v_lshl_add_u32 v233, v199, 4, v195
	v_mul_u32_u24_e32 v195, 0x90, v198
	v_lshl_add_u32 v195, v199, 4, v195
	v_add_u32_e32 v235, 0x12c00, v195
	v_add_u32_e32 v197, 0x200, v202
	v_lshrrev_b32_e32 v198, 3, v197
	v_and_b32_e32 v199, 7, v197
	v_mul_u32_u24_e32 v195, 0x1200, v198
	v_lshl_add_u32 v234, v199, 4, v195
	v_mul_u32_u24_e32 v195, 0x90, v198
	v_lshl_add_u32 v195, v199, 4, v195
	v_add_u32_e32 v236, 0x12c00, v195
	v_mul_u32_u24_e32 v195, 0x190, v192
	v_lshl_add_u32 v237, v193, 4, v195
	v_mul_u32_u24_e32 v195, 0x90, v192
	v_lshl_add_u32 v195, v193, 3, v195
	v_add_u32_e32 v238, 0x12c00, v195
	global_load_dwordx4 v[204:207], v224, s[4:5]
	global_load_dwordx4 v[208:211], v225, s[4:5]
	global_load_dwordx4 v[212:215], v226, s[4:5]
	global_load_dwordx4 v[216:219], v233, s[8:9]
	global_load_dwordx4 v[220:223], v234, s[8:9]
	v_add_u32_e32 v224, v224, v227
	v_add_u32_e32 v225, v225, v228
	v_add_u32_e32 v226, v226, v229
	s_add_u32 s8, s8, 0x80
	s_addc_u32 s9, s9, 0
	v_mov_b32_e32 v48, 0
	v_mov_b32_e32 v49, 0
	v_mov_b32_e32 v50, 0
	v_mov_b32_e32 v51, 0
	v_mov_b32_e32 v52, 0
	v_mov_b32_e32 v53, 0
	v_mov_b32_e32 v54, 0
	v_mov_b32_e32 v55, 0
	v_mov_b32_e32 v56, 0
	v_mov_b32_e32 v57, 0
	v_mov_b32_e32 v58, 0
	v_mov_b32_e32 v59, 0
	v_mov_b32_e32 v60, 0
	v_mov_b32_e32 v61, 0
	v_mov_b32_e32 v62, 0
	v_mov_b32_e32 v63, 0
	v_mov_b32_e32 v64, 0
	v_mov_b32_e32 v65, 0
	v_mov_b32_e32 v66, 0
	v_mov_b32_e32 v67, 0
	v_mov_b32_e32 v68, 0
	v_mov_b32_e32 v69, 0
	v_mov_b32_e32 v70, 0
	v_mov_b32_e32 v71, 0
	v_mov_b32_e32 v72, 0
	v_mov_b32_e32 v73, 0
	v_mov_b32_e32 v74, 0
	v_mov_b32_e32 v75, 0
	v_mov_b32_e32 v76, 0
	v_mov_b32_e32 v77, 0
	v_mov_b32_e32 v78, 0
	v_mov_b32_e32 v79, 0
	v_mov_b32_e32 v80, 0
	v_mov_b32_e32 v81, 0
	v_mov_b32_e32 v82, 0
	v_mov_b32_e32 v83, 0
	v_mov_b32_e32 v84, 0
	v_mov_b32_e32 v85, 0
	v_mov_b32_e32 v86, 0
	v_mov_b32_e32 v87, 0
	v_mov_b32_e32 v88, 0
	v_mov_b32_e32 v89, 0
	v_mov_b32_e32 v90, 0
	v_mov_b32_e32 v91, 0
	v_mov_b32_e32 v92, 0
	v_mov_b32_e32 v93, 0
	v_mov_b32_e32 v94, 0
	v_mov_b32_e32 v95, 0
	v_mov_b32_e32 v96, 0
	v_mov_b32_e32 v97, 0
	v_mov_b32_e32 v98, 0
	v_mov_b32_e32 v99, 0
	v_mov_b32_e32 v100, 0
	v_mov_b32_e32 v101, 0
	v_mov_b32_e32 v102, 0
	v_mov_b32_e32 v103, 0
	v_mov_b32_e32 v104, 0
	v_mov_b32_e32 v105, 0
	v_mov_b32_e32 v106, 0
	v_mov_b32_e32 v107, 0
	v_mov_b32_e32 v108, 0
	v_mov_b32_e32 v109, 0
	v_mov_b32_e32 v110, 0
	v_mov_b32_e32 v111, 0
	v_mov_b32_e32 v242, 0xf149f2ca
	v_mov_b32_e32 v244, 0
	v_mov_b32_e32 v243, 0xf149f2ca
	v_mov_b32_e32 v245, 0
	s_waitcnt vmcnt(0)
	v_lshl_add_u32 v195, v194, 5, v192
	v_lshlrev_b32_e32 v195, 12, v195
	v_lshl_add_u32 v250, v193, 3, v195
	v_add_u32_e32 v251, 0x10000, v250
	ds_write_b128 v230, v[204:207]
	ds_write_b128 v231, v[208:211]
	ds_write_b128 v232, v[212:215]
	ds_write_b128 v235, v[216:219]
	ds_write_b128 v236, v[220:223]
	s_waitcnt lgkmcnt(0)
	global_load_dwordx4 v[204:207], v224, s[4:5]
	global_load_dwordx4 v[208:211], v225, s[4:5]
	global_load_dwordx4 v[212:215], v226, s[4:5]
	global_load_dwordx4 v[216:219], v233, s[8:9]
	global_load_dwordx4 v[220:223], v234, s[8:9]
	s_barrier
; template <int DK>
; DI void dense_attn_item(LAS unsigned char* lds, const bf16_t* Qb, int ldq, const bf16_t* Kb, int ldk, const bf16_t* Kpe, const bf16_t* Vt, int nkeys, float sl2, bf16_t* Ob) {
;     ...
;     for (int kt = 0; kt < ntiles; ++kt) {
;         const int cur = kt & 1;
;         if (kt + 1 < ntiles) DA_LOAD((kt + 1) * 64);
;         const LAS unsigned char* kb_ = lds + cur * KTILE; const LAS unsigned char* vb_ = lds + 2 * KTILE + cur * VTILE;
; #pragma unroll
;         for (int kc = 0; kc < 2; ++kc) {
;             f32x4 sacc[2][2];
; #pragma unroll
;             for (int kb = 0; kb < 2; ++kb) {
;                 sacc[0][kb] = (f32x4){0.f, 0.f, 0.f, 0.f}; sacc[1][kb] = (f32x4){0.f, 0.f, 0.f, 0.f};
; #pragma unroll
;                 for (int kh = 0; kh < KS / 2; ++kh) {
;                     const bf16x8 k0 = *(const LAS bf16x8*)(kb_ + ((2 * kc + kb) * 16 + r16) * KROW + (2 * kh) * 64 + q4 * 16);
;                     const bf16x8 k1 = *(const LAS bf16x8*)(kb_ + ((2 * kc + kb) * 16 + r16) * KROW + (2 * kh + 1) * 64 + q4 * 16);
;                     __builtin_amdgcn_s_setprio(1);
;                     sacc[0][kb] = MFMA16(k0, qf[0][2 * kh], sacc[0][kb]); sacc[1][kb] = MFMA16(k0, qf[1][2 * kh], sacc[1][kb]);
;                     sacc[0][kb] = MFMA16(k1, qf[0][2 * kh + 1], sacc[0][kb]); sacc[1][kb] = MFMA16(k1, qf[1][2 * kh + 1], sacc[1][kb]);
;                     __builtin_amdgcn_s_setprio(0);
;                 }
;             }
;             bf16x8 pb[2];
; #pragma unroll
;             for (int qg = 0; qg < 2; ++qg) {
;                 float mx = fmaxf(fmaxf(fmaxf(sacc[qg][0][0], sacc[qg][0][1]), fmaxf(sacc[qg][0][2], sacc[qg][0][3])), fmaxf(fmaxf(sacc[qg][1][0], sacc[qg][1][1]), fmaxf(sacc[qg][1][2], sacc[qg][1][3])));
;                 mx = fmaxf(mx, __shfl_xor(mx, 16)); mx = fmaxf(mx, __shfl_xor(mx, 32));
;                 const float mnew = fmaxf(mrun[qg], mx * sl2), alpha = fast_exp2(mrun[qg] - mnew);
;                 mrun[qg] = mnew;
;                 float ps = 0.f;
; #pragma unroll
;                 for (int kb = 0; kb < 2; ++kb)
; #pragma unroll
;                     for (int j = 0; j < 4; ++j) { const float pv = fast_exp2(sacc[qg][kb][j] * sl2 - mnew); sacc[qg][kb][j] = pv; ps += pv; }
;                 lsum[qg] = lsum[qg] * alpha + ps;
; #pragma unroll
;                 for (int d = 0; d < 8; ++d) oacc[qg][d] *= alpha;
	v_mov_b32_e32 v239, v237
	ds_read_b128 v[144:147], v239 offset:0
	ds_read_b128 v[148:151], v239 offset:64
	ds_read_b128 v[152:155], v239 offset:128
	ds_read_b128 v[156:159], v239 offset:192
	ds_read_b128 v[160:163], v239 offset:256
	ds_read_b128 v[164:167], v239 offset:320
	s_waitcnt lgkmcnt(5)
	v_mfma_f32_16x16x32_bf16 v[112:115], v[144:147], v[0:3], 0
	v_mfma_f32_16x16x32_bf16 v[120:123], v[144:147], v[24:27], 0
	s_waitcnt lgkmcnt(4)
	v_mfma_f32_16x16x32_bf16 v[112:115], v[148:151], v[4:7], v[112:115]
	v_mfma_f32_16x16x32_bf16 v[120:123], v[148:151], v[28:31], v[120:123]
	s_waitcnt lgkmcnt(3)
	v_mfma_f32_16x16x32_bf16 v[112:115], v[152:155], v[8:11], v[112:115]
	v_mfma_f32_16x16x32_bf16 v[120:123], v[152:155], v[32:35], v[120:123]
	s_waitcnt lgkmcnt(2)
	v_mfma_f32_16x16x32_bf16 v[112:115], v[156:159], v[12:15], v[112:115]
	v_mfma_f32_16x16x32_bf16 v[120:123], v[156:159], v[36:39], v[120:123]
	s_waitcnt lgkmcnt(1)
	v_mfma_f32_16x16x32_bf16 v[112:115], v[160:163], v[16:19], v[112:115]
	v_mfma_f32_16x16x32_bf16 v[120:123], v[160:163], v[40:43], v[120:123]
	s_waitcnt lgkmcnt(0)
	v_mfma_f32_16x16x32_bf16 v[112:115], v[164:167], v[20:23], v[112:115]
	v_mfma_f32_16x16x32_bf16 v[120:123], v[164:167], v[44:47], v[120:123]
	ds_read_b128 v[144:147], v239 offset:6400
	ds_read_b128 v[148:151], v239 offset:6464
	ds_read_b128 v[152:155], v239 offset:6528
	ds_read_b128 v[156:159], v239 offset:6592
	ds_read_b128 v[160:163], v239 offset:6656
	ds_read_b128 v[164:167], v239 offset:6720
	s_waitcnt lgkmcnt(5)
	v_mfma_f32_16x16x32_bf16 v[116:119], v[144:147], v[0:3], 0
	v_mfma_f32_16x16x32_bf16 v[124:127], v[144:147], v[24:27], 0
	s_waitcnt lgkmcnt(4)
	v_mfma_f32_16x16x32_bf16 v[116:119], v[148:151], v[4:7], v[116:119]
	v_mfma_f32_16x16x32_bf16 v[124:127], v[148:151], v[28:31], v[124:127]
	s_waitcnt lgkmcnt(3)
	v_mfma_f32_16x16x32_bf16 v[116:119], v[152:155], v[8:11], v[116:119]
	v_mfma_f32_16x16x32_bf16 v[124:127], v[152:155], v[32:35], v[124:127]
	s_waitcnt lgkmcnt(2)
	v_mfma_f32_16x16x32_bf16 v[116:119], v[156:159], v[12:15], v[116:119]
	v_mfma_f32_16x16x32_bf16 v[124:127], v[156:159], v[36:39], v[124:127]
	s_waitcnt lgkmcnt(1)
	v_mfma_f32_16x16x32_bf16 v[116:119], v[160:163], v[16:19], v[116:119]
	v_mfma_f32_16x16x32_bf16 v[124:127], v[160:163], v[40:43], v[124:127]
	s_waitcnt lgkmcnt(0)
	v_mfma_f32_16x16x32_bf16 v[116:119], v[164:167], v[20:23], v[116:119]
	v_mfma_f32_16x16x32_bf16 v[124:127], v[164:167], v[44:47], v[124:127]
	s_mov_b32 s23, 0
	s_mov_b32 s27, 0
dn1_top:
	s_add_u32 s57, s27, 1
	s_cmp_eq_u32 s57, 3
	s_cselect_b32 s57, 0, s57
	s_mul_i32 s36, s27, 0x6400
	s_mul_i32 s54, s27, 0x4800
	s_mul_i32 s37, s57, 0x6400
	s_mul_i32 s56, s57, 0x4800
	v_add_u32_e32 v239, s36, v237
	v_add_u32_e32 v240, s37, v237
	v_add_u32_e32 v241, s54, v238
	v_add_u32_e32 v196, s37, v230
	v_add_u32_e32 v197, s37, v231
	v_add_u32_e32 v198, s37, v232
	v_add_u32_e32 v199, s56, v235
	v_add_u32_e32 v200, s56, v236
	v_add_u32_e32 v224, v224, v227
	v_add_u32_e32 v225, v225, v228
	v_add_u32_e32 v226, v226, v229
	s_add_u32 s8, s8, 0x80
	s_addc_u32 s9, s9, 0
	s_waitcnt vmcnt(0)
	ds_write_b128 v196, v[204:207]
	ds_write_b128 v197, v[208:211]
	ds_write_b128 v198, v[212:215]
	ds_write_b128 v199, v[216:219]
	ds_write_b128 v200, v[220:223]
	ds_read_b128 v[144:147], v239 offset:12800
	ds_read_b128 v[148:151], v239 offset:12864
	ds_read_b128 v[152:155], v239 offset:12928
	ds_read_b128 v[156:159], v239 offset:12992
	ds_read_b128 v[160:163], v239 offset:13056
	ds_read_b128 v[164:167], v239 offset:13120
	v_max3_f32 v192, v112, v113, v114
	v_max3_f32 v194, v120, v121, v122
	v_max3_f32 v193, v115, v116, v117
	v_max3_f32 v195, v123, v124, v125
	v_max3_f32 v192, v192, v118, v119
	v_max3_f32 v194, v194, v126, v127
	v_max_f32_e32 v192, v192, v193
	v_max_f32_e32 v194, v194, v195
	v_mov_b32_e32 v193, v192
	v_mov_b32_e32 v195, v194
	s_nop 1
	v_permlane16_swap_b32_e32 v192, v193
	s_waitcnt lgkmcnt(5)
	global_load_dwordx4 v[204:207], v224, s[4:5]
	global_load_dwordx4 v[208:211], v225, s[4:5]
	global_load_dwordx4 v[212:215], v226, s[4:5]
	global_load_dwordx4 v[216:219], v233, s[8:9]
	global_load_dwordx4 v[220:223], v234, s[8:9]
	v_mfma_f32_16x16x32_bf16 v[128:131], v[144:147], v[0:3], 0
	v_permlane16_swap_b32_e32 v194, v195
	v_max_f32_e32 v192, v192, v193
	v_max_f32_e32 v194, v194, v195
	v_mfma_f32_16x16x32_bf16 v[136:139], v[144:147], v[24:27], 0
	v_mov_b32_e32 v193, v192
	v_mov_b32_e32 v195, v194
	s_nop 1
	ds_read_b128 v[144:147], v239 offset:19200
	s_waitcnt lgkmcnt(5)
	v_mfma_f32_16x16x32_bf16 v[128:131], v[148:151], v[4:7], v[128:131]
	v_permlane32_swap_b32_e32 v192, v193
	v_permlane32_swap_b32_e32 v194, v195
	v_max_f32_e32 v192, v192, v193
	v_mfma_f32_16x16x32_bf16 v[136:139], v[148:151], v[28:31], v[136:139]
	v_max_f32_e32 v194, v194, v195
	v_mul_f32_e32 v192, s22, v192
	v_mul_f32_e32 v194, s22, v194
	ds_read_b128 v[148:151], v239 offset:19264
	s_waitcnt lgkmcnt(5)
	v_mfma_f32_16x16x32_bf16 v[128:131], v[152:155], v[8:11], v[128:131]
	v_max_f32_e32 v193, v242, v192
	v_max_f32_e32 v195, v243, v194
	v_sub_f32_e32 v192, v242, v193
	v_mfma_f32_16x16x32_bf16 v[136:139], v[152:155], v[32:35], v[136:139]
	v_sub_f32_e32 v194, v243, v195
	v_exp_f32_e32 v246, v192
	v_exp_f32_e32 v248, v194
	ds_read_b128 v[152:155], v239 offset:19328
	s_waitcnt lgkmcnt(5)
	v_mfma_f32_16x16x32_bf16 v[128:131], v[156:159], v[12:15], v[128:131]
	v_mov_b32_e32 v242, v193
	v_mov_b32_e32 v243, v195
	v_fma_f32 v112, v112, s22, -v193
	v_mfma_f32_16x16x32_bf16 v[136:139], v[156:159], v[36:39], v[136:139]
	v_fma_f32 v120, v120, s22, -v195
	v_fma_f32 v113, v113, s22, -v193
	v_fma_f32 v121, v121, s22, -v195
	ds_read_b128 v[156:159], v239 offset:19392
	s_waitcnt lgkmcnt(5)
; #define LAS __attribute__((address_space(3)))
; template <int DK>
; DI void dense_attn_item(LAS unsigned char* lds, const bf16_t* Qb, int ldq, const bf16_t* Kb, int ldk, const bf16_t* Kpe, const bf16_t* Vt, int nkeys, float sl2, bf16_t* Ob) {
;     ...
;             for (int qg = 0; qg < 2; ++qg) {
;                 float mx = fmaxf(fmaxf(fmaxf(sacc[qg][0][0], sacc[qg][0][1]), fmaxf(sacc[qg][0][2], sacc[qg][0][3])), fmaxf(fmaxf(sacc[qg][1][0], sacc[qg][1][1]), fmaxf(sacc[qg][1][2], sacc[qg][1][3])));
;                 mx = fmaxf(mx, __shfl_xor(mx, 16)); mx = fmaxf(mx, __shfl_xor(mx, 32));
;                 const float mnew = fmaxf(mrun[qg], mx * sl2), alpha = fast_exp2(mrun[qg] - mnew);
;                 mrun[qg] = mnew;
;                 float ps = 0.f;
; #pragma unroll
;                 for (int kb = 0; kb < 2; ++kb)
; #pragma unroll
;                     for (int j = 0; j < 4; ++j) { const float pv = fast_exp2(sacc[qg][kb][j] * sl2 - mnew); sacc[qg][kb][j] = pv; ps += pv; }
;                 lsum[qg] = lsum[qg] * alpha + ps;
; #pragma unroll
;                 for (int d = 0; d < 8; ++d) oacc[qg][d] *= alpha;
;                 u32x4 w; w.x = cvt_pk_bf16(sacc[qg][0][0], sacc[qg][0][1]); w.y = cvt_pk_bf16(sacc[qg][0][2], sacc[qg][0][3]);
;                 w.z = cvt_pk_bf16(sacc[qg][1][0], sacc[qg][1][1]); w.w = cvt_pk_bf16(sacc[qg][1][2], sacc[qg][1][3]);
;                 pb[qg] = __builtin_bit_cast(bf16x8, w);
;             }
; #pragma unroll
;             for (int dh = 0; dh < 4; ++dh) {
;                 bf16x8 vfr[2];
; #pragma unroll
;                 for (int d4 = 0; d4 < 2; ++d4) {
;                     const int d = dh * 2 + d4;
;                     const u32x2 lo = *(const LAS u32x2*)(vb_ + (d * 16 + r16) * VROW + (kc * 32 + q4 * 4) * 2);
;                     const u32x2 hi = *(const LAS u32x2*)(vb_ + (d * 16 + r16) * VROW + (kc * 32 + 16 + q4 * 4) * 2);
;                     u32x4 w; w.x = lo.x; w.y = lo.y; w.z = hi.x; w.w = hi.y;
;                     vfr[d4] = __builtin_bit_cast(bf16x8, w);
;                 }
;                 __builtin_amdgcn_s_setprio(1);
; #pragma unroll
;                 for (int d4 = 0; d4 < 2; ++d4) { const int d = dh * 2 + d4; oacc[0][d] = MFMA16(vfr[d4], pb[0], oacc[0][d]); oacc[1][d] = MFMA16(vfr[d4], pb[1], oacc[1][d]); }
;                 __builtin_amdgcn_s_setprio(0);
;             }
	v_mfma_f32_16x16x32_bf16 v[128:131], v[160:163], v[16:19], v[128:131]
	v_fma_f32 v114, v114, s22, -v193
	v_fma_f32 v122, v122, s22, -v195
	v_fma_f32 v115, v115, s22, -v193
	v_mfma_f32_16x16x32_bf16 v[136:139], v[160:163], v[40:43], v[136:139]
	v_fma_f32 v123, v123, s22, -v195
	v_fma_f32 v116, v116, s22, -v193
	v_fma_f32 v124, v124, s22, -v195
	ds_read_b128 v[160:163], v239 offset:19456
	s_waitcnt lgkmcnt(5)
	v_mfma_f32_16x16x32_bf16 v[128:131], v[164:167], v[20:23], v[128:131]
	v_fma_f32 v117, v117, s22, -v193
	v_fma_f32 v125, v125, s22, -v195
	v_fma_f32 v118, v118, s22, -v193
	v_mfma_f32_16x16x32_bf16 v[136:139], v[164:167], v[44:47], v[136:139]
	v_fma_f32 v126, v126, s22, -v195
	v_fma_f32 v119, v119, s22, -v193
	v_fma_f32 v127, v127, s22, -v195
	ds_read_b128 v[164:167], v239 offset:19520
	s_waitcnt lgkmcnt(5)
	v_mfma_f32_16x16x32_bf16 v[132:135], v[144:147], v[0:3], 0
	v_exp_f32_e32 v112, v112
	v_exp_f32_e32 v120, v120
	v_exp_f32_e32 v113, v113
	v_mfma_f32_16x16x32_bf16 v[140:143], v[144:147], v[24:27], 0
	v_exp_f32_e32 v121, v121
	v_exp_f32_e32 v114, v114
	v_exp_f32_e32 v122, v122
	ds_read_b64 v[168:169], v241 offset:0
	ds_read_b64 v[170:171], v241 offset:32
	s_waitcnt lgkmcnt(6)
	v_mfma_f32_16x16x32_bf16 v[132:135], v[148:151], v[4:7], v[132:135]
	v_exp_f32_e32 v115, v115
	v_exp_f32_e32 v123, v123
	v_exp_f32_e32 v116, v116
	v_mfma_f32_16x16x32_bf16 v[140:143], v[148:151], v[28:31], v[140:143]
	v_exp_f32_e32 v124, v124
	v_exp_f32_e32 v117, v117
	v_exp_f32_e32 v125, v125
	ds_read_b64 v[172:173], v241 offset:2304
	ds_read_b64 v[174:175], v241 offset:2336
	s_waitcnt lgkmcnt(7)
	v_mfma_f32_16x16x32_bf16 v[132:135], v[152:155], v[8:11], v[132:135]
	v_exp_f32_e32 v118, v118
	v_exp_f32_e32 v126, v126
	v_exp_f32_e32 v119, v119
	v_mfma_f32_16x16x32_bf16 v[140:143], v[152:155], v[32:35], v[140:143]
	v_exp_f32_e32 v127, v127
	v_add_f32_e32 v192, v112, v113
	v_add_f32_e32 v194, v120, v121
	ds_read_b64 v[176:177], v241 offset:4608
	ds_read_b64 v[178:179], v241 offset:4640
	s_waitcnt lgkmcnt(8)
	v_mfma_f32_16x16x32_bf16 v[132:135], v[156:159], v[12:15], v[132:135]
	v_add_f32_e32 v192, v192, v114
	v_add_f32_e32 v194, v194, v122
	v_add_f32_e32 v192, v192, v115
	v_mfma_f32_16x16x32_bf16 v[140:143], v[156:159], v[36:39], v[140:143]
	v_add_f32_e32 v194, v194, v123
	v_add_f32_e32 v192, v192, v116
	v_add_f32_e32 v194, v194, v124
	ds_read_b64 v[180:181], v241 offset:6912
	ds_read_b64 v[182:183], v241 offset:6944
	s_waitcnt lgkmcnt(9)
	v_mfma_f32_16x16x32_bf16 v[132:135], v[160:163], v[16:19], v[132:135]
	v_add_f32_e32 v192, v192, v117
	v_add_f32_e32 v194, v194, v125
	v_add_f32_e32 v192, v192, v118
	v_mfma_f32_16x16x32_bf16 v[140:143], v[160:163], v[40:43], v[140:143]
	v_add_f32_e32 v194, v194, v126
	v_add_f32_e32 v192, v192, v119
	v_add_f32_e32 v194, v194, v127
	s_waitcnt lgkmcnt(8)
	v_mfma_f32_16x16x32_bf16 v[132:135], v[164:167], v[20:23], v[132:135]
	v_fma_f32 v244, v244, v246, v192
	v_fma_f32 v245, v245, v248, v194
	v_cvt_pk_bf16_f32 v184, v112, v113
	v_mfma_f32_16x16x32_bf16 v[140:143], v[164:167], v[44:47], v[140:143]
	v_cvt_pk_bf16_f32 v188, v120, v121
	v_cvt_pk_bf16_f32 v185, v114, v115
	v_cvt_pk_bf16_f32 v189, v122, v123
	v_cvt_pk_bf16_f32 v186, v116, v117
	v_cvt_pk_bf16_f32 v190, v124, v125
	v_cvt_pk_bf16_f32 v187, v118, v119
	v_cvt_pk_bf16_f32 v191, v126, v127
	v_pk_mul_f32 v[48:49], v[48:49], v[246:247] op_sel_hi:[1,0]
	v_pk_mul_f32 v[50:51], v[50:51], v[246:247] op_sel_hi:[1,0]
	v_pk_mul_f32 v[80:81], v[80:81], v[248:249] op_sel_hi:[1,0]
	v_pk_mul_f32 v[82:83], v[82:83], v[248:249] op_sel_hi:[1,0]
	s_waitcnt lgkmcnt(6)
	v_mfma_f32_16x16x32_bf16 v[48:51], v[168:171], v[184:187], v[48:51]
	v_pk_mul_f32 v[52:53], v[52:53], v[246:247] op_sel_hi:[1,0]
	v_pk_mul_f32 v[54:55], v[54:55], v[246:247] op_sel_hi:[1,0]
	v_mfma_f32_16x16x32_bf16 v[80:83], v[168:171], v[188:191], v[80:83]
	v_pk_mul_f32 v[84:85], v[84:85], v[248:249] op_sel_hi:[1,0]
	v_pk_mul_f32 v[86:87], v[86:87], v[248:249] op_sel_hi:[1,0]
	ds_read_b64 v[168:169], v241 offset:9216
	ds_read_b64 v[170:171], v241 offset:9248
	s_waitcnt lgkmcnt(6)
	v_mfma_f32_16x16x32_bf16 v[52:55], v[172:175], v[184:187], v[52:55]
	v_pk_mul_f32 v[56:57], v[56:57], v[246:247] op_sel_hi:[1,0]
	v_pk_mul_f32 v[58:59], v[58:59], v[246:247] op_sel_hi:[1,0]
	v_mfma_f32_16x16x32_bf16 v[84:87], v[172:175], v[188:191], v[84:87]
	v_pk_mul_f32 v[88:89], v[88:89], v[248:249] op_sel_hi:[1,0]
	v_pk_mul_f32 v[90:91], v[90:91], v[248:249] op_sel_hi:[1,0]
	ds_read_b64 v[172:173], v241 offset:11520
	ds_read_b64 v[174:175], v241 offset:11552
	s_waitcnt lgkmcnt(6)
	v_mfma_f32_16x16x32_bf16 v[56:59], v[176:179], v[184:187], v[56:59]
	v_pk_mul_f32 v[60:61], v[60:61], v[246:247] op_sel_hi:[1,0]
	v_pk_mul_f32 v[62:63], v[62:63], v[246:247] op_sel_hi:[1,0]
	v_mfma_f32_16x16x32_bf16 v[88:91], v[176:179], v[188:191], v[88:91]
	v_pk_mul_f32 v[92:93], v[92:93], v[248:249] op_sel_hi:[1,0]
	v_pk_mul_f32 v[94:95], v[94:95], v[248:249] op_sel_hi:[1,0]
	ds_read_b64 v[176:177], v241 offset:13824
	ds_read_b64 v[178:179], v241 offset:13856
	s_waitcnt lgkmcnt(6)
	v_mfma_f32_16x16x32_bf16 v[60:63], v[180:183], v[184:187], v[60:63]
	v_pk_mul_f32 v[64:65], v[64:65], v[246:247] op_sel_hi:[1,0]
	v_pk_mul_f32 v[66:67], v[66:67], v[246:247] op_sel_hi:[1,0]
	v_mfma_f32_16x16x32_bf16 v[92:95], v[180:183], v[188:191], v[92:95]
	v_pk_mul_f32 v[96:97], v[96:97], v[248:249] op_sel_hi:[1,0]
	v_pk_mul_f32 v[98:99], v[98:99], v[248:249] op_sel_hi:[1,0]
	ds_read_b64 v[180:181], v241 offset:16128
	ds_read_b64 v[182:183], v241 offset:16160
	s_waitcnt lgkmcnt(6)
	v_mfma_f32_16x16x32_bf16 v[64:67], v[168:171], v[184:187], v[64:67]
	v_pk_mul_f32 v[68:69], v[68:69], v[246:247] op_sel_hi:[1,0]
	v_pk_mul_f32 v[70:71], v[70:71], v[246:247] op_sel_hi:[1,0]
	v_mfma_f32_16x16x32_bf16 v[96:99], v[168:171], v[188:191], v[96:99]
	v_pk_mul_f32 v[100:101], v[100:101], v[248:249] op_sel_hi:[1,0]
	v_pk_mul_f32 v[102:103], v[102:103], v[248:249] op_sel_hi:[1,0]
	s_waitcnt lgkmcnt(4)
	v_mfma_f32_16x16x32_bf16 v[68:71], v[172:175], v[184:187], v[68:71]
	v_pk_mul_f32 v[72:73], v[72:73], v[246:247] op_sel_hi:[1,0]
	v_pk_mul_f32 v[74:75], v[74:75], v[246:247] op_sel_hi:[1,0]
	v_mfma_f32_16x16x32_bf16 v[100:103], v[172:175], v[188:191], v[100:103]
	v_pk_mul_f32 v[104:105], v[104:105], v[248:249] op_sel_hi:[1,0]
	v_pk_mul_f32 v[106:107], v[106:107], v[248:249] op_sel_hi:[1,0]
	s_waitcnt lgkmcnt(2)
	v_mfma_f32_16x16x32_bf16 v[72:75], v[176:179], v[184:187], v[72:75]
	v_pk_mul_f32 v[76:77], v[76:77], v[246:247] op_sel_hi:[1,0]
	v_pk_mul_f32 v[78:79], v[78:79], v[246:247] op_sel_hi:[1,0]
	v_mfma_f32_16x16x32_bf16 v[104:107], v[176:179], v[188:191], v[104:107]
	v_pk_mul_f32 v[108:109], v[108:109], v[248:249] op_sel_hi:[1,0]
	v_pk_mul_f32 v[110:111], v[110:111], v[248:249] op_sel_hi:[1,0]
	s_waitcnt lgkmcnt(0)
	v_mfma_f32_16x16x32_bf16 v[76:79], v[180:183], v[184:187], v[76:79]
	v_mfma_f32_16x16x32_bf16 v[108:111], v[180:183], v[188:191], v[108:111]
	s_waitcnt lgkmcnt(0)
	s_barrier
; template <int DK>
; DI void dense_attn_item(LAS unsigned char* lds, const bf16_t* Qb, int ldq, const bf16_t* Kb, int ldk, const bf16_t* Kpe, const bf16_t* Vt, int nkeys, float sl2, bf16_t* Ob) {
;     ...
;     for (int kt = 0; kt < ntiles; ++kt) {
;         const int cur = kt & 1;
;         if (kt + 1 < ntiles) DA_LOAD((kt + 1) * 64);
;         const LAS unsigned char* kb_ = lds + cur * KTILE; const LAS unsigned char* vb_ = lds + 2 * KTILE + cur * VTILE;
; #pragma unroll
;         for (int kc = 0; kc < 2; ++kc) {
;             f32x4 sacc[2][2];
; #pragma unroll
;             for (int kb = 0; kb < 2; ++kb) {
;                 sacc[0][kb] = (f32x4){0.f, 0.f, 0.f, 0.f}; sacc[1][kb] = (f32x4){0.f, 0.f, 0.f, 0.f};
; #pragma unroll
;                 for (int kh = 0; kh < KS / 2; ++kh) {
;                     const bf16x8 k0 = *(const LAS bf16x8*)(kb_ + ((2 * kc + kb) * 16 + r16) * KROW + (2 * kh) * 64 + q4 * 16);
;                     const bf16x8 k1 = *(const LAS bf16x8*)(kb_ + ((2 * kc + kb) * 16 + r16) * KROW + (2 * kh + 1) * 64 + q4 * 16);
;                     __builtin_amdgcn_s_setprio(1);
;                     sacc[0][kb] = MFMA16(k0, qf[0][2 * kh], sacc[0][kb]); sacc[1][kb] = MFMA16(k0, qf[1][2 * kh], sacc[1][kb]);
;                     sacc[0][kb] = MFMA16(k1, qf[0][2 * kh + 1], sacc[0][kb]); sacc[1][kb] = MFMA16(k1, qf[1][2 * kh + 1], sacc[1][kb]);
;                     __builtin_amdgcn_s_setprio(0);
;                 }
;             }
;             bf16x8 pb[2];
; #pragma unroll
;             for (int qg = 0; qg < 2; ++qg) {
;                 float mx = fmaxf(fmaxf(fmaxf(sacc[qg][0][0], sacc[qg][0][1]), fmaxf(sacc[qg][0][2], sacc[qg][0][3])), fmaxf(fmaxf(sacc[qg][1][0], sacc[qg][1][1]), fmaxf(sacc[qg][1][2], sacc[qg][1][3])));
;                 mx = fmaxf(mx, __shfl_xor(mx, 16)); mx = fmaxf(mx, __shfl_xor(mx, 32));
;                 const float mnew = fmaxf(mrun[qg], mx * sl2), alpha = fast_exp2(mrun[qg] - mnew);
;                 mrun[qg] = mnew;
;                 float ps = 0.f;
; #pragma unroll
;                 for (int kb = 0; kb < 2; ++kb)
; #pragma unroll
;                     for (int j = 0; j < 4; ++j) { const float pv = fast_exp2(sacc[qg][kb][j] * sl2 - mnew); sacc[qg][kb][j] = pv; ps += pv; }
;                 lsum[qg] = lsum[qg] * alpha + ps;
; #pragma unroll
;                 for (int d = 0; d < 8; ++d) oacc[qg][d] *= alpha;
	ds_read_b128 v[144:147], v240 offset:0
	ds_read_b128 v[148:151], v240 offset:64
	ds_read_b128 v[152:155], v240 offset:128
	ds_read_b128 v[156:159], v240 offset:192
	ds_read_b128 v[160:163], v240 offset:256
	ds_read_b128 v[164:167], v240 offset:320
	v_max3_f32 v192, v128, v129, v130
	v_max3_f32 v194, v136, v137, v138
	v_max3_f32 v193, v131, v132, v133
	v_max3_f32 v195, v139, v140, v141
	v_max3_f32 v192, v192, v134, v135
	v_max3_f32 v194, v194, v142, v143
	v_max_f32_e32 v192, v192, v193
	v_max_f32_e32 v194, v194, v195
	v_mov_b32_e32 v193, v192
	v_mov_b32_e32 v195, v194
	s_nop 1
	v_permlane16_swap_b32_e32 v192, v193
	s_waitcnt lgkmcnt(5)
	v_mfma_f32_16x16x32_bf16 v[112:115], v[144:147], v[0:3], 0
	v_permlane16_swap_b32_e32 v194, v195
	v_max_f32_e32 v192, v192, v193
	v_max_f32_e32 v194, v194, v195
	v_mfma_f32_16x16x32_bf16 v[120:123], v[144:147], v[24:27], 0
	v_mov_b32_e32 v193, v192
	v_mov_b32_e32 v195, v194
	s_nop 1
	ds_read_b128 v[144:147], v240 offset:6400
	s_waitcnt lgkmcnt(5)
	v_mfma_f32_16x16x32_bf16 v[112:115], v[148:151], v[4:7], v[112:115]
	v_permlane32_swap_b32_e32 v192, v193
	v_permlane32_swap_b32_e32 v194, v195
	v_max_f32_e32 v192, v192, v193
	v_mfma_f32_16x16x32_bf16 v[120:123], v[148:151], v[28:31], v[120:123]
	v_max_f32_e32 v194, v194, v195
	v_mul_f32_e32 v192, s22, v192
	v_mul_f32_e32 v194, s22, v194
	ds_read_b128 v[148:151], v240 offset:6464
	s_waitcnt lgkmcnt(5)
	v_mfma_f32_16x16x32_bf16 v[112:115], v[152:155], v[8:11], v[112:115]
	v_max_f32_e32 v193, v242, v192
	v_max_f32_e32 v195, v243, v194
	v_sub_f32_e32 v192, v242, v193
	v_mfma_f32_16x16x32_bf16 v[120:123], v[152:155], v[32:35], v[120:123]
	v_sub_f32_e32 v194, v243, v195
	v_exp_f32_e32 v246, v192
	v_exp_f32_e32 v248, v194
	ds_read_b128 v[152:155], v240 offset:6528
	s_waitcnt lgkmcnt(5)
	v_mfma_f32_16x16x32_bf16 v[112:115], v[156:159], v[12:15], v[112:115]
	v_mov_b32_e32 v242, v193
	v_mov_b32_e32 v243, v195
	v_fma_f32 v128, v128, s22, -v193
	v_mfma_f32_16x16x32_bf16 v[120:123], v[156:159], v[36:39], v[120:123]
	v_fma_f32 v136, v136, s22, -v195
	v_fma_f32 v129, v129, s22, -v193
	v_fma_f32 v137, v137, s22, -v195
	ds_read_b128 v[156:159], v240 offset:6592
	s_waitcnt lgkmcnt(5)
	v_mfma_f32_16x16x32_bf16 v[112:115], v[160:163], v[16:19], v[112:115]
	v_fma_f32 v130, v130, s22, -v193
	v_fma_f32 v138, v138, s22, -v195
	v_fma_f32 v131, v131, s22, -v193
	v_mfma_f32_16x16x32_bf16 v[120:123], v[160:163], v[40:43], v[120:123]
	v_fma_f32 v139, v139, s22, -v195
	v_fma_f32 v132, v132, s22, -v193
	v_fma_f32 v140, v140, s22, -v195
	ds_read_b128 v[160:163], v240 offset:6656
	s_waitcnt lgkmcnt(5)
	v_mfma_f32_16x16x32_bf16 v[112:115], v[164:167], v[20:23], v[112:115]
	v_fma_f32 v133, v133, s22, -v193
	v_fma_f32 v141, v141, s22, -v195
	v_fma_f32 v134, v134, s22, -v193
	v_mfma_f32_16x16x32_bf16 v[120:123], v[164:167], v[44:47], v[120:123]
	v_fma_f32 v142, v142, s22, -v195
	v_fma_f32 v135, v135, s22, -v193
	v_fma_f32 v143, v143, s22, -v195
	ds_read_b128 v[164:167], v240 offset:6720
	s_waitcnt lgkmcnt(5)
	v_mfma_f32_16x16x32_bf16 v[116:119], v[144:147], v[0:3], 0
	v_exp_f32_e32 v128, v128
	v_exp_f32_e32 v136, v136
	v_exp_f32_e32 v129, v129
	v_mfma_f32_16x16x32_bf16 v[124:127], v[144:147], v[24:27], 0
	v_exp_f32_e32 v137, v137
	v_exp_f32_e32 v130, v130
	v_exp_f32_e32 v138, v138
	ds_read_b64 v[168:169], v241 offset:64
	ds_read_b64 v[170:171], v241 offset:96
	s_waitcnt lgkmcnt(6)
	v_mfma_f32_16x16x32_bf16 v[116:119], v[148:151], v[4:7], v[116:119]
	v_exp_f32_e32 v131, v131
	v_exp_f32_e32 v139, v139
	v_exp_f32_e32 v132, v132
	v_mfma_f32_16x16x32_bf16 v[124:127], v[148:151], v[28:31], v[124:127]
	v_exp_f32_e32 v140, v140
	v_exp_f32_e32 v133, v133
	v_exp_f32_e32 v141, v141
	ds_read_b64 v[172:173], v241 offset:2368
	ds_read_b64 v[174:175], v241 offset:2400
	s_waitcnt lgkmcnt(7)
	v_mfma_f32_16x16x32_bf16 v[116:119], v[152:155], v[8:11], v[116:119]
	v_exp_f32_e32 v134, v134
	v_exp_f32_e32 v142, v142
	v_exp_f32_e32 v135, v135
	v_mfma_f32_16x16x32_bf16 v[124:127], v[152:155], v[32:35], v[124:127]
	v_exp_f32_e32 v143, v143
	v_add_f32_e32 v192, v128, v129
	v_add_f32_e32 v194, v136, v137
	ds_read_b64 v[176:177], v241 offset:4672
	ds_read_b64 v[178:179], v241 offset:4704
	s_waitcnt lgkmcnt(8)
	v_mfma_f32_16x16x32_bf16 v[116:119], v[156:159], v[12:15], v[116:119]
	v_add_f32_e32 v192, v192, v130
	v_add_f32_e32 v194, v194, v138
	v_add_f32_e32 v192, v192, v131
	v_mfma_f32_16x16x32_bf16 v[124:127], v[156:159], v[36:39], v[124:127]
	v_add_f32_e32 v194, v194, v139
	v_add_f32_e32 v192, v192, v132
	v_add_f32_e32 v194, v194, v140
	ds_read_b64 v[180:181], v241 offset:6976
	ds_read_b64 v[182:183], v241 offset:7008
	s_waitcnt lgkmcnt(9)
	v_mfma_f32_16x16x32_bf16 v[116:119], v[160:163], v[16:19], v[116:119]
	v_add_f32_e32 v192, v192, v133
	v_add_f32_e32 v194, v194, v141
	v_add_f32_e32 v192, v192, v134
	v_mfma_f32_16x16x32_bf16 v[124:127], v[160:163], v[40:43], v[124:127]
	v_add_f32_e32 v194, v194, v142
	v_add_f32_e32 v192, v192, v135
	v_add_f32_e32 v194, v194, v143
	s_waitcnt lgkmcnt(8)
	v_mfma_f32_16x16x32_bf16 v[116:119], v[164:167], v[20:23], v[116:119]
	v_fma_f32 v244, v244, v246, v192
	v_fma_f32 v245, v245, v248, v194
	v_cvt_pk_bf16_f32 v184, v128, v129
	v_mfma_f32_16x16x32_bf16 v[124:127], v[164:167], v[44:47], v[124:127]
	v_cvt_pk_bf16_f32 v188, v136, v137
	v_cvt_pk_bf16_f32 v185, v130, v131
	v_cvt_pk_bf16_f32 v189, v138, v139
	v_cvt_pk_bf16_f32 v186, v132, v133
	v_cvt_pk_bf16_f32 v190, v140, v141
	v_cvt_pk_bf16_f32 v187, v134, v135
	v_cvt_pk_bf16_f32 v191, v142, v143
	v_pk_mul_f32 v[48:49], v[48:49], v[246:247] op_sel_hi:[1,0]
	v_pk_mul_f32 v[50:51], v[50:51], v[246:247] op_sel_hi:[1,0]
	v_pk_mul_f32 v[80:81], v[80:81], v[248:249] op_sel_hi:[1,0]
	v_pk_mul_f32 v[82:83], v[82:83], v[248:249] op_sel_hi:[1,0]
	s_waitcnt lgkmcnt(6)
; #define LAS __attribute__((address_space(3)))
; #define MFMA16(a, b, c) __builtin_amdgcn_mfma_f32_16x16x32_bf16((a), (b), (c), 0, 0, 0)
; template <int DK>
; DI void dense_attn_item(LAS unsigned char* lds, const bf16_t* Qb, int ldq, const bf16_t* Kb, int ldk, const bf16_t* Kpe, const bf16_t* Vt, int nkeys, float sl2, bf16_t* Ob) {
;     ...
; #pragma unroll
;             for (int dh = 0; dh < 4; ++dh) {
;                 bf16x8 vfr[2];
; #pragma unroll
;                 for (int d4 = 0; d4 < 2; ++d4) {
;                     const int d = dh * 2 + d4;
;                     const u32x2 lo = *(const LAS u32x2*)(vb_ + (d * 16 + r16) * VROW + (kc * 32 + q4 * 4) * 2);
;                     const u32x2 hi = *(const LAS u32x2*)(vb_ + (d * 16 + r16) * VROW + (kc * 32 + 16 + q4 * 4) * 2);
;                     u32x4 w; w.x = lo.x; w.y = lo.y; w.z = hi.x; w.w = hi.y;
;                     vfr[d4] = __builtin_bit_cast(bf16x8, w);
;                 }
;                 __builtin_amdgcn_s_setprio(1);
; #pragma unroll
;                 for (int d4 = 0; d4 < 2; ++d4) { const int d = dh * 2 + d4; oacc[0][d] = MFMA16(vfr[d4], pb[0], oacc[0][d]); oacc[1][d] = MFMA16(vfr[d4], pb[1], oacc[1][d]); }
;                 __builtin_amdgcn_s_setprio(0);
;             }
;         }
;         if (kt + 1 < ntiles) DA_STORE(cur ^ 1);
;         __syncthreads();
;     }
	v_mfma_f32_16x16x32_bf16 v[48:51], v[168:171], v[184:187], v[48:51]
	v_pk_mul_f32 v[52:53], v[52:53], v[246:247] op_sel_hi:[1,0]
	v_pk_mul_f32 v[54:55], v[54:55], v[246:247] op_sel_hi:[1,0]
	v_mfma_f32_16x16x32_bf16 v[80:83], v[168:171], v[188:191], v[80:83]
	v_pk_mul_f32 v[84:85], v[84:85], v[248:249] op_sel_hi:[1,0]
	v_pk_mul_f32 v[86:87], v[86:87], v[248:249] op_sel_hi:[1,0]
	ds_read_b64 v[168:169], v241 offset:9280
	ds_read_b64 v[170:171], v241 offset:9312
	s_waitcnt lgkmcnt(6)
	v_mfma_f32_16x16x32_bf16 v[52:55], v[172:175], v[184:187], v[52:55]
	v_pk_mul_f32 v[56:57], v[56:57], v[246:247] op_sel_hi:[1,0]
	v_pk_mul_f32 v[58:59], v[58:59], v[246:247] op_sel_hi:[1,0]
	v_mfma_f32_16x16x32_bf16 v[84:87], v[172:175], v[188:191], v[84:87]
	v_pk_mul_f32 v[88:89], v[88:89], v[248:249] op_sel_hi:[1,0]
	v_pk_mul_f32 v[90:91], v[90:91], v[248:249] op_sel_hi:[1,0]
	ds_read_b64 v[172:173], v241 offset:11584
	ds_read_b64 v[174:175], v241 offset:11616
	s_waitcnt lgkmcnt(6)
	v_mfma_f32_16x16x32_bf16 v[56:59], v[176:179], v[184:187], v[56:59]
	v_pk_mul_f32 v[60:61], v[60:61], v[246:247] op_sel_hi:[1,0]
	v_pk_mul_f32 v[62:63], v[62:63], v[246:247] op_sel_hi:[1,0]
	v_mfma_f32_16x16x32_bf16 v[88:91], v[176:179], v[188:191], v[88:91]
	v_pk_mul_f32 v[92:93], v[92:93], v[248:249] op_sel_hi:[1,0]
	v_pk_mul_f32 v[94:95], v[94:95], v[248:249] op_sel_hi:[1,0]
	ds_read_b64 v[176:177], v241 offset:13888
	ds_read_b64 v[178:179], v241 offset:13920
	s_waitcnt lgkmcnt(6)
	v_mfma_f32_16x16x32_bf16 v[60:63], v[180:183], v[184:187], v[60:63]
	v_pk_mul_f32 v[64:65], v[64:65], v[246:247] op_sel_hi:[1,0]
	v_pk_mul_f32 v[66:67], v[66:67], v[246:247] op_sel_hi:[1,0]
	v_mfma_f32_16x16x32_bf16 v[92:95], v[180:183], v[188:191], v[92:95]
	v_pk_mul_f32 v[96:97], v[96:97], v[248:249] op_sel_hi:[1,0]
	v_pk_mul_f32 v[98:99], v[98:99], v[248:249] op_sel_hi:[1,0]
	ds_read_b64 v[180:181], v241 offset:16192
	ds_read_b64 v[182:183], v241 offset:16224
	s_waitcnt lgkmcnt(6)
	v_mfma_f32_16x16x32_bf16 v[64:67], v[168:171], v[184:187], v[64:67]
	v_pk_mul_f32 v[68:69], v[68:69], v[246:247] op_sel_hi:[1,0]
	v_pk_mul_f32 v[70:71], v[70:71], v[246:247] op_sel_hi:[1,0]
	v_mfma_f32_16x16x32_bf16 v[96:99], v[168:171], v[188:191], v[96:99]
	v_pk_mul_f32 v[100:101], v[100:101], v[248:249] op_sel_hi:[1,0]
	v_pk_mul_f32 v[102:103], v[102:103], v[248:249] op_sel_hi:[1,0]
	s_waitcnt lgkmcnt(4)
	v_mfma_f32_16x16x32_bf16 v[68:71], v[172:175], v[184:187], v[68:71]
	v_pk_mul_f32 v[72:73], v[72:73], v[246:247] op_sel_hi:[1,0]
	v_pk_mul_f32 v[74:75], v[74:75], v[246:247] op_sel_hi:[1,0]
	v_mfma_f32_16x16x32_bf16 v[100:103], v[172:175], v[188:191], v[100:103]
	v_pk_mul_f32 v[104:105], v[104:105], v[248:249] op_sel_hi:[1,0]
	v_pk_mul_f32 v[106:107], v[106:107], v[248:249] op_sel_hi:[1,0]
	s_waitcnt lgkmcnt(2)
	v_mfma_f32_16x16x32_bf16 v[72:75], v[176:179], v[184:187], v[72:75]
	v_pk_mul_f32 v[76:77], v[76:77], v[246:247] op_sel_hi:[1,0]
	v_pk_mul_f32 v[78:79], v[78:79], v[246:247] op_sel_hi:[1,0]
	v_mfma_f32_16x16x32_bf16 v[104:107], v[176:179], v[188:191], v[104:107]
	v_pk_mul_f32 v[108:109], v[108:109], v[248:249] op_sel_hi:[1,0]
	v_pk_mul_f32 v[110:111], v[110:111], v[248:249] op_sel_hi:[1,0]
	s_waitcnt lgkmcnt(0)
	v_mfma_f32_16x16x32_bf16 v[76:79], v[180:183], v[184:187], v[76:79]
	v_mfma_f32_16x16x32_bf16 v[108:111], v[180:183], v[188:191], v[108:111]
	s_mov_b32 s27, s57
	s_add_u32 s23, s23, 1
	s_cmp_lt_u32 s23, 36
	s_cbranch_scc1 dn1_top
; DI void st_bf16x4(bf16_t* p, f32x4 v) { u32x2 w; w.x = cvt_pk_bf16(v[0], v[1]); w.y = cvt_pk_bf16(v[2], v[3]); *(u32x2*)p = w; }
; template <int DK>
; DI void dense_attn_item(LAS unsigned char* lds, const bf16_t* Qb, int ldq, const bf16_t* Kb, int ldk, const bf16_t* Kpe, const bf16_t* Vt, int nkeys, float sl2, bf16_t* Ob) {
;     ...
; #pragma unroll
;     for (int qg = 0; qg < 2; ++qg) {
;         float l = lsum[qg]; l += __shfl_xor(l, 16); l += __shfl_xor(l, 32);
;         const float inv = 1.f / l;
;         bf16_t* op = Ob + (size_t)(wid * 32 + qg * 16 + r16) * DM + q4 * 4;
; #pragma unroll
;         for (int d = 0; d < 8; ++d) st_bf16x4(op + d * 16, oacc[qg][d] * inv);
;     }
	s_waitcnt vmcnt(0) lgkmcnt(0)
	v_mov_b32_e32 v192, v244
	v_mov_b32_e32 v193, v244
	v_mov_b32_e32 v194, v245
	v_mov_b32_e32 v195, v245
	s_nop 1
	v_permlane16_swap_b32_e32 v192, v193
	v_permlane16_swap_b32_e32 v194, v195
	v_add_f32_e32 v192, v192, v193
	v_add_f32_e32 v194, v194, v195
	v_mov_b32_e32 v193, v192
	v_mov_b32_e32 v195, v194
	s_nop 1
	v_permlane32_swap_b32_e32 v192, v193
	v_permlane32_swap_b32_e32 v194, v195
	v_add_f32_e32 v192, v192, v193
	v_add_f32_e32 v194, v194, v195
	v_rcp_f32_e32 v193, v192
	v_rcp_f32_e32 v195, v194
	s_nop 0
	v_fma_f32 v192, -v192, v193, 1.0
	v_fma_f32 v194, -v194, v195, 1.0
	v_fma_f32 v246, v192, v193, v193
	v_fma_f32 v248, v194, v195, v195
	v_pk_mul_f32 v[48:49], v[48:49], v[246:247] op_sel_hi:[1,0]
	v_pk_mul_f32 v[50:51], v[50:51], v[246:247] op_sel_hi:[1,0]
	v_cvt_pk_bf16_f32 v48, v48, v49
	v_cvt_pk_bf16_f32 v49, v50, v51
	global_store_dwordx2 v250, v[48:49], s[20:21] offset:0
	v_pk_mul_f32 v[52:53], v[52:53], v[246:247] op_sel_hi:[1,0]
	v_pk_mul_f32 v[54:55], v[54:55], v[246:247] op_sel_hi:[1,0]
	v_cvt_pk_bf16_f32 v52, v52, v53
	v_cvt_pk_bf16_f32 v53, v54, v55
	global_store_dwordx2 v250, v[52:53], s[20:21] offset:32
	v_pk_mul_f32 v[56:57], v[56:57], v[246:247] op_sel_hi:[1,0]
	v_pk_mul_f32 v[58:59], v[58:59], v[246:247] op_sel_hi:[1,0]
	v_cvt_pk_bf16_f32 v56, v56, v57
	v_cvt_pk_bf16_f32 v57, v58, v59
	global_store_dwordx2 v250, v[56:57], s[20:21] offset:64
	v_pk_mul_f32 v[60:61], v[60:61], v[246:247] op_sel_hi:[1,0]
	v_pk_mul_f32 v[62:63], v[62:63], v[246:247] op_sel_hi:[1,0]
	v_cvt_pk_bf16_f32 v60, v60, v61
	v_cvt_pk_bf16_f32 v61, v62, v63
	global_store_dwordx2 v250, v[60:61], s[20:21] offset:96
	v_pk_mul_f32 v[64:65], v[64:65], v[246:247] op_sel_hi:[1,0]
	v_pk_mul_f32 v[66:67], v[66:67], v[246:247] op_sel_hi:[1,0]
	v_cvt_pk_bf16_f32 v64, v64, v65
	v_cvt_pk_bf16_f32 v65, v66, v67
	global_store_dwordx2 v250, v[64:65], s[20:21] offset:128
	v_pk_mul_f32 v[68:69], v[68:69], v[246:247] op_sel_hi:[1,0]
	v_pk_mul_f32 v[70:71], v[70:71], v[246:247] op_sel_hi:[1,0]
	v_cvt_pk_bf16_f32 v68, v68, v69
	v_cvt_pk_bf16_f32 v69, v70, v71
	global_store_dwordx2 v250, v[68:69], s[20:21] offset:160
	v_pk_mul_f32 v[72:73], v[72:73], v[246:247] op_sel_hi:[1,0]
	v_pk_mul_f32 v[74:75], v[74:75], v[246:247] op_sel_hi:[1,0]
	v_cvt_pk_bf16_f32 v72, v72, v73
	v_cvt_pk_bf16_f32 v73, v74, v75
	global_store_dwordx2 v250, v[72:73], s[20:21] offset:192
	v_pk_mul_f32 v[76:77], v[76:77], v[246:247] op_sel_hi:[1,0]
	v_pk_mul_f32 v[78:79], v[78:79], v[246:247] op_sel_hi:[1,0]
	v_cvt_pk_bf16_f32 v76, v76, v77
	v_cvt_pk_bf16_f32 v77, v78, v79
	global_store_dwordx2 v250, v[76:77], s[20:21] offset:224
	v_pk_mul_f32 v[80:81], v[80:81], v[248:249] op_sel_hi:[1,0]
	v_pk_mul_f32 v[82:83], v[82:83], v[248:249] op_sel_hi:[1,0]
	v_cvt_pk_bf16_f32 v80, v80, v81
	v_cvt_pk_bf16_f32 v81, v82, v83
	global_store_dwordx2 v251, v[80:81], s[20:21] offset:0
	v_pk_mul_f32 v[84:85], v[84:85], v[248:249] op_sel_hi:[1,0]
	v_pk_mul_f32 v[86:87], v[86:87], v[248:249] op_sel_hi:[1,0]
	v_cvt_pk_bf16_f32 v84, v84, v85
	v_cvt_pk_bf16_f32 v85, v86, v87
	global_store_dwordx2 v251, v[84:85], s[20:21] offset:32
	v_pk_mul_f32 v[88:89], v[88:89], v[248:249] op_sel_hi:[1,0]
	v_pk_mul_f32 v[90:91], v[90:91], v[248:249] op_sel_hi:[1,0]
	v_cvt_pk_bf16_f32 v88, v88, v89
	v_cvt_pk_bf16_f32 v89, v90, v91
	global_store_dwordx2 v251, v[88:89], s[20:21] offset:64
	v_pk_mul_f32 v[92:93], v[92:93], v[248:249] op_sel_hi:[1,0]
	v_pk_mul_f32 v[94:95], v[94:95], v[248:249] op_sel_hi:[1,0]
	v_cvt_pk_bf16_f32 v92, v92, v93
	v_cvt_pk_bf16_f32 v93, v94, v95
	global_store_dwordx2 v251, v[92:93], s[20:21] offset:96
	v_pk_mul_f32 v[96:97], v[96:97], v[248:249] op_sel_hi:[1,0]
	v_pk_mul_f32 v[98:99], v[98:99], v[248:249] op_sel_hi:[1,0]
	v_cvt_pk_bf16_f32 v96, v96, v97
	v_cvt_pk_bf16_f32 v97, v98, v99
	global_store_dwordx2 v251, v[96:97], s[20:21] offset:128
	v_pk_mul_f32 v[100:101], v[100:101], v[248:249] op_sel_hi:[1,0]
	v_pk_mul_f32 v[102:103], v[102:103], v[248:249] op_sel_hi:[1,0]
	v_cvt_pk_bf16_f32 v100, v100, v101
	v_cvt_pk_bf16_f32 v101, v102, v103
	global_store_dwordx2 v251, v[100:101], s[20:21] offset:160
	v_pk_mul_f32 v[104:105], v[104:105], v[248:249] op_sel_hi:[1,0]
	v_pk_mul_f32 v[106:107], v[106:107], v[248:249] op_sel_hi:[1,0]
	v_cvt_pk_bf16_f32 v104, v104, v105
	v_cvt_pk_bf16_f32 v105, v106, v107
	global_store_dwordx2 v251, v[104:105], s[20:21] offset:192
	v_pk_mul_f32 v[108:109], v[108:109], v[248:249] op_sel_hi:[1,0]
	v_pk_mul_f32 v[110:111], v[110:111], v[248:249] op_sel_hi:[1,0]
	v_cvt_pk_bf16_f32 v108, v108, v109
	v_cvt_pk_bf16_f32 v109, v110, v111
	global_store_dwordx2 v251, v[108:109], s[20:21] offset:224
	v_mov_b32_e32 v133, 0
	s_waitcnt vmcnt(0)
	s_barrier
	s_and_saveexec_b64 s[0:1], s[24:25]
	s_cbranch_execz .LBB0_2592
	s_mov_b64 s[4:5], exec
	v_mbcnt_lo_u32_b32 v0, s4, 0
	v_mbcnt_hi_u32_b32 v0, s5, v0
	v_cmp_eq_u32_e32 vcc, 0, v0
	s_and_saveexec_b64 s[2:3], vcc
	s_cbranch_execz .LBB0_2591
	s_bcnt1_i32_b64 s4, s[4:5]
	v_mov_b32_e32 v1, s4
	global_atomic_add v1, v133, v1, s[34:35] sc0
	s_branch .LBB0_2591

; #define LAS __attribute__((address_space(3)))
; DI void na_block_item(const Params& p, int l, int b, int h, int rp, LAS unsigned char* lds) {
;     const int tid = otid(), lane = tid & 63, wid = tid >> 6, r16 = lane & 15, q4 = lane >> 4;
;     unsigned char* ws = p.ws;
;     const bf16_t* P = (const bf16_t*)(ws + WS_P);
;     constexpr int KROW = 272, KTILE = 64 * KROW, VROW = 144, VTILE = 128 * VROW;
;     const int gr = 2 * rp + (wid >> 2), jq = wid & 3;
;     const int gc = jq * 16 + r16, r0w = min(max(gr - 4, 0), 24), band = min(max(jq * 16 - 8, 0), 32), cs = min(max(gc - 8, 0), 48);
;     const int r0a = min(max(2 * rp - 4, 0), 24), r0b = min(max(2 * rp - 3, 0), 24), nloc = r0b + 8 - r0a, ntl = nloc + 4;
;     const size_t rowb = (size_t)b * RB, rowq = rowb + CL + gr * 64 + gc;
;     const float sl2 = 0.08838834764831845f * 1.4426950408889634f;
;     const float* rpb = p.in[11] + (size_t)(l * 6 + h) * 15 * 31;
;     bf16x8 qf[4];
; #pragma unroll
;     for (int ks = 0; ks < 4; ++ks) qf[ks] = *(const bf16x8*)(P + rowq * INP + C_NAQ + h * 128 + ks * 32 + q4 * 8);
;     f32x4 oacc[8];
; #pragma unroll
;     for (int d = 0; d < 8; ++d) oacc[d] = (f32x4){0.f, 0.f, 0.f, 0.f};
;     float mrun = -1e30f, lsum = 0.f;
;     const bf16_t* kg = P + rowb * INP + C_NAK + h * 128;
;     const bf16_t* vg = (const bf16_t*)(ws + WS_VTNA) + ((size_t)b * 768 + h * 128) * RB;
;     u32x4 kstA[2], vstA[2], kstB[2], vstB[2];
;     ...
;     LAS float* s_rpb = (LAS float*)(lds + 3 * KTILE + 3 * VTILE);
;     if (tid < 465) s_rpb[tid] = rpb[tid];
;     NA_LOAD(0, kstA, vstA); NA_LOAD(1, kstB, vstB);
;     NA_STORE(0, kstA, vstA);
;     NA_LOAD(2, kstA, vstA);
;     __syncthreads();
;     for (int t = 0; t < ntl; ++t) {
;         const int cur = t % 3;
;         const bool local = t < nloc; const int kr = r0a + t;
;         const int nch = local ? ((kr >= r0w && kr < r0w + 8) ? 1 : 0) : 2;
;         for (int ci = 0; ci < nch; ++ci) {
;             const int toff = local ? band : ci * 32;
;             const LAS unsigned char* kb_ = lds + cur * KTILE + (toff + r16) * KROW + q4 * 16;
;             const LAS unsigned char* vb_ = lds + 3 * KTILE + cur * VTILE + r16 * VROW + (toff + q4 * 4) * 2;
;             float bias8[8];
;             if (local) {
;                 const LAS float* rp_ = s_rpb + (kr - gr + 7) * 31;
; #pragma unroll
.LBB0_2630:
	s_cmpk_gt_u32 s0, 0x35f
	s_cbranch_scc1 .LBB0_2681
	s_mov_b32 s29, s0
	s_mov_b32 s22, 0x3e0293ee
	s_mov_b32 s23, 0x3fb8aa3b
	v_and_b32_e32 v196, 15, v202
	v_bfe_u32 v197, v202, 4, 2
	v_lshrrev_b32_e32 v198, 6, v202
	s_nop 0
	v_readfirstlane_b32 s74, v198
	v_mov_b32_e32 v199, v202
	v_lshrrev_b32_e32 v200, 4, v199
	v_and_b32_e32 v201, 15, v199
	v_lshlrev_b32_e32 v201, 4, v201
	v_mul_u32_u24_e32 v230, 0x3000, v200
	v_add_u32_e32 v230, v230, v201
	v_mul_u32_u24_e32 v234, 0x110, v200
	v_add_u32_e32 v234, v234, v201
	v_lshrrev_b32_e32 v200, 3, v199
	v_and_b32_e32 v201, 7, v199
	v_lshlrev_b32_e32 v201, 4, v201
	v_mul_u32_u24_e32 v232, 0x1200, v200
	v_add_u32_e32 v232, v232, v201
	v_mul_u32_u24_e32 v236, 0x90, v200
	v_add_u32_e32 v236, v236, v201
	v_add_u32_e32 v236, 0xcc00, v236
	v_add_u32_e32 v199, 0x200, v202
	v_lshrrev_b32_e32 v200, 4, v199
	v_and_b32_e32 v201, 15, v199
	v_lshlrev_b32_e32 v201, 4, v201
	v_mul_u32_u24_e32 v231, 0x3000, v200
	v_add_u32_e32 v231, v231, v201
	v_mul_u32_u24_e32 v235, 0x110, v200
	v_add_u32_e32 v235, v235, v201
	v_lshrrev_b32_e32 v200, 3, v199
	v_and_b32_e32 v201, 7, v199
	v_lshlrev_b32_e32 v201, 4, v201
	v_mul_u32_u24_e32 v233, 0x1200, v200
	v_add_u32_e32 v233, v233, v201
	v_mul_u32_u24_e32 v237, 0x90, v200
	v_add_u32_e32 v237, v237, v201
	v_add_u32_e32 v237, 0xcc00, v237
	v_mul_u32_u24_e32 v199, 0x110, v196
	v_lshl_add_u32 v238, v197, 4, v199
	v_mul_u32_u24_e32 v199, 0x90, v196
	v_lshl_add_u32 v199, v197, 3, v199
	v_add_u32_e32 v239, 0xcc00, v199
	v_mul_u32_u24_e32 v199, 0x3000, v196
	v_lshl_add_u32 v251, v197, 4, v199
	v_lshlrev_b32_e32 v199, 12, v196
	v_lshl_add_u32 v246, v197, 3, v199
	s_and_b32 s73, s74, 3
	s_lshl_b32 s73, s73, 4
	s_sub_i32 s56, s73, 8
	s_max_i32 s56, s56, 0
	s_min_i32 s56, s56, 32
	v_add_u32_e32 v220, s73, v196
	v_subrev_u32_e32 v221, 8, v220
	v_max_i32_e32 v221, 0, v221
	v_min_i32_e32 v221, 48, v221
	v_add_u32_e32 v222, 16, v221
	v_lshlrev_b32_e32 v223, 2, v197
	v_mov_b32_e32 v224, 0xf149f2ca
	v_mov_b32_e32 v225, 0x7f7fffff
	s_add_u32 s57, s56, 0
	v_add_u32_e32 v199, s57, v223
	v_sub_u32_e32 v200, v199, v220
	v_add_u32_e32 v200, 15, v200
	v_max_i32_e32 v200, 0, v200
	v_min_i32_e32 v200, 30, v200
	v_lshlrev_b32_e32 v200, 2, v200
	v_add_u32_e32 v132, 0x1a400, v200
	v_cmp_ge_i32_e32 vcc, v199, v221
	v_cmp_lt_i32_e64 s[0:1], v199, v222
	s_and_b64 vcc, vcc, s[0:1]
	v_cndmask_b32_e32 v140, v224, v225, vcc
	s_add_u32 s57, s56, 1
	v_add_u32_e32 v199, s57, v223
	v_sub_u32_e32 v200, v199, v220
	v_add_u32_e32 v200, 15, v200
	v_max_i32_e32 v200, 0, v200
	v_min_i32_e32 v200, 30, v200
	v_lshlrev_b32_e32 v200, 2, v200
	v_add_u32_e32 v133, 0x1a400, v200
	v_cmp_ge_i32_e32 vcc, v199, v221
	v_cmp_lt_i32_e64 s[0:1], v199, v222
	s_and_b64 vcc, vcc, s[0:1]
	v_cndmask_b32_e32 v141, v224, v225, vcc
	s_add_u32 s57, s56, 2
	v_add_u32_e32 v199, s57, v223
	v_sub_u32_e32 v200, v199, v220
	v_add_u32_e32 v200, 15, v200
	v_max_i32_e32 v200, 0, v200
	v_min_i32_e32 v200, 30, v200
	v_lshlrev_b32_e32 v200, 2, v200
	v_add_u32_e32 v134, 0x1a400, v200
	v_cmp_ge_i32_e32 vcc, v199, v221
	v_cmp_lt_i32_e64 s[0:1], v199, v222
	s_and_b64 vcc, vcc, s[0:1]
	v_cndmask_b32_e32 v142, v224, v225, vcc
	s_add_u32 s57, s56, 3
	v_add_u32_e32 v199, s57, v223
	v_sub_u32_e32 v200, v199, v220
	v_add_u32_e32 v200, 15, v200
	v_max_i32_e32 v200, 0, v200
	v_min_i32_e32 v200, 30, v200
	v_lshlrev_b32_e32 v200, 2, v200
	v_add_u32_e32 v135, 0x1a400, v200
	v_cmp_ge_i32_e32 vcc, v199, v221
	v_cmp_lt_i32_e64 s[0:1], v199, v222
	s_and_b64 vcc, vcc, s[0:1]
	v_cndmask_b32_e32 v143, v224, v225, vcc
	s_add_u32 s57, s56, 16
	v_add_u32_e32 v199, s57, v223
	v_sub_u32_e32 v200, v199, v220
	v_add_u32_e32 v200, 15, v200
	v_max_i32_e32 v200, 0, v200
	v_min_i32_e32 v200, 30, v200
	v_lshlrev_b32_e32 v200, 2, v200
	v_add_u32_e32 v136, 0x1a400, v200
	v_cmp_ge_i32_e32 vcc, v199, v221
	v_cmp_lt_i32_e64 s[0:1], v199, v222
	s_and_b64 vcc, vcc, s[0:1]
	v_cndmask_b32_e32 v144, v224, v225, vcc
	s_add_u32 s57, s56, 17
	v_add_u32_e32 v199, s57, v223
	v_sub_u32_e32 v200, v199, v220
	v_add_u32_e32 v200, 15, v200
	v_max_i32_e32 v200, 0, v200
	v_min_i32_e32 v200, 30, v200
	v_lshlrev_b32_e32 v200, 2, v200
	v_add_u32_e32 v137, 0x1a400, v200
	v_cmp_ge_i32_e32 vcc, v199, v221
	v_cmp_lt_i32_e64 s[0:1], v199, v222
	s_and_b64 vcc, vcc, s[0:1]
	v_cndmask_b32_e32 v145, v224, v225, vcc
	s_add_u32 s57, s56, 18
	v_add_u32_e32 v199, s57, v223
	v_sub_u32_e32 v200, v199, v220
	v_add_u32_e32 v200, 15, v200
	v_max_i32_e32 v200, 0, v200
	v_min_i32_e32 v200, 30, v200
	v_lshlrev_b32_e32 v200, 2, v200
	v_add_u32_e32 v138, 0x1a400, v200
	v_cmp_ge_i32_e32 vcc, v199, v221
	v_cmp_lt_i32_e64 s[0:1], v199, v222
	s_and_b64 vcc, vcc, s[0:1]
	v_cndmask_b32_e32 v146, v224, v225, vcc
	s_add_u32 s57, s56, 19
	v_add_u32_e32 v199, s57, v223
	v_sub_u32_e32 v200, v199, v220
	v_add_u32_e32 v200, 15, v200
	v_max_i32_e32 v200, 0, v200
	v_min_i32_e32 v200, 30, v200
	v_lshlrev_b32_e32 v200, 2, v200
	v_add_u32_e32 v139, 0x1a400, v200
	v_cmp_ge_i32_e32 vcc, v199, v221
	v_cmp_lt_i32_e64 s[0:1], v199, v222
	s_and_b64 vcc, vcc, s[0:1]
	v_cndmask_b32_e32 v147, v224, v225, vcc
	v_readlane_b32 s10, v255, 62
	v_readlane_b32 s11, v255, 63
	s_nop 4
	s_load_dwordx2 s[100:101], s[10:11], 0x58
	s_waitcnt lgkmcnt(0)
	v_writelane_b32 v254, s100, 0
	v_writelane_b32 v254, s101, 1
	v_writelane_b32 v254, s74, 2
; #define LAS __attribute__((address_space(3)))
; #define NA_LOAD(t, ks_, vs_) do { const int tb_ = NA_TB(t); \
;         _Pragma("unroll") for (int i = 0; i < 2; ++i) { const int cid = tid + i * 512; \
;             ks_[i] = *(const u32x4*)(kg + (size_t)(tb_ + (cid >> 4)) * INP + (cid & 15) * 8); \
;             vs_[i] = *(const u32x4*)(vg + (size_t)(cid >> 3) * RB + tb_ + (cid & 7) * 8); } } while (0)
; #define NA_STORE(buf, ks_, vs_) do { \
;         _Pragma("unroll") for (int i = 0; i < 2; ++i) { const int cid = tid + i * 512; \
;             *(LAS u32x4*)(lds + (buf) * KTILE + (cid >> 4) * KROW + (cid & 15) * 16) = ks_[i]; \
;             *(LAS u32x4*)(lds + 3 * KTILE + (buf) * VTILE + (cid >> 3) * VROW + (cid & 7) * 16) = vs_[i]; } } while (0)
; DI void na_block_item(const Params& p, int l, int b, int h, int rp, LAS unsigned char* lds) {
;     ...
;     const int gr = 2 * rp + (wid >> 2), jq = wid & 3;
;     const int gc = jq * 16 + r16, r0w = min(max(gr - 4, 0), 24), band = min(max(jq * 16 - 8, 0), 32), cs = min(max(gc - 8, 0), 48);
;     const int r0a = min(max(2 * rp - 4, 0), 24), r0b = min(max(2 * rp - 3, 0), 24), nloc = r0b + 8 - r0a, ntl = nloc + 4;
;     const size_t rowb = (size_t)b * RB, rowq = rowb + CL + gr * 64 + gc;
;     const float sl2 = 0.08838834764831845f * 1.4426950408889634f;
;     const float* rpb = p.in[11] + (size_t)(l * 6 + h) * 15 * 31;
;     bf16x8 qf[4];
; #pragma unroll
;     for (int ks = 0; ks < 4; ++ks) qf[ks] = *(const bf16x8*)(P + rowq * INP + C_NAQ + h * 128 + ks * 32 + q4 * 8);
;     f32x4 oacc[8];
; #pragma unroll
;     for (int d = 0; d < 8; ++d) oacc[d] = (f32x4){0.f, 0.f, 0.f, 0.f};
;     float mrun = -1e30f, lsum = 0.f;
;     const bf16_t* kg = P + rowb * INP + C_NAK + h * 128;
;     const bf16_t* vg = (const bf16_t*)(ws + WS_VTNA) + ((size_t)b * 768 + h * 128) * RB;
;     u32x4 kstA[2], vstA[2], kstB[2], vstB[2];
;     ...
;     LAS float* s_rpb = (LAS float*)(lds + 3 * KTILE + 3 * VTILE);
;     if (tid < 465) s_rpb[tid] = rpb[tid];
;     NA_LOAD(0, kstA, vstA); NA_LOAD(1, kstB, vstB);
;     NA_STORE(0, kstA, vstA);
;     NA_LOAD(2, kstA, vstA);
;     __syncthreads();
na1_item:
	s_sub_u32 s57, s29, 0x1e0
	s_and_b32 s101, s57, 15
	s_lshr_b32 s57, s57, 4
	s_mul_i32 s99, s57, 43
	s_lshr_b32 s99, s99, 8
	s_mul_i32 s63, s99, 6
	s_sub_u32 s98, s57, s63
	s_lshl_b32 s57, s101, 1
	s_sub_i32 s36, s57, 4
	s_max_i32 s36, s36, 0
	s_min_i32 s36, s36, 24
	s_sub_i32 s63, s57, 3
	s_max_i32 s63, s63, 0
	s_min_i32 s63, s63, 24
	s_sub_u32 s30, s63, s36
	s_add_u32 s30, s30, 8
	s_add_u32 s31, s30, 4
	v_readlane_b32 s74, v254, 2
	s_lshr_b32 s63, s74, 2
	s_add_u32 s37, s57, s63
	s_sub_i32 s54, s37, 4
	s_max_i32 s54, s54, 0
	s_min_i32 s54, s54, 24
	s_mul_i32 s68, s99, 0x900
	s_mul_i32 s57, s68, 0x3000
	s_lshl_b32 s63, s98, 8
	s_add_u32 s57, s57, s63
	s_add_u32 s57, s57, 0x113a0600
	s_add_u32 s2, s50, s57
	s_addc_u32 s3, s51, 0
	s_mul_i32 s57, s99, 0x300
	s_lshl_b32 s69, s98, 7
	s_add_u32 s57, s57, s69
	s_mul_i32 s57, s57, 0x1200
	s_add_u32 s57, s57, 0x17fa0000
	s_add_u32 s4, s50, s57
	s_addc_u32 s5, s51, 0
	s_and_b32 s69, s74, 3
	s_lshl_b32 s69, s69, 4
	s_lshl_b32 s70, s37, 6
	s_add_u32 s69, s69, s70
	s_add_u32 s69, s69, s68
	s_addk_i32 s69, 0x100
	s_mul_i32 s57, s69, 0x3000
	s_add_u32 s57, s57, s63
	s_add_u32 s57, s57, 0x113a0000
	s_add_u32 s6, s50, s57
	s_addc_u32 s7, s51, 0
	global_load_dwordx4 v[0:3], v251, s[6:7] offset:0
	global_load_dwordx4 v[4:7], v251, s[6:7] offset:64
	global_load_dwordx4 v[8:11], v251, s[6:7] offset:128
	global_load_dwordx4 v[12:15], v251, s[6:7] offset:192
	s_lshl_b32 s57, s69, 12
	s_add_u32 s57, s57, s63
	s_add_u32 s57, s57, 0x1d9a0000
	s_add_u32 s10, s50, s57
	s_addc_u32 s11, s51, 0
	v_readlane_b32 s6, v254, 0
	v_readlane_b32 s7, v254, 1
	s_mul_i32 s57, s98, 0x744
	s_add_u32 s57, s57, 0x2b98
	s_nop 2
	s_add_u32 s6, s6, s57
	s_addc_u32 s7, s7, 0
	v_lshlrev_b32_e32 v196, 2, v202
	v_cmp_gt_u32_e32 vcc, 0x1d1, v202
	s_and_saveexec_b64 s[0:1], vcc
	global_load_dword v197, v196, s[6:7]
	s_or_b64 exec, exec, s[0:1]
	s_mov_b32 s70, 0
	s_add_u32 s57, s36, s70
	s_lshl_b32 s57, s57, 6
	s_addk_i32 s57, 0x100
	s_sub_u32 s63, s70, s30
	s_lshl_b32 s63, s63, 6
	s_cmp_lt_u32 s70, s30
	s_cselect_b32 s57, s57, s63
	s_mul_i32 s63, s57, 0x3000
	s_add_u32 s6, s2, s63
	s_addc_u32 s7, s3, 0
	s_lshl_b32 s63, s57, 1
	s_add_u32 s8, s4, s63
	s_addc_u32 s9, s5, 0
	global_load_dwordx4 v[148:151], v230, s[6:7]
	global_load_dwordx4 v[152:155], v231, s[6:7]
	global_load_dwordx4 v[156:159], v232, s[8:9]
	global_load_dwordx4 v[160:163], v233, s[8:9]
	s_mov_b32 s70, 1
	s_add_u32 s57, s36, s70
	s_lshl_b32 s57, s57, 6
	s_addk_i32 s57, 0x100
	s_sub_u32 s63, s70, s30
	s_lshl_b32 s63, s63, 6
	s_cmp_lt_u32 s70, s30
	s_cselect_b32 s57, s57, s63
	s_mul_i32 s63, s57, 0x3000
	s_add_u32 s6, s2, s63
	s_addc_u32 s7, s3, 0
	s_lshl_b32 s63, s57, 1
	s_add_u32 s8, s4, s63
	s_addc_u32 s9, s5, 0
	global_load_dwordx4 v[164:167], v230, s[6:7]
	global_load_dwordx4 v[168:171], v231, s[6:7]
	global_load_dwordx4 v[172:175], v232, s[8:9]
	global_load_dwordx4 v[176:179], v233, s[8:9]
	s_mov_b32 s70, 2
	s_add_u32 s57, s36, s70
	s_lshl_b32 s57, s57, 6
	s_addk_i32 s57, 0x100
	s_sub_u32 s63, s70, s30
	s_lshl_b32 s63, s63, 6
	s_cmp_lt_u32 s70, s30
	s_cselect_b32 s57, s57, s63
	s_mul_i32 s63, s57, 0x3000
	s_add_u32 s6, s2, s63
	s_addc_u32 s7, s3, 0
	s_lshl_b32 s63, s57, 1
	s_add_u32 s8, s4, s63
	s_addc_u32 s9, s5, 0
	global_load_dwordx4 v[180:183], v230, s[6:7]
	global_load_dwordx4 v[184:187], v231, s[6:7]
	global_load_dwordx4 v[188:191], v232, s[8:9]
	global_load_dwordx4 v[192:195], v233, s[8:9]
	s_mov_b32 s70, 3
	s_add_u32 s57, s36, s70
	s_lshl_b32 s57, s57, 6
	s_addk_i32 s57, 0x100
	s_sub_u32 s63, s70, s30
	s_lshl_b32 s63, s63, 6
	s_cmp_lt_u32 s70, s30
	s_cselect_b32 s57, s57, s63
	s_mul_i32 s63, s57, 0x3000
	s_add_u32 s6, s2, s63
	s_addc_u32 s7, s3, 0
	s_lshl_b32 s63, s57, 1
	s_add_u32 s8, s4, s63
	s_addc_u32 s9, s5, 0
	global_load_dwordx4 v[204:207], v230, s[6:7]
	global_load_dwordx4 v[208:211], v231, s[6:7]
	global_load_dwordx4 v[212:215], v232, s[8:9]
	global_load_dwordx4 v[216:219], v233, s[8:9]
	v_mov_b32_e32 v16, 0
	v_mov_b32_e32 v17, 0
	v_mov_b32_e32 v18, 0
	v_mov_b32_e32 v19, 0
	v_mov_b32_e32 v20, 0
	v_mov_b32_e32 v21, 0
	v_mov_b32_e32 v22, 0
	v_mov_b32_e32 v23, 0
	v_mov_b32_e32 v24, 0
	v_mov_b32_e32 v25, 0
	v_mov_b32_e32 v26, 0
	v_mov_b32_e32 v27, 0
	v_mov_b32_e32 v28, 0
	v_mov_b32_e32 v29, 0
	v_mov_b32_e32 v30, 0
	v_mov_b32_e32 v31, 0
	v_mov_b32_e32 v32, 0
	v_mov_b32_e32 v33, 0
	v_mov_b32_e32 v34, 0
	v_mov_b32_e32 v35, 0
	v_mov_b32_e32 v36, 0
	v_mov_b32_e32 v37, 0
	v_mov_b32_e32 v38, 0
	v_mov_b32_e32 v39, 0
	v_mov_b32_e32 v40, 0
	v_mov_b32_e32 v41, 0
	v_mov_b32_e32 v42, 0
	v_mov_b32_e32 v43, 0
	v_mov_b32_e32 v44, 0
	v_mov_b32_e32 v45, 0
	v_mov_b32_e32 v46, 0
	v_mov_b32_e32 v47, 0
	v_mov_b32_e32 v242, 0xf149f2ca
	v_mov_b32_e32 v243, 0
	s_waitcnt vmcnt(12)
	v_cmp_gt_u32_e32 vcc, 0x1d1, v202
	s_and_saveexec_b64 s[0:1], vcc
	v_add_u32_e32 v196, 0x1a400, v196
	ds_write_b32 v196, v197
	s_or_b64 exec, exec, s[0:1]
	ds_write_b128 v234, v[148:151]
	ds_write_b128 v235, v[152:155]
	ds_write_b128 v236, v[156:159]
	ds_write_b128 v237, v[160:163]
	s_waitcnt lgkmcnt(0)
	s_mov_b32 s70, 4
	s_add_u32 s57, s36, s70
	s_lshl_b32 s57, s57, 6
	s_addk_i32 s57, 0x100
	s_sub_u32 s63, s70, s30
	s_lshl_b32 s63, s63, 6
	s_cmp_lt_u32 s70, s30
	s_cselect_b32 s57, s57, s63
	s_mul_i32 s63, s57, 0x3000
	s_add_u32 s6, s2, s63
	s_addc_u32 s7, s3, 0
	s_lshl_b32 s63, s57, 1
	s_add_u32 s8, s4, s63
	s_addc_u32 s9, s5, 0
	global_load_dwordx4 v[148:151], v230, s[6:7]
	global_load_dwordx4 v[152:155], v231, s[6:7]
	global_load_dwordx4 v[156:159], v232, s[8:9]
	global_load_dwordx4 v[160:163], v233, s[8:9]
	s_barrier
	s_mov_b32 s27, 0
; #define LAS __attribute__((address_space(3)))
; #define MFMA16(a, b, c) __builtin_amdgcn_mfma_f32_16x16x32_bf16((a), (b), (c), 0, 0, 0)
; DI void na_block_item(const Params& p, int l, int b, int h, int rp, LAS unsigned char* lds) {
;     ...
;     for (int t = 0; t < ntl; ++t) {
;         const int cur = t % 3;
;         const bool local = t < nloc; const int kr = r0a + t;
;         const int nch = local ? ((kr >= r0w && kr < r0w + 8) ? 1 : 0) : 2;
;         for (int ci = 0; ci < nch; ++ci) {
;             const int toff = local ? band : ci * 32;
;             const LAS unsigned char* kb_ = lds + cur * KTILE + (toff + r16) * KROW + q4 * 16;
;             const LAS unsigned char* vb_ = lds + 3 * KTILE + cur * VTILE + r16 * VROW + (toff + q4 * 4) * 2;
;             float bias8[8];
;             if (local) {
;                 const LAS float* rp_ = s_rpb + (kr - gr + 7) * 31;
; #pragma unroll
;                 for (int e = 0; e < 8; ++e) { const int kcol = band + (e >> 2) * 16 + q4 * 4 + (e & 3); bias8[e] = rp_[min(max(kcol - gc + 15, 0), 30)]; }
;             }
;             f32x4 s[2];
; #pragma unroll
;             for (int hf = 0; hf < 2; ++hf) {
;                 s[hf] = (f32x4){0.f, 0.f, 0.f, 0.f};
; #pragma unroll
;                 for (int ks = 0; ks < 4; ++ks) s[hf] = MFMA16(*(const LAS bf16x8*)(kb_ + hf * 16 * KROW + ks * 64), qf[ks], s[hf]);
;     ...
;                 const u32x2 lo = *(const LAS u32x2*)(vb_ + d * 16 * VROW), hi = *(const LAS u32x2*)(vb_ + d * 16 * VROW + 32);
na1_top:
	s_add_u32 s70, s27, 1
	s_cmp_ge_u32 s70, s31
	s_cbranch_scc1 na1_nostage
	s_mul_hi_u32 s57, s70, 0x55555556
	s_mul_i32 s57, s57, 3
	s_sub_u32 s57, s70, s57
	s_mul_i32 s63, s57, 0x4400
	s_mul_i32 s57, s57, 0x4800
	v_add_u32_e32 v247, s63, v234
	v_add_u32_e32 v248, s63, v235
	v_add_u32_e32 v249, s57, v236
	v_add_u32_e32 v250, s57, v237
	s_sub_u32 s57, s31, s27
	s_sub_u32 s57, s57, 2
	s_cmp_ge_u32 s57, 3
	s_cbranch_scc1 na1_w12
	s_cmp_eq_u32 s57, 2
	s_cbranch_scc1 na1_w8
	s_cmp_eq_u32 s57, 1
	s_cbranch_scc1 na1_w4
	s_waitcnt vmcnt(0)
	s_branch na1_wd
na1_w4:
	s_waitcnt vmcnt(4)
	s_branch na1_wd
na1_w8:
	s_waitcnt vmcnt(8)
	s_branch na1_wd
na1_w12:
	s_waitcnt vmcnt(12)
na1_wd:
	s_add_u32 s71, s27, 5
	s_add_u32 s57, s36, s71
	s_lshl_b32 s57, s57, 6
	s_addk_i32 s57, 0x100
	s_sub_u32 s63, s71, s30
	s_lshl_b32 s63, s63, 6
	s_cmp_lt_u32 s71, s30
	s_cselect_b32 s57, s57, s63
	s_mul_i32 s63, s57, 0x3000
	s_add_u32 s6, s2, s63
	s_addc_u32 s7, s3, 0
	s_lshl_b32 s63, s57, 1
	s_add_u32 s8, s4, s63
	s_addc_u32 s9, s5, 0
	s_and_b32 s57, s70, 3
	s_cmp_eq_u32 s57, 1
	s_cbranch_scc1 na1_rs1
	s_cmp_eq_u32 s57, 2
	s_cbranch_scc1 na1_rs2
	s_cmp_eq_u32 s57, 3
	s_cbranch_scc1 na1_rs3
	ds_write_b128 v247, v[148:151]
	ds_write_b128 v248, v[152:155]
	ds_write_b128 v249, v[156:159]
	ds_write_b128 v250, v[160:163]
	s_waitcnt lgkmcnt(0)
	s_cmp_ge_u32 s71, s31
	s_cbranch_scc1 na1_nostage
	global_load_dwordx4 v[148:151], v230, s[6:7]
	global_load_dwordx4 v[152:155], v231, s[6:7]
	global_load_dwordx4 v[156:159], v232, s[8:9]
	global_load_dwordx4 v[160:163], v233, s[8:9]
	s_branch na1_nostage
na1_rs1:
	ds_write_b128 v247, v[164:167]
	ds_write_b128 v248, v[168:171]
	ds_write_b128 v249, v[172:175]
	ds_write_b128 v250, v[176:179]
	s_waitcnt lgkmcnt(0)
	s_cmp_ge_u32 s71, s31
	s_cbranch_scc1 na1_nostage
	global_load_dwordx4 v[164:167], v230, s[6:7]
	global_load_dwordx4 v[168:171], v231, s[6:7]
	global_load_dwordx4 v[172:175], v232, s[8:9]
	global_load_dwordx4 v[176:179], v233, s[8:9]
	s_branch na1_nostage
na1_rs2:
	ds_write_b128 v247, v[180:183]
	ds_write_b128 v248, v[184:187]
	ds_write_b128 v249, v[188:191]
	ds_write_b128 v250, v[192:195]
	s_waitcnt lgkmcnt(0)
	s_cmp_ge_u32 s71, s31
	s_cbranch_scc1 na1_nostage
	global_load_dwordx4 v[180:183], v230, s[6:7]
	global_load_dwordx4 v[184:187], v231, s[6:7]
	global_load_dwordx4 v[188:191], v232, s[8:9]
	global_load_dwordx4 v[192:195], v233, s[8:9]
	s_branch na1_nostage
na1_rs3:
	ds_write_b128 v247, v[204:207]
	ds_write_b128 v248, v[208:211]
	ds_write_b128 v249, v[212:215]
	ds_write_b128 v250, v[216:219]
	s_waitcnt lgkmcnt(0)
	s_cmp_ge_u32 s71, s31
	s_cbranch_scc1 na1_nostage
	global_load_dwordx4 v[204:207], v230, s[6:7]
	global_load_dwordx4 v[208:211], v231, s[6:7]
	global_load_dwordx4 v[212:215], v232, s[8:9]
	global_load_dwordx4 v[216:219], v233, s[8:9]
na1_nostage:
	s_mul_hi_u32 s57, s27, 0x55555556
	s_mul_i32 s57, s57, 3
	s_sub_u32 s57, s27, s57
	s_mul_i32 s75, s57, 0x4400
	s_mul_i32 s76, s57, 0x4800
	s_cmp_lt_u32 s27, s30
	s_cbranch_scc0 na1_ctx
	s_add_u32 s68, s36, s27
	s_cmp_lt_i32 s68, s54
	s_cbranch_scc1 na1_bar
	s_add_u32 s69, s54, 8
	s_cmp_ge_i32 s68, s69
	s_cbranch_scc1 na1_bar
	s_sub_i32 s69, s68, s37
	s_add_u32 s69, s69, 7
	s_mul_i32 s100, s69, 0x7c
	s_mul_i32 s57, s56, 0x110
	s_add_u32 s57, s57, s75
	s_lshl_b32 s63, s56, 1
	s_add_u32 s63, s63, s76
	v_add_u32_e32 v240, s57, v238
	v_add_u32_e32 v241, s63, v239
	v_add_u32_e32 v222, s100, v132
	v_add_u32_e32 v223, s100, v133
	v_add_u32_e32 v224, s100, v134
	v_add_u32_e32 v225, s100, v135
	v_add_u32_e32 v226, s100, v136
	v_add_u32_e32 v227, s100, v137
	v_add_u32_e32 v228, s100, v138
	v_add_u32_e32 v229, s100, v139
	ds_read_b32 v124, v222
	ds_read_b32 v125, v223
	ds_read_b32 v126, v224
	ds_read_b32 v127, v225
	ds_read_b32 v128, v226
	ds_read_b32 v129, v227
	ds_read_b32 v130, v228
	ds_read_b32 v131, v229
	ds_read_b128 v[56:59], v240 offset:0
	ds_read_b128 v[72:75], v240 offset:4352
	ds_read_b128 v[60:63], v240 offset:64
	ds_read_b128 v[76:79], v240 offset:4416
	ds_read_b128 v[64:67], v240 offset:128
	ds_read_b128 v[80:83], v240 offset:4480
	ds_read_b128 v[68:71], v240 offset:192
	ds_read_b128 v[84:87], v240 offset:4544
	s_waitcnt lgkmcnt(7)
	v_mfma_f32_16x16x32_bf16 v[48:51], v[56:59], v[0:3], 0
	ds_read_b64 v[88:89], v241 offset:0
	ds_read_b64 v[90:91], v241 offset:32
	s_waitcnt lgkmcnt(8)
	v_mfma_f32_16x16x32_bf16 v[52:55], v[72:75], v[0:3], 0
	ds_read_b64 v[92:93], v241 offset:2304
	ds_read_b64 v[94:95], v241 offset:2336
	s_waitcnt lgkmcnt(9)
	v_mfma_f32_16x16x32_bf16 v[48:51], v[60:63], v[4:7], v[48:51]
	ds_read_b64 v[96:97], v241 offset:4608
	ds_read_b64 v[98:99], v241 offset:4640
	s_waitcnt lgkmcnt(10)
	v_mfma_f32_16x16x32_bf16 v[52:55], v[76:79], v[4:7], v[52:55]
	ds_read_b64 v[100:101], v241 offset:6912
	ds_read_b64 v[102:103], v241 offset:6944
	s_waitcnt lgkmcnt(11)
	v_mfma_f32_16x16x32_bf16 v[48:51], v[64:67], v[8:11], v[48:51]
	ds_read_b64 v[104:105], v241 offset:9216
	ds_read_b64 v[106:107], v241 offset:9248
	s_waitcnt lgkmcnt(12)
	v_mfma_f32_16x16x32_bf16 v[52:55], v[80:83], v[8:11], v[52:55]
	ds_read_b64 v[108:109], v241 offset:11520
	ds_read_b64 v[110:111], v241 offset:11552
	s_waitcnt lgkmcnt(13)
	v_mfma_f32_16x16x32_bf16 v[48:51], v[68:71], v[12:15], v[48:51]
	ds_read_b64 v[112:113], v241 offset:13824
	ds_read_b64 v[114:115], v241 offset:13856
	s_waitcnt lgkmcnt(14)
; DI void na_block_item(const Params& p, int l, int b, int h, int rp, LAS unsigned char* lds) {
;     ...
;             const int toff = local ? band : ci * 32;
;             const LAS unsigned char* kb_ = lds + cur * KTILE + (toff + r16) * KROW + q4 * 16;
;             const LAS unsigned char* vb_ = lds + 3 * KTILE + cur * VTILE + r16 * VROW + (toff + q4 * 4) * 2;
;             float bias8[8];
;             if (local) {
;                 const LAS float* rp_ = s_rpb + (kr - gr + 7) * 31;
; #pragma unroll
;     ...
;             if (local) {
; #pragma unroll
;                 for (int hf = 0; hf < 2; ++hf)
; #pragma unroll
;                     for (int j = 0; j < 4; ++j) {
;                         const int kcol = band + hf * 16 + q4 * 4 + j; const bool inw = kcol >= cs && kcol < cs + 16;
;                         s[hf][j] = inw ? s[hf][j] * sl2 + bias8[hf * 4 + j] * 1.4426950408889634f : -1e30f;
;                     }
;             } else { s[0] *= sl2; s[1] *= sl2; }
;             float mx = fmaxf(fmaxf(fmaxf(s[0][0], s[0][1]), fmaxf(s[0][2], s[0][3])), fmaxf(fmaxf(s[1][0], s[1][1]), fmaxf(s[1][2], s[1][3])));
;             mx = fmaxf(mx, __shfl_xor(mx, 16)); mx = fmaxf(mx, __shfl_xor(mx, 32));
;             const float mnew = fmaxf(mrun, mx), alpha = fast_exp2(mrun - mnew);
;             mrun = mnew;
;             float ps = 0.f;
; #pragma unroll
;             for (int hf = 0; hf < 2; ++hf)
; #pragma unroll
;                 for (int j = 0; j < 4; ++j) { const float pv = fast_exp2(s[hf][j] - mnew); s[hf][j] = pv; ps += pv; }
;             lsum = lsum * alpha + ps;
; #pragma unroll
;             for (int d = 0; d < 8; ++d) oacc[d] *= alpha;
;             u32x4 w4; w4.x = cvt_pk_bf16(s[0][0], s[0][1]); w4.y = cvt_pk_bf16(s[0][2], s[0][3]); w4.z = cvt_pk_bf16(s[1][0], s[1][1]); w4.w = cvt_pk_bf16(s[1][2], s[1][3]);
;             const bf16x8 pb = __builtin_bit_cast(bf16x8, w4);
;             __builtin_amdgcn_s_setprio(1);
; #pragma unroll
;             for (int d = 0; d < 8; ++d) {
;                 const u32x2 lo = *(const LAS u32x2*)(vb_ + d * 16 * VROW), hi = *(const LAS u32x2*)(vb_ + d * 16 * VROW + 32);
;                 u32x4 a4; a4.x = lo.x; a4.y = lo.y; a4.z = hi.x; a4.w = hi.y;
;                 oacc[d] = MFMA16(__builtin_bit_cast(bf16x8, a4), pb, oacc[d]);
;             }
;             __builtin_amdgcn_s_setprio(0);
;         }
	v_mfma_f32_16x16x32_bf16 v[52:55], v[84:87], v[12:15], v[52:55]
	ds_read_b64 v[116:117], v241 offset:16128
	ds_read_b64 v[118:119], v241 offset:16160
	v_mul_f32_e32 v124, s23, v124
	v_mul_f32_e32 v125, s23, v125
	v_mul_f32_e32 v126, s23, v126
	v_mul_f32_e32 v127, s23, v127
	v_mul_f32_e32 v128, s23, v128
	v_mul_f32_e32 v129, s23, v129
	v_mul_f32_e32 v130, s23, v130
	v_mul_f32_e32 v131, s23, v131
	s_nop 1
	v_fma_f32 v48, v48, s22, v124
	v_fma_f32 v49, v49, s22, v125
	v_fma_f32 v50, v50, s22, v126
	v_fma_f32 v51, v51, s22, v127
	v_fma_f32 v52, v52, s22, v128
	v_fma_f32 v53, v53, s22, v129
	v_fma_f32 v54, v54, s22, v130
	v_fma_f32 v55, v55, s22, v131
	v_min_f32_e32 v48, v48, v140
	v_min_f32_e32 v49, v49, v141
	v_min_f32_e32 v50, v50, v142
	v_min_f32_e32 v51, v51, v143
	v_min_f32_e32 v52, v52, v144
	v_min_f32_e32 v53, v53, v145
	v_min_f32_e32 v54, v54, v146
	v_min_f32_e32 v55, v55, v147
	v_max3_f32 v196, v48, v49, v50
	v_max3_f32 v197, v51, v52, v53
	v_max3_f32 v196, v196, v54, v55
	v_max_f32_e32 v196, v196, v197
	v_mov_b32_e32 v197, v196
	s_nop 1
	v_permlane16_swap_b32_e32 v196, v197
	v_max_f32_e32 v196, v196, v197
	v_mov_b32_e32 v197, v196
	s_nop 1
	v_permlane32_swap_b32_e32 v196, v197
	v_max_f32_e32 v196, v196, v197
	v_max_f32_e32 v197, v242, v196
	v_sub_f32_e32 v196, v242, v197
	v_exp_f32_e32 v244, v196
	v_mov_b32_e32 v242, v197
	v_sub_f32_e32 v48, v48, v197
	v_sub_f32_e32 v49, v49, v197
	v_sub_f32_e32 v50, v50, v197
	v_sub_f32_e32 v51, v51, v197
	v_sub_f32_e32 v52, v52, v197
	v_sub_f32_e32 v53, v53, v197
	v_sub_f32_e32 v54, v54, v197
	v_sub_f32_e32 v55, v55, v197
	v_exp_f32_e32 v48, v48
	v_exp_f32_e32 v49, v49
	v_exp_f32_e32 v50, v50
	v_exp_f32_e32 v51, v51
	v_exp_f32_e32 v52, v52
	v_exp_f32_e32 v53, v53
	v_exp_f32_e32 v54, v54
	v_exp_f32_e32 v55, v55
	v_add_f32_e32 v196, v48, v49
	v_add_f32_e32 v196, v196, v50
	v_add_f32_e32 v196, v196, v51
	v_add_f32_e32 v196, v196, v52
	v_add_f32_e32 v196, v196, v53
	v_add_f32_e32 v196, v196, v54
	v_add_f32_e32 v196, v196, v55
	v_fma_f32 v243, v243, v244, v196
	v_cvt_pk_bf16_f32 v120, v48, v49
	v_cvt_pk_bf16_f32 v121, v50, v51
	v_cvt_pk_bf16_f32 v122, v52, v53
	v_cvt_pk_bf16_f32 v123, v54, v55
	v_pk_mul_f32 v[16:17], v[16:17], v[244:245] op_sel_hi:[1,0]
	v_pk_mul_f32 v[18:19], v[18:19], v[244:245] op_sel_hi:[1,0]
	v_pk_mul_f32 v[20:21], v[20:21], v[244:245] op_sel_hi:[1,0]
	v_pk_mul_f32 v[22:23], v[22:23], v[244:245] op_sel_hi:[1,0]
	v_pk_mul_f32 v[24:25], v[24:25], v[244:245] op_sel_hi:[1,0]
	v_pk_mul_f32 v[26:27], v[26:27], v[244:245] op_sel_hi:[1,0]
	v_pk_mul_f32 v[28:29], v[28:29], v[244:245] op_sel_hi:[1,0]
	v_pk_mul_f32 v[30:31], v[30:31], v[244:245] op_sel_hi:[1,0]
	v_pk_mul_f32 v[32:33], v[32:33], v[244:245] op_sel_hi:[1,0]
	v_pk_mul_f32 v[34:35], v[34:35], v[244:245] op_sel_hi:[1,0]
	v_pk_mul_f32 v[36:37], v[36:37], v[244:245] op_sel_hi:[1,0]
	v_pk_mul_f32 v[38:39], v[38:39], v[244:245] op_sel_hi:[1,0]
	v_pk_mul_f32 v[40:41], v[40:41], v[244:245] op_sel_hi:[1,0]
	v_pk_mul_f32 v[42:43], v[42:43], v[244:245] op_sel_hi:[1,0]
	v_pk_mul_f32 v[44:45], v[44:45], v[244:245] op_sel_hi:[1,0]
	v_pk_mul_f32 v[46:47], v[46:47], v[244:245] op_sel_hi:[1,0]
	s_waitcnt lgkmcnt(14)
	v_mfma_f32_16x16x32_bf16 v[16:19], v[88:91], v[120:123], v[16:19]
	s_waitcnt lgkmcnt(12)
	v_mfma_f32_16x16x32_bf16 v[20:23], v[92:95], v[120:123], v[20:23]
	s_waitcnt lgkmcnt(10)
	v_mfma_f32_16x16x32_bf16 v[24:27], v[96:99], v[120:123], v[24:27]
	s_waitcnt lgkmcnt(8)
	v_mfma_f32_16x16x32_bf16 v[28:31], v[100:103], v[120:123], v[28:31]
	s_waitcnt lgkmcnt(6)
	v_mfma_f32_16x16x32_bf16 v[32:35], v[104:107], v[120:123], v[32:35]
	s_waitcnt lgkmcnt(4)
	v_mfma_f32_16x16x32_bf16 v[36:39], v[108:111], v[120:123], v[36:39]
	s_waitcnt lgkmcnt(2)
	v_mfma_f32_16x16x32_bf16 v[40:43], v[112:115], v[120:123], v[40:43]
	s_waitcnt lgkmcnt(0)
	v_mfma_f32_16x16x32_bf16 v[44:47], v[116:119], v[120:123], v[44:47]
	s_branch na1_bar
na1_ctx:
	s_add_u32 s57, s75, 0x0
	s_add_u32 s63, s76, 0x0
	v_add_u32_e32 v240, s57, v238
	v_add_u32_e32 v241, s63, v239
	ds_read_b128 v[56:59], v240 offset:0
	ds_read_b128 v[72:75], v240 offset:4352
	ds_read_b128 v[60:63], v240 offset:64
	ds_read_b128 v[76:79], v240 offset:4416
	ds_read_b128 v[64:67], v240 offset:128
	ds_read_b128 v[80:83], v240 offset:4480
	ds_read_b128 v[68:71], v240 offset:192
	ds_read_b128 v[84:87], v240 offset:4544
	s_waitcnt lgkmcnt(7)
	v_mfma_f32_16x16x32_bf16 v[48:51], v[56:59], v[0:3], 0
	ds_read_b64 v[88:89], v241 offset:0
	ds_read_b64 v[90:91], v241 offset:32
	s_waitcnt lgkmcnt(8)
	v_mfma_f32_16x16x32_bf16 v[52:55], v[72:75], v[0:3], 0
	ds_read_b64 v[92:93], v241 offset:2304
	ds_read_b64 v[94:95], v241 offset:2336
	s_waitcnt lgkmcnt(9)
	v_mfma_f32_16x16x32_bf16 v[48:51], v[60:63], v[4:7], v[48:51]
	ds_read_b64 v[96:97], v241 offset:4608
	ds_read_b64 v[98:99], v241 offset:4640
	s_waitcnt lgkmcnt(10)
	v_mfma_f32_16x16x32_bf16 v[52:55], v[76:79], v[4:7], v[52:55]
	ds_read_b64 v[100:101], v241 offset:6912
	ds_read_b64 v[102:103], v241 offset:6944
	s_waitcnt lgkmcnt(11)
	v_mfma_f32_16x16x32_bf16 v[48:51], v[64:67], v[8:11], v[48:51]
	ds_read_b64 v[104:105], v241 offset:9216
	ds_read_b64 v[106:107], v241 offset:9248
	s_waitcnt lgkmcnt(12)
	v_mfma_f32_16x16x32_bf16 v[52:55], v[80:83], v[8:11], v[52:55]
	ds_read_b64 v[108:109], v241 offset:11520
	ds_read_b64 v[110:111], v241 offset:11552
	s_waitcnt lgkmcnt(13)
	v_mfma_f32_16x16x32_bf16 v[48:51], v[68:71], v[12:15], v[48:51]
	ds_read_b64 v[112:113], v241 offset:13824
	ds_read_b64 v[114:115], v241 offset:13856
	s_waitcnt lgkmcnt(14)
; DI void na_block_item(const Params& p, int l, int b, int h, int rp, LAS unsigned char* lds) {
;     ...
;         for (int ci = 0; ci < nch; ++ci) {
;             const int toff = local ? band : ci * 32;
;             const LAS unsigned char* kb_ = lds + cur * KTILE + (toff + r16) * KROW + q4 * 16;
;             const LAS unsigned char* vb_ = lds + 3 * KTILE + cur * VTILE + r16 * VROW + (toff + q4 * 4) * 2;
;             float bias8[8];
;             if (local) {
;                 const LAS float* rp_ = s_rpb + (kr - gr + 7) * 31;
; #pragma unroll
;                 for (int e = 0; e < 8; ++e) { const int kcol = band + (e >> 2) * 16 + q4 * 4 + (e & 3); bias8[e] = rp_[min(max(kcol - gc + 15, 0), 30)]; }
;             }
;             f32x4 s[2];
; #pragma unroll
;             for (int hf = 0; hf < 2; ++hf) {
;                 s[hf] = (f32x4){0.f, 0.f, 0.f, 0.f};
; #pragma unroll
;                 for (int ks = 0; ks < 4; ++ks) s[hf] = MFMA16(*(const LAS bf16x8*)(kb_ + hf * 16 * KROW + ks * 64), qf[ks], s[hf]);
;             }
;             if (local) {
; #pragma unroll
;                 for (int hf = 0; hf < 2; ++hf)
; #pragma unroll
;                     for (int j = 0; j < 4; ++j) {
;                         const int kcol = band + hf * 16 + q4 * 4 + j; const bool inw = kcol >= cs && kcol < cs + 16;
;                         s[hf][j] = inw ? s[hf][j] * sl2 + bias8[hf * 4 + j] * 1.4426950408889634f : -1e30f;
;                     }
;             } else { s[0] *= sl2; s[1] *= sl2; }
;             float mx = fmaxf(fmaxf(fmaxf(s[0][0], s[0][1]), fmaxf(s[0][2], s[0][3])), fmaxf(fmaxf(s[1][0], s[1][1]), fmaxf(s[1][2], s[1][3])));
;             mx = fmaxf(mx, __shfl_xor(mx, 16)); mx = fmaxf(mx, __shfl_xor(mx, 32));
;             const float mnew = fmaxf(mrun, mx), alpha = fast_exp2(mrun - mnew);
;             mrun = mnew;
;             float ps = 0.f;
; #pragma unroll
;             for (int hf = 0; hf < 2; ++hf)
; #pragma unroll
;                 for (int j = 0; j < 4; ++j) { const float pv = fast_exp2(s[hf][j] - mnew); s[hf][j] = pv; ps += pv; }
;             lsum = lsum * alpha + ps;
; #pragma unroll
;             for (int d = 0; d < 8; ++d) oacc[d] *= alpha;
;             u32x4 w4; w4.x = cvt_pk_bf16(s[0][0], s[0][1]); w4.y = cvt_pk_bf16(s[0][2], s[0][3]); w4.z = cvt_pk_bf16(s[1][0], s[1][1]); w4.w = cvt_pk_bf16(s[1][2], s[1][3]);
	v_mfma_f32_16x16x32_bf16 v[52:55], v[84:87], v[12:15], v[52:55]
	ds_read_b64 v[116:117], v241 offset:16128
	ds_read_b64 v[118:119], v241 offset:16160
	s_nop 7
	s_nop 1
	v_mul_f32_e32 v48, s22, v48
	v_mul_f32_e32 v49, s22, v49
	v_mul_f32_e32 v50, s22, v50
	v_mul_f32_e32 v51, s22, v51
	v_mul_f32_e32 v52, s22, v52
	v_mul_f32_e32 v53, s22, v53
	v_mul_f32_e32 v54, s22, v54
	v_mul_f32_e32 v55, s22, v55
	v_max3_f32 v196, v48, v49, v50
	v_max3_f32 v197, v51, v52, v53
	v_max3_f32 v196, v196, v54, v55
	v_max_f32_e32 v196, v196, v197
	v_mov_b32_e32 v197, v196
	s_nop 1
	v_permlane16_swap_b32_e32 v196, v197
	v_max_f32_e32 v196, v196, v197
	v_mov_b32_e32 v197, v196
	s_nop 1
	v_permlane32_swap_b32_e32 v196, v197
	v_max_f32_e32 v196, v196, v197
	v_max_f32_e32 v197, v242, v196
	v_sub_f32_e32 v196, v242, v197
	v_exp_f32_e32 v244, v196
	v_mov_b32_e32 v242, v197
	v_sub_f32_e32 v48, v48, v197
	v_sub_f32_e32 v49, v49, v197
	v_sub_f32_e32 v50, v50, v197
	v_sub_f32_e32 v51, v51, v197
	v_sub_f32_e32 v52, v52, v197
	v_sub_f32_e32 v53, v53, v197
	v_sub_f32_e32 v54, v54, v197
	v_sub_f32_e32 v55, v55, v197
	v_exp_f32_e32 v48, v48
	v_exp_f32_e32 v49, v49
	v_exp_f32_e32 v50, v50
	v_exp_f32_e32 v51, v51
	v_exp_f32_e32 v52, v52
	v_exp_f32_e32 v53, v53
	v_exp_f32_e32 v54, v54
	v_exp_f32_e32 v55, v55
	v_add_f32_e32 v196, v48, v49
	v_add_f32_e32 v196, v196, v50
	v_add_f32_e32 v196, v196, v51
	v_add_f32_e32 v196, v196, v52
	v_add_f32_e32 v196, v196, v53
	v_add_f32_e32 v196, v196, v54
	v_add_f32_e32 v196, v196, v55
	v_fma_f32 v243, v243, v244, v196
	v_cvt_pk_bf16_f32 v120, v48, v49
	v_cvt_pk_bf16_f32 v121, v50, v51
	v_cvt_pk_bf16_f32 v122, v52, v53
	v_cvt_pk_bf16_f32 v123, v54, v55
	v_pk_mul_f32 v[16:17], v[16:17], v[244:245] op_sel_hi:[1,0]
	v_pk_mul_f32 v[18:19], v[18:19], v[244:245] op_sel_hi:[1,0]
	v_pk_mul_f32 v[20:21], v[20:21], v[244:245] op_sel_hi:[1,0]
	v_pk_mul_f32 v[22:23], v[22:23], v[244:245] op_sel_hi:[1,0]
	v_pk_mul_f32 v[24:25], v[24:25], v[244:245] op_sel_hi:[1,0]
	v_pk_mul_f32 v[26:27], v[26:27], v[244:245] op_sel_hi:[1,0]
	v_pk_mul_f32 v[28:29], v[28:29], v[244:245] op_sel_hi:[1,0]
	v_pk_mul_f32 v[30:31], v[30:31], v[244:245] op_sel_hi:[1,0]
	v_pk_mul_f32 v[32:33], v[32:33], v[244:245] op_sel_hi:[1,0]
	v_pk_mul_f32 v[34:35], v[34:35], v[244:245] op_sel_hi:[1,0]
	v_pk_mul_f32 v[36:37], v[36:37], v[244:245] op_sel_hi:[1,0]
	v_pk_mul_f32 v[38:39], v[38:39], v[244:245] op_sel_hi:[1,0]
	v_pk_mul_f32 v[40:41], v[40:41], v[244:245] op_sel_hi:[1,0]
	v_pk_mul_f32 v[42:43], v[42:43], v[244:245] op_sel_hi:[1,0]
	v_pk_mul_f32 v[44:45], v[44:45], v[244:245] op_sel_hi:[1,0]
	v_pk_mul_f32 v[46:47], v[46:47], v[244:245] op_sel_hi:[1,0]
	s_waitcnt lgkmcnt(14)
	v_mfma_f32_16x16x32_bf16 v[16:19], v[88:91], v[120:123], v[16:19]
	s_waitcnt lgkmcnt(12)
	v_mfma_f32_16x16x32_bf16 v[20:23], v[92:95], v[120:123], v[20:23]
	s_waitcnt lgkmcnt(10)
	v_mfma_f32_16x16x32_bf16 v[24:27], v[96:99], v[120:123], v[24:27]
	s_waitcnt lgkmcnt(8)
	v_mfma_f32_16x16x32_bf16 v[28:31], v[100:103], v[120:123], v[28:31]
	s_waitcnt lgkmcnt(6)
	v_mfma_f32_16x16x32_bf16 v[32:35], v[104:107], v[120:123], v[32:35]
	s_waitcnt lgkmcnt(4)
	v_mfma_f32_16x16x32_bf16 v[36:39], v[108:111], v[120:123], v[36:39]
	s_waitcnt lgkmcnt(2)
	v_mfma_f32_16x16x32_bf16 v[40:43], v[112:115], v[120:123], v[40:43]
	s_waitcnt lgkmcnt(0)
	v_mfma_f32_16x16x32_bf16 v[44:47], v[116:119], v[120:123], v[44:47]
	s_add_u32 s57, s75, 0x2200
	s_add_u32 s63, s76, 0x40
	v_add_u32_e32 v240, s57, v238
	v_add_u32_e32 v241, s63, v239
	ds_read_b128 v[56:59], v240 offset:0
	ds_read_b128 v[72:75], v240 offset:4352
	ds_read_b128 v[60:63], v240 offset:64
	ds_read_b128 v[76:79], v240 offset:4416
	ds_read_b128 v[64:67], v240 offset:128
	ds_read_b128 v[80:83], v240 offset:4480
	ds_read_b128 v[68:71], v240 offset:192
	ds_read_b128 v[84:87], v240 offset:4544
	s_waitcnt lgkmcnt(7)
	v_mfma_f32_16x16x32_bf16 v[48:51], v[56:59], v[0:3], 0
	ds_read_b64 v[88:89], v241 offset:0
	ds_read_b64 v[90:91], v241 offset:32
	s_waitcnt lgkmcnt(8)
	v_mfma_f32_16x16x32_bf16 v[52:55], v[72:75], v[0:3], 0
	ds_read_b64 v[92:93], v241 offset:2304
	ds_read_b64 v[94:95], v241 offset:2336
	s_waitcnt lgkmcnt(9)
	v_mfma_f32_16x16x32_bf16 v[48:51], v[60:63], v[4:7], v[48:51]
	ds_read_b64 v[96:97], v241 offset:4608
	ds_read_b64 v[98:99], v241 offset:4640
	s_waitcnt lgkmcnt(10)
	v_mfma_f32_16x16x32_bf16 v[52:55], v[76:79], v[4:7], v[52:55]
	ds_read_b64 v[100:101], v241 offset:6912
	ds_read_b64 v[102:103], v241 offset:6944
	s_waitcnt lgkmcnt(11)
	v_mfma_f32_16x16x32_bf16 v[48:51], v[64:67], v[8:11], v[48:51]
	ds_read_b64 v[104:105], v241 offset:9216
	ds_read_b64 v[106:107], v241 offset:9248
	s_waitcnt lgkmcnt(12)
	v_mfma_f32_16x16x32_bf16 v[52:55], v[80:83], v[8:11], v[52:55]
	ds_read_b64 v[108:109], v241 offset:11520
	ds_read_b64 v[110:111], v241 offset:11552
	s_waitcnt lgkmcnt(13)
	v_mfma_f32_16x16x32_bf16 v[48:51], v[68:71], v[12:15], v[48:51]
	ds_read_b64 v[112:113], v241 offset:13824
	ds_read_b64 v[114:115], v241 offset:13856
	s_waitcnt lgkmcnt(14)
; #define LAS __attribute__((address_space(3)))
; #define MFMA16(a, b, c) __builtin_amdgcn_mfma_f32_16x16x32_bf16((a), (b), (c), 0, 0, 0)
; DI int next_item(unsigned* ctr, volatile LAS int* slot) {
;     __syncthreads();
;     if (threadIdx.x == 0) *slot = (int)xb_add(ctr, 1u);
;     __syncthreads();
;     return *slot;
; }
; DI void na_block_item(const Params& p, int l, int b, int h, int rp, LAS unsigned char* lds) {
;     ...
;             float mx = fmaxf(fmaxf(fmaxf(s[0][0], s[0][1]), fmaxf(s[0][2], s[0][3])), fmaxf(fmaxf(s[1][0], s[1][1]), fmaxf(s[1][2], s[1][3])));
;             mx = fmaxf(mx, __shfl_xor(mx, 16)); mx = fmaxf(mx, __shfl_xor(mx, 32));
;             const float mnew = fmaxf(mrun, mx), alpha = fast_exp2(mrun - mnew);
;             mrun = mnew;
;             float ps = 0.f;
; #pragma unroll
;             for (int hf = 0; hf < 2; ++hf)
; #pragma unroll
;                 for (int j = 0; j < 4; ++j) { const float pv = fast_exp2(s[hf][j] - mnew); s[hf][j] = pv; ps += pv; }
;             lsum = lsum * alpha + ps;
; #pragma unroll
;             for (int d = 0; d < 8; ++d) oacc[d] *= alpha;
;             u32x4 w4; w4.x = cvt_pk_bf16(s[0][0], s[0][1]); w4.y = cvt_pk_bf16(s[0][2], s[0][3]); w4.z = cvt_pk_bf16(s[1][0], s[1][1]); w4.w = cvt_pk_bf16(s[1][2], s[1][3]);
;             const bf16x8 pb = __builtin_bit_cast(bf16x8, w4);
;             __builtin_amdgcn_s_setprio(1);
; #pragma unroll
;             for (int d = 0; d < 8; ++d) {
;                 const u32x2 lo = *(const LAS u32x2*)(vb_ + d * 16 * VROW), hi = *(const LAS u32x2*)(vb_ + d * 16 * VROW + 32);
;                 u32x4 a4; a4.x = lo.x; a4.y = lo.y; a4.z = hi.x; a4.w = hi.y;
;                 oacc[d] = MFMA16(__builtin_bit_cast(bf16x8, a4), pb, oacc[d]);
;             }
;             __builtin_amdgcn_s_setprio(0);
;         }
;         const int nb_ = (t + 1) % 3;
;         if (t & 1) { if (t + 1 < ntl) NA_STORE(nb_, kstA, vstA); if (t + 3 < ntl) NA_LOAD(t + 3, kstA, vstA); }
;         else       { if (t + 1 < ntl) NA_STORE(nb_, kstB, vstB); if (t + 3 < ntl) NA_LOAD(t + 3, kstB, vstB); }
;         __syncthreads();
;     }
;     ...
;     float lt = lsum; lt += __shfl_xor(lt, 16); lt += __shfl_xor(lt, 32);
;     const float inv = 1.f / lt;
;     bf16_t* op = (bf16_t*)(ws + WS_YMIX) + rowq * DM + h * 128 + q4 * 4;
; #pragma unroll
;     for (int d = 0; d < 8; ++d) st_bf16x4(op + d * 16, oacc[d] * inv);
	v_mfma_f32_16x16x32_bf16 v[52:55], v[84:87], v[12:15], v[52:55]
	ds_read_b64 v[116:117], v241 offset:16128
	ds_read_b64 v[118:119], v241 offset:16160
	s_nop 7
	s_nop 1
	v_mul_f32_e32 v48, s22, v48
	v_mul_f32_e32 v49, s22, v49
	v_mul_f32_e32 v50, s22, v50
	v_mul_f32_e32 v51, s22, v51
	v_mul_f32_e32 v52, s22, v52
	v_mul_f32_e32 v53, s22, v53
	v_mul_f32_e32 v54, s22, v54
	v_mul_f32_e32 v55, s22, v55
	v_max3_f32 v196, v48, v49, v50
	v_max3_f32 v197, v51, v52, v53
	v_max3_f32 v196, v196, v54, v55
	v_max_f32_e32 v196, v196, v197
	v_mov_b32_e32 v197, v196
	s_nop 1
	v_permlane16_swap_b32_e32 v196, v197
	v_max_f32_e32 v196, v196, v197
	v_mov_b32_e32 v197, v196
	s_nop 1
	v_permlane32_swap_b32_e32 v196, v197
	v_max_f32_e32 v196, v196, v197
	v_max_f32_e32 v197, v242, v196
	v_sub_f32_e32 v196, v242, v197
	v_exp_f32_e32 v244, v196
	v_mov_b32_e32 v242, v197
	v_sub_f32_e32 v48, v48, v197
	v_sub_f32_e32 v49, v49, v197
	v_sub_f32_e32 v50, v50, v197
	v_sub_f32_e32 v51, v51, v197
	v_sub_f32_e32 v52, v52, v197
	v_sub_f32_e32 v53, v53, v197
	v_sub_f32_e32 v54, v54, v197
	v_sub_f32_e32 v55, v55, v197
	v_exp_f32_e32 v48, v48
	v_exp_f32_e32 v49, v49
	v_exp_f32_e32 v50, v50
	v_exp_f32_e32 v51, v51
	v_exp_f32_e32 v52, v52
	v_exp_f32_e32 v53, v53
	v_exp_f32_e32 v54, v54
	v_exp_f32_e32 v55, v55
	v_add_f32_e32 v196, v48, v49
	v_add_f32_e32 v196, v196, v50
	v_add_f32_e32 v196, v196, v51
	v_add_f32_e32 v196, v196, v52
	v_add_f32_e32 v196, v196, v53
	v_add_f32_e32 v196, v196, v54
	v_add_f32_e32 v196, v196, v55
	v_fma_f32 v243, v243, v244, v196
	v_cvt_pk_bf16_f32 v120, v48, v49
	v_cvt_pk_bf16_f32 v121, v50, v51
	v_cvt_pk_bf16_f32 v122, v52, v53
	v_cvt_pk_bf16_f32 v123, v54, v55
	v_pk_mul_f32 v[16:17], v[16:17], v[244:245] op_sel_hi:[1,0]
	v_pk_mul_f32 v[18:19], v[18:19], v[244:245] op_sel_hi:[1,0]
	v_pk_mul_f32 v[20:21], v[20:21], v[244:245] op_sel_hi:[1,0]
	v_pk_mul_f32 v[22:23], v[22:23], v[244:245] op_sel_hi:[1,0]
	v_pk_mul_f32 v[24:25], v[24:25], v[244:245] op_sel_hi:[1,0]
	v_pk_mul_f32 v[26:27], v[26:27], v[244:245] op_sel_hi:[1,0]
	v_pk_mul_f32 v[28:29], v[28:29], v[244:245] op_sel_hi:[1,0]
	v_pk_mul_f32 v[30:31], v[30:31], v[244:245] op_sel_hi:[1,0]
	v_pk_mul_f32 v[32:33], v[32:33], v[244:245] op_sel_hi:[1,0]
	v_pk_mul_f32 v[34:35], v[34:35], v[244:245] op_sel_hi:[1,0]
	v_pk_mul_f32 v[36:37], v[36:37], v[244:245] op_sel_hi:[1,0]
	v_pk_mul_f32 v[38:39], v[38:39], v[244:245] op_sel_hi:[1,0]
	v_pk_mul_f32 v[40:41], v[40:41], v[244:245] op_sel_hi:[1,0]
	v_pk_mul_f32 v[42:43], v[42:43], v[244:245] op_sel_hi:[1,0]
	v_pk_mul_f32 v[44:45], v[44:45], v[244:245] op_sel_hi:[1,0]
	v_pk_mul_f32 v[46:47], v[46:47], v[244:245] op_sel_hi:[1,0]
	s_waitcnt lgkmcnt(14)
	v_mfma_f32_16x16x32_bf16 v[16:19], v[88:91], v[120:123], v[16:19]
	s_waitcnt lgkmcnt(12)
	v_mfma_f32_16x16x32_bf16 v[20:23], v[92:95], v[120:123], v[20:23]
	s_waitcnt lgkmcnt(10)
	v_mfma_f32_16x16x32_bf16 v[24:27], v[96:99], v[120:123], v[24:27]
	s_waitcnt lgkmcnt(8)
	v_mfma_f32_16x16x32_bf16 v[28:31], v[100:103], v[120:123], v[28:31]
	s_waitcnt lgkmcnt(6)
	v_mfma_f32_16x16x32_bf16 v[32:35], v[104:107], v[120:123], v[32:35]
	s_waitcnt lgkmcnt(4)
	v_mfma_f32_16x16x32_bf16 v[36:39], v[108:111], v[120:123], v[36:39]
	s_waitcnt lgkmcnt(2)
	v_mfma_f32_16x16x32_bf16 v[40:43], v[112:115], v[120:123], v[40:43]
	s_waitcnt lgkmcnt(0)
	v_mfma_f32_16x16x32_bf16 v[44:47], v[116:119], v[120:123], v[44:47]
na1_bar:
	s_waitcnt lgkmcnt(0)
	s_barrier
	s_add_u32 s27, s27, 1
	s_cmp_lt_u32 s27, s31
	s_cbranch_scc1 na1_top
	v_mov_b32_e32 v196, v243
	v_mov_b32_e32 v197, v243
	s_nop 1
	v_permlane16_swap_b32_e32 v196, v197
	v_add_f32_e32 v196, v196, v197
	v_mov_b32_e32 v197, v196
	s_nop 1
	v_permlane32_swap_b32_e32 v196, v197
	v_add_f32_e32 v196, v196, v197
	v_rcp_f32_e32 v197, v196
	s_nop 0
	v_fma_f32 v196, -v196, v197, 1.0
	v_fma_f32 v244, v196, v197, v197
	v_pk_mul_f32 v[16:17], v[16:17], v[244:245] op_sel_hi:[1,0]
	v_pk_mul_f32 v[18:19], v[18:19], v[244:245] op_sel_hi:[1,0]
	v_cvt_pk_bf16_f32 v16, v16, v17
	v_cvt_pk_bf16_f32 v17, v18, v19
	global_store_dwordx2 v246, v[16:17], s[10:11] offset:0
	v_pk_mul_f32 v[20:21], v[20:21], v[244:245] op_sel_hi:[1,0]
	v_pk_mul_f32 v[22:23], v[22:23], v[244:245] op_sel_hi:[1,0]
	v_cvt_pk_bf16_f32 v20, v20, v21
	v_cvt_pk_bf16_f32 v21, v22, v23
	global_store_dwordx2 v246, v[20:21], s[10:11] offset:32
	v_pk_mul_f32 v[24:25], v[24:25], v[244:245] op_sel_hi:[1,0]
	v_pk_mul_f32 v[26:27], v[26:27], v[244:245] op_sel_hi:[1,0]
	v_cvt_pk_bf16_f32 v24, v24, v25
	v_cvt_pk_bf16_f32 v25, v26, v27
	global_store_dwordx2 v246, v[24:25], s[10:11] offset:64
	v_pk_mul_f32 v[28:29], v[28:29], v[244:245] op_sel_hi:[1,0]
	v_pk_mul_f32 v[30:31], v[30:31], v[244:245] op_sel_hi:[1,0]
	v_cvt_pk_bf16_f32 v28, v28, v29
	v_cvt_pk_bf16_f32 v29, v30, v31
	global_store_dwordx2 v246, v[28:29], s[10:11] offset:96
	v_pk_mul_f32 v[32:33], v[32:33], v[244:245] op_sel_hi:[1,0]
	v_pk_mul_f32 v[34:35], v[34:35], v[244:245] op_sel_hi:[1,0]
	v_cvt_pk_bf16_f32 v32, v32, v33
	v_cvt_pk_bf16_f32 v33, v34, v35
	global_store_dwordx2 v246, v[32:33], s[10:11] offset:128
	v_pk_mul_f32 v[36:37], v[36:37], v[244:245] op_sel_hi:[1,0]
	v_pk_mul_f32 v[38:39], v[38:39], v[244:245] op_sel_hi:[1,0]
	v_cvt_pk_bf16_f32 v36, v36, v37
	v_cvt_pk_bf16_f32 v37, v38, v39
	global_store_dwordx2 v246, v[36:37], s[10:11] offset:160
	v_pk_mul_f32 v[40:41], v[40:41], v[244:245] op_sel_hi:[1,0]
	v_pk_mul_f32 v[42:43], v[42:43], v[244:245] op_sel_hi:[1,0]
	v_cvt_pk_bf16_f32 v40, v40, v41
	v_cvt_pk_bf16_f32 v41, v42, v43
	global_store_dwordx2 v246, v[40:41], s[10:11] offset:192
	v_pk_mul_f32 v[44:45], v[44:45], v[244:245] op_sel_hi:[1,0]
	v_pk_mul_f32 v[46:47], v[46:47], v[244:245] op_sel_hi:[1,0]
	v_cvt_pk_bf16_f32 v44, v44, v45
	v_cvt_pk_bf16_f32 v45, v46, v47
	global_store_dwordx2 v246, v[44:45], s[10:11] offset:224
	s_barrier
	s_and_saveexec_b64 s[0:1], s[24:25]
	s_cbranch_execz na1_nq
	v_mov_b32_e32 v196, 1
	v_mov_b32_e32 v197, 0
	s_add_u32 s6, s50, 0x4200
	s_addc_u32 s7, s51, 0
	global_atomic_add v196, v197, v196, s[6:7] sc0
	v_mov_b32_e32 v197, 0x22040
	s_waitcnt vmcnt(0)
	ds_write_b32 v197, v196
na1_nq:
	s_or_b64 exec, exec, s[0:1]
	v_mov_b32_e32 v197, 0x22040
	s_waitcnt vmcnt(0) lgkmcnt(0)
	s_barrier
	ds_read_b32 v196, v197
	s_waitcnt lgkmcnt(0)
	v_readfirstlane_b32 s29, v196
	s_cmp_lt_u32 s29, 0x360
	s_cbranch_scc1 na1_item
	v_mov_b32_e32 v133, 0
